# softmax scale folded into Q producer, running max enters QK through the MFMA C operand (no per-score fma on common path), K/V LDS tile writes moved to step start
# speedup vs baseline: 1.0180x; 1.0037x over previous
; #define LAS __attribute__((address_space(3)))
; DEV unsigned xb_add(unsigned* p, unsigned v) { return __hip_atomic_fetch_add(p, v, __ATOMIC_RELAXED, __HIP_MEMORY_SCOPE_AGENT); }
; DEV unsigned xb_xcc_id() { return (unsigned)__builtin_amdgcn_s_getreg((3 << 11) | 20) & 0xFu; }
; DEV void phase_retout(const Params& p, int l) {
;     ...
;   const int natt = (l == DEPTH - 1) ? 512 : 544;
;   int x, j;
;   const bool ok = xcc_rank(x, j);
;   const int nmain = (512 + (int)gridDim.x - 1) / (int)gridDim.x;
; #pragma unroll 1
;   for (int sl = 0; sl <= nmain; ++sl) {
;     int b, h, qb; bool valid;
;     if (sl < nmain) {
;       if (ok) { const int k = sl * 32 + j, head = x * 4 + (k >> 4); b = head >> 3; h = head & 7; qb = k & 15; valid = true; }
;       else { const int it = (int)blockIdx.x + sl * (int)gridDim.x; valid = it < 512; b = it >> 7; h = (it >> 4) & 7; qb = it & 15; }
;     } else {
;       const int it = (int)blockIdx.x - ((gridDim.x >= 64) ? 32 : 0);
;       valid = natt > 512 && it >= 0 && it < 32; b = it >> 3; h = it & 7; qb = 16;
; __global__ void __launch_bounds__(512) mega(Params p0, int ph_lo, int ph_hi) {
;   cg::grid_group grid = cg::this_grid();
;   unsigned* bar = (unsigned*)(p0.ws + OFF_BAR);
;   if (threadIdx.x == 0) { volatile LAS unsigned* st = (volatile LAS unsigned*)(LAS char*)(g_shm + SHM_MAIN); st[0] = 0u; st[1] = 0u;
;     const unsigned xcc = xb_xcc_id();
;     st[2] = xcc; st[3] = xb_add(&bar[XB_XCNT(xcc)], 1u); }
;   __syncthreads();
; #pragma unroll 1
;   for (int ph = ph_lo; ph < ph_hi; ++ph) {
;     Params p = p0;
;     { size_t zoff = 0; asm volatile("" : "+s"(zoff)); p.ws = p0.ws + zoff; }
.LBB0_5:
	s_lshl_b32 s14, s74, 3
	s_lshl_b32 s3, s10, 3
	s_cmpk_lt_i32 s10, 0x581
	v_writelane_b32 v253, s3, 10
	s_cselect_b64 s[4:5], -1, 0
	v_writelane_b32 v253, s4, 11
	s_cmpk_lt_i32 s10, 0x220
	s_mov_b32 s91, 0
	v_writelane_b32 v253, s5, 12
	s_cselect_b64 s[4:5], -1, 0
	s_add_i32 s3, s74, 0x1ff
	v_writelane_b32 v253, s4, 13
	s_cmp_gt_u32 s74, 63
	s_mov_b32 s11, s91
	v_writelane_b32 v253, s5, 14
	s_cselect_b32 s4, 0xffffffe0, 0
	s_add_i32 s4, s4, s10
	s_cmp_lt_u32 s4, 32
	s_cselect_b64 s[6:7], -1, 0
	v_writelane_b32 v253, s6, 15
	s_ashr_i32 s81, s4, 3
	s_lshl_b64 s[4:5], s[10:11], 17
	v_writelane_b32 v253, s7, 16
	v_writelane_b32 v253, s4, 17
	s_cmpk_eq_i32 s74, 0x100
	s_mul_i32 s2, s75, s74
	v_writelane_b32 v253, s5, 18
	s_cselect_b64 s[4:5], -1, 0
	v_writelane_b32 v253, s4, 19
	s_cmpk_lt_i32 s10, 0x100
	s_mov_b32 s75, s91
	v_writelane_b32 v253, s5, 20
	s_cselect_b64 s[4:5], -1, 0
	v_writelane_b32 v253, s4, 21
	s_load_dwordx2 s[12:13], s[0:1], 0x88
	v_mov_b32_e32 v163, 0
	v_writelane_b32 v253, s5, 22
	s_lshl_b64 s[4:5], s[10:11], 9
	v_writelane_b32 v253, s4, 23
	v_mov_b32_e32 v175, 0x358637bd
	s_mov_b32 s70, -1
	v_writelane_b32 v253, s5, 24
	s_lshl_b64 s[4:5], s[74:75], 9
	v_writelane_b32 v253, s4, 25
	s_mov_b32 s71, 0x20000
	v_mov_b32_e32 v176, 0xb9500d01
	v_writelane_b32 v253, s5, 26
	s_and_b32 s4, s74, 7
	s_cmp_eq_u32 s4, 0
	s_cselect_b64 s[4:5], -1, 0
	v_writelane_b32 v253, s4, 27
	v_mov_b32_e32 v178, 0x37d00d01
	v_mov_b32_e32 v197, 0x42800000
	v_writelane_b32 v253, s5, 28
	s_load_dwordx2 s[4:5], s[0:1], 0x90
	v_not_b32_e32 v196, 63
	v_mov_b32_e32 v177, 0x7f800000
	s_movk_i32 s33, 0x4400
	s_mov_b32 s66, 0x800000
	s_waitcnt lgkmcnt(0)
	s_cmpk_lt_i32 s5, 0x1001
	s_cselect_b64 s[4:5], -1, 0
	v_writelane_b32 v253, s4, 29
	s_movk_i32 s87, 0x1000
	s_mov_b32 s94, 0x1a80c000
	v_writelane_b32 v253, s5, 30
	s_add_u32 s4, s12, 0x3a646300
	s_addc_u32 s5, s13, 0
	s_add_u32 s22, s12, 0x3a646500
	s_addc_u32 s23, s13, 0
	s_add_u32 s24, s12, 0x3a646600
	s_addc_u32 s25, s13, 0
	s_add_u32 s60, s12, 0x3a646700
	s_addc_u32 s61, s13, 0
	s_add_u32 s34, s12, 0x3a646800
	s_addc_u32 s35, s13, 0
	s_add_u32 s26, s12, 0x3a646900
	s_addc_u32 s27, s13, 0
	s_add_u32 s28, s12, 0x3a646a00
	s_addc_u32 s29, s13, 0
	s_add_u32 s62, s12, 0x3a646b00
	s_addc_u32 s63, s13, 0
	s_add_u32 s64, s12, 0x3a646c00
	s_addc_u32 s65, s13, 0
	s_add_u32 s96, s12, 0x3a646d00
	s_addc_u32 s97, s13, 0
	s_add_u32 s68, s12, 0x3a646e00
	s_addc_u32 s69, s13, 0
	s_add_u32 s78, s12, 0x3a646f00
	s_addc_u32 s79, s13, 0
	s_add_u32 s30, s12, 0x3a647000
	s_addc_u32 s31, s13, 0
	s_add_u32 s52, s12, 0x3a647100
	s_addc_u32 s53, s13, 0
	s_add_u32 s56, s12, 0x3a647200
	s_addc_u32 s57, s13, 0
	s_add_u32 s58, s12, 0x3a647300
	v_writelane_b32 v253, s4, 31
	s_addc_u32 s59, s13, 0
	v_writelane_b32 v255, s62, 0
	v_writelane_b32 v253, s5, 32
	s_add_u32 s4, s12, 0x3a647400
	s_addc_u32 s5, s13, 0
	v_writelane_b32 v253, s4, 33
	v_writelane_b32 v255, s63, 1
	v_writelane_b32 v255, s64, 2
	v_writelane_b32 v253, s5, 34
	s_add_u32 s4, s12, 0x3a649500
	s_addc_u32 s5, s13, 0
	v_writelane_b32 v253, s4, 35
	v_writelane_b32 v255, s65, 3
	v_writelane_b32 v255, s96, 4
	v_writelane_b32 v253, s5, 36
	s_add_u32 s4, s12, 0x3a649600
	s_addc_u32 s5, s13, 0
	v_writelane_b32 v253, s4, 37
	v_writelane_b32 v255, s97, 5
	v_writelane_b32 v255, s68, 6
	v_writelane_b32 v253, s5, 38
	s_abs_i32 s4, s74
	v_cvt_f32_u32_e32 v1, s4
	s_sub_i32 s5, 0, s4
	v_writelane_b32 v255, s69, 7
	v_writelane_b32 v255, s78, 8
	v_rcp_iflag_f32_e32 v1, v1
	s_mov_b32 s95, 0x1a80e000
	v_writelane_b32 v255, s79, 9
	v_writelane_b32 v255, s30, 10
	v_mul_f32_e32 v1, 0x4f7ffffe, v1
	v_cvt_u32_f32_e32 v1, v1
	v_writelane_b32 v255, s31, 11
	v_writelane_b32 v255, s52, 12
	s_movk_i32 s93, 0x7fff
	v_readfirstlane_b32 s6, v1
	s_mul_i32 s5, s5, s6
	s_mul_hi_u32 s5, s6, s5
	s_add_i32 s6, s6, s5
	s_abs_i32 s5, s3
	s_mul_hi_u32 s6, s5, s6
	s_mul_i32 s7, s6, s4
	s_sub_i32 s5, s5, s7
	s_xor_b32 s3, s3, s74
	s_ashr_i32 s3, s3, 31
	s_add_i32 s7, s6, 1
	s_sub_i32 s8, s5, s4
	s_cmp_ge_u32 s5, s4
	s_cselect_b32 s6, s7, s6
	s_cselect_b32 s5, s8, s5
	s_add_i32 s7, s6, 1
	s_cmp_ge_u32 s5, s4
	s_load_dword s4, s[0:1], 0xa0
	v_lshrrev_b32_e32 v1, 20, v0
	v_lshrrev_b32_e32 v0, 10, v0
	v_or_b32_e32 v0, v0, v1
	v_writelane_b32 v255, s53, 13
	s_waitcnt lgkmcnt(0)
; #define LAS __attribute__((address_space(3)))
; DEV unsigned xb_add(unsigned* p, unsigned v) { return __hip_atomic_fetch_add(p, v, __ATOMIC_RELAXED, __HIP_MEMORY_SCOPE_AGENT); }
; DEV unsigned xb_xcc_id() { return (unsigned)__builtin_amdgcn_s_getreg((3 << 11) | 20) & 0xFu; }
; __global__ void __launch_bounds__(512) mega(Params p0, int ph_lo, int ph_hi) {
;   cg::grid_group grid = cg::this_grid();
;   unsigned* bar = (unsigned*)(p0.ws + OFF_BAR);
;   if (threadIdx.x == 0) { volatile LAS unsigned* st = (volatile LAS unsigned*)(LAS char*)(g_shm + SHM_MAIN); st[0] = 0u; st[1] = 0u;
;     const unsigned xcc = xb_xcc_id();
;     st[2] = xcc; st[3] = xb_add(&bar[XB_XCNT(xcc)], 1u); }
;   __syncthreads();
; #pragma unroll 1
;   for (int ph = ph_lo; ph < ph_hi; ++ph) {
;     Params p = p0;
;     { size_t zoff = 0; asm volatile("" : "+s"(zoff)); p.ws = p0.ws + zoff; }
	s_mul_i32 s77, s2, s4
	s_movk_i32 s2, 0x3ff
	v_and_or_b32 v0, v0, s2, v252
	s_cselect_b32 s2, s7, s6
	s_xor_b32 s2, s2, s3
	s_sub_i32 s92, s2, s3
	s_cmp_gt_i32 s92, -1
	s_cselect_b64 s[2:3], -1, 0
	v_writelane_b32 v253, s2, 39
	v_writelane_b32 v255, s56, 14
	s_mov_b32 s86, 1.0
	v_writelane_b32 v253, s3, 40
	s_add_u32 s2, s12, 0xdc00400
	s_addc_u32 s3, s13, 0
	v_writelane_b32 v253, s2, 41
	s_ashr_i32 s15, s14, 31
	v_writelane_b32 v255, s57, 15
	v_writelane_b32 v253, s3, 42
	s_lshl_b64 s[2:3], s[14:15], 11
	v_writelane_b32 v253, s2, 43
	v_writelane_b32 v255, s58, 16
	s_mov_b64 s[54:55], 0x100
	v_writelane_b32 v253, s3, 44
	s_add_u32 s2, s12, 0x9800800
	s_addc_u32 s3, s13, 0
	v_writelane_b32 v253, s2, 45
	v_writelane_b32 v255, s59, 17
	s_nop 0
	v_writelane_b32 v253, s3, 46
	s_mov_b32 s2, s14
	v_writelane_b32 v253, s2, 47
	s_nop 1
	v_writelane_b32 v253, s3, 48
	s_lshl_b64 s[2:3], s[14:15], 12
	v_writelane_b32 v253, s2, 49
	s_nop 1
	v_writelane_b32 v253, s3, 50
	s_add_u32 s2, s12, 0x3a63c000
	v_writelane_b32 v253, s2, 51
	s_addc_u32 s2, s13, 0
	v_writelane_b32 v253, s2, 52
	s_add_u32 s2, s12, 0x3a644000
	v_writelane_b32 v253, s2, 53
	s_addc_u32 s2, s13, 0
	v_writelane_b32 v253, s2, 54
	s_add_u32 s2, s12, 0x7800000
	v_writelane_b32 v253, s2, 55
	s_addc_u32 s2, s13, 0
	v_writelane_b32 v253, s2, 56
	s_add_i32 s2, s10, 0xfffffc40
	v_writelane_b32 v253, s2, 57
	s_mov_b32 s2, s10
	v_writelane_b32 v253, s2, 58
	s_nop 1
	v_writelane_b32 v253, s3, 59
	s_lshl_b32 s2, s10, 6
	v_writelane_b32 v253, s2, 60
	s_lshl_b32 s2, s74, 6
	v_writelane_b32 v253, s2, 61
	s_lshl_b64 s[2:3], s[74:75], 12
	v_writelane_b32 v253, s2, 62
	s_nop 1
	v_writelane_b32 v253, s3, 63
	s_lshl_b64 s[2:3], s[74:75], 13
	v_writelane_b32 v254, s2, 0
	v_writelane_b32 v255, s74, 18
	s_nop 0
	v_writelane_b32 v254, s3, 1
	s_add_u32 s2, s12, 0x3b249700
	v_writelane_b32 v254, s2, 2
	s_addc_u32 s2, s13, 0
	v_writelane_b32 v254, s2, 3
	s_add_i32 s2, 0, 0x10800
	v_writelane_b32 v254, s2, 4
	s_add_i32 s2, 0, 0x19000
	v_writelane_b32 v254, s2, 5
	s_add_i32 s2, 0, 0x19800
	v_writelane_b32 v254, s2, 6
	s_add_i32 s2, 0, 0x1a000
	v_writelane_b32 v254, s2, 7
	s_add_i32 s2, 0, 0x1a800
	v_writelane_b32 v254, s2, 8
	s_add_i32 s2, 0, 0x21000
	v_writelane_b32 v254, s2, 9
	s_add_i32 s2, 0, 0x21004
	v_writelane_b32 v254, s2, 10
	s_add_i32 s2, 0, 0x21008
	v_writelane_b32 v254, s2, 11
	s_add_i32 s2, 0, 0x2100c
	v_writelane_b32 v254, s2, 12
	s_add_i32 s2, 0, 0x14000
	v_writelane_b32 v254, s2, 13
	s_add_i32 s2, 0, 0x18000
	v_writelane_b32 v254, s2, 14
	s_add_i32 s2, 0, 0x1c000
	v_writelane_b32 v254, s2, 15
	s_load_dwordx2 s[2:3], s[0:1], 0x80
	s_load_dwordx16 s[4:19], s[0:1], 0x0
	v_writelane_b32 v255, s75, 19
	v_writelane_b32 v255, s77, 20
	v_writelane_b32 v255, s92, 21
	s_waitcnt lgkmcnt(0)
	v_writelane_b32 v254, s2, 16
	v_writelane_b32 v255, s81, 22
	s_nop 0
	v_writelane_b32 v254, s3, 17
	v_cmp_eq_u32_e64 s[2:3], 0, v0
	s_nop 1
	v_writelane_b32 v254, s2, 18
	s_nop 1
	v_writelane_b32 v254, s3, 19
	v_writelane_b32 v254, s4, 20
	s_nop 1
	v_writelane_b32 v254, s5, 21
	v_writelane_b32 v254, s6, 22
	v_writelane_b32 v254, s7, 23
	v_writelane_b32 v254, s8, 24
	v_writelane_b32 v254, s9, 25
	v_writelane_b32 v254, s10, 26
	v_writelane_b32 v254, s11, 27
	v_writelane_b32 v254, s12, 28
	v_writelane_b32 v254, s13, 29
	v_writelane_b32 v254, s14, 30
	v_writelane_b32 v254, s15, 31
	v_writelane_b32 v254, s16, 32
	v_writelane_b32 v254, s17, 33
	v_writelane_b32 v254, s18, 34
	v_writelane_b32 v254, s19, 35
	s_load_dwordx16 s[4:19], s[0:1], 0x40
	s_waitcnt lgkmcnt(0)
	v_writelane_b32 v254, s4, 36
	s_nop 1
	v_writelane_b32 v254, s5, 37
	v_writelane_b32 v254, s6, 38
	v_writelane_b32 v254, s7, 39
	v_writelane_b32 v254, s8, 40
	v_writelane_b32 v254, s9, 41
	v_writelane_b32 v254, s10, 42
	v_writelane_b32 v254, s11, 43
	v_writelane_b32 v254, s12, 44
	v_writelane_b32 v254, s13, 45
	v_writelane_b32 v254, s14, 46
	v_writelane_b32 v254, s15, 47
	v_writelane_b32 v254, s16, 48
	v_writelane_b32 v254, s17, 49
	v_writelane_b32 v254, s18, 50
	v_writelane_b32 v254, s19, 51
	v_writelane_b32 v254, s22, 52
	s_nop 1
	v_writelane_b32 v254, s23, 53
	v_writelane_b32 v254, s24, 54
	s_nop 1
	v_writelane_b32 v254, s25, 55
	v_writelane_b32 v254, s60, 56
	s_nop 1
	v_writelane_b32 v254, s61, 57
	v_writelane_b32 v254, s34, 58
	s_nop 1
	v_writelane_b32 v254, s35, 59
	v_writelane_b32 v254, s26, 60
	s_nop 1
	v_writelane_b32 v254, s27, 61
	v_writelane_b32 v254, s28, 62
	s_nop 1
	v_writelane_b32 v254, s29, 63
	s_branch .LBB0_10

; #define SWAIT() asm volatile("s_waitcnt vmcnt(3)" ::: "memory")
; DEV void attn_pass(const u16* __restrict__ Qb, const u16* __restrict__ Kh, const u16* __restrict__ Vh, int seq, f32x16* o, float* rli) {
;   char* lds = g_shm;
;   const int tid = ltid(), wid = tid >> 6, lane = tid & 63, r32 = lane & 31, hi = lane >> 5;
;   char* V_lds = lds; char* K_lds = lds + 3 * AT_SHM_V;
;   float* wsx = (float*)(lds + 3 * AT_SHM_V + 3 * AT_SHM_K) + wid * 64; float* li_l = wsx; float* al_l = wsx + 32;
;   float m_reg = -1e30f, l_reg = 0; bf16x8 qr[4];
; #pragma unroll
;   for (int d = 0; d < 4; ++d) o[d] = f32x16{};
;   const u16* Qw = Qb + (size_t)(wid * 32 + r32) * 64 + hi * 8;
; #pragma unroll
;   for (int d0 = 0; d0 < 4; ++d0) qr[d0] = *reinterpret_cast<const bf16x8*>(Qw + d0 * 16);
;   const int sr = tid >> 4, sc = (tid & 15) * 8, vst0 = v_st(sr, sc), vst1 = v_st(32 + sr, sc);
;   const int kr = tid >> 3, kc = (tid & 7) * 8, kst = KSWZ64(kr, kc * 2);
;   const int vb0 = (int)(uintptr_t)(__attribute__((address_space(3))) char*)V_lds + v_rd_base(lane);
;   struct { bf16x8 vs0, vs1, ks0; } sr_[2];
;     ...
;   f32x16 pA0, pA1, pB0, pB1; float mnA, mnB, alA, alB; bf16x8 pa0, pa1, pa2, pa3; const int NT = seq / 64;
;   constexpr int SE = 0, SO = 1;
;   SLOAD(SE, 0); SLOAD(SO, 64);
;   asm volatile("s_waitcnt vmcnt(3)" ::: "memory"); SWRITE(0, SE); __syncthreads();
;   if (2 < NT) SLOAD(SE, 2 * 64);
;   qkt(pA0, pA1, K_lds, qr, r32, hi); partialSM(pA0, pA1, m_reg, mnA, alA);
;   SWAIT(); SWRITE(1, SO); __syncthreads();
; DEV void attn_item(const Params& p, int l, int b, int h, int qb, int dry) {
;   const int tid = ltid(), wid = tid >> 6, lane = tid & 63, r32 = lane & 31, hi = lane >> 5;
;   const u16* AQ = (const u16*)(p.ws + OFF_AQ); const u16* AK = (const u16*)(p.ws + OFF_AK); const u16* AV = (const u16*)(p.ws + OFF_AV);
;   u16* AG = (u16*)(p.ws + OFF_AG);
;   float* scr = (float*)(p.ws + OFF_H) + (size_t)blockIdx.x * 32768;
;   const float* lamv = (const float*)(p.ws + OFF_LAM);
;   const float lam = lamv[l * 2], lam_init = lamv[l * 2 + 1];
;   const bool isctx = (qb == 16);
;   const int uq = isctx ? 0 : 256 + qb * 256, seq = isctx ? 256 : UU;
;   const size_t Rbase = isctx ? (size_t)ROWS_LAT + b * 256 : (size_t)b * 4096 + qb * 256;
;   const u16* Vh = AV + (size_t)(b * 8 + h) * UU * 128;
;   f32x16 o[4]; float rli[16];
;   {
;     const int s = b * 16 + h * 2;
.LBB0_69:
	s_and_b32 s43, s10, 7
	s_addk_i32 s11, 0x100
	s_and_b64 s[6:7], s[6:7], exec
	s_cselect_b32 s44, 4, 0x44
	s_cselect_b32 s46, 0, s11
	s_lshl_b32 s1, s0, 3
	s_or_b32 s49, s1, s43
	s_mul_i32 s52, s49, 0x110000
	s_mul_hi_i32 s53, s49, 0x110000
	s_add_u32 s64, s40, s52
	s_addc_u32 s65, s41, s53
	s_lshl_b32 s0, s0, 4
	s_lshl_b32 s1, s43, 1
	s_or_b32 s47, s0, s1
	s_mul_i32 s0, s47, 0x1100
	s_mul_hi_i32 s1, s47, 0x1100
	s_add_u32 s0, s0, s46
	v_mov_b32_e32 v70, v252
	s_addc_u32 s1, s1, 0
	s_lshl_b64 s[0:1], s[0:1], 7
	v_ashrrev_i32_e32 v48, 4, v70
	v_lshlrev_b32_e32 v20, 3, v70
	v_ashrrev_i32_e32 v49, 31, v48
	s_add_u32 s0, s36, s0
	v_and_b32_e32 v2, 0x78, v20
	v_add_u32_e32 v12, 32, v48
	v_lshlrev_b64 v[50:51], 8, v[48:49]
	s_addc_u32 s1, s37, s1
	s_mul_i32 s62, s47, 0x88000
	v_ashrrev_i32_e32 v14, 3, v70
	v_lshl_add_u64 v[0:1], s[64:65], 0, v[50:51]
	v_lshlrev_b32_e32 v2, 1, v2
	v_mov_b32_e32 v3, v163
	v_ashrrev_i32_e32 v13, 31, v12
	s_mul_hi_i32 s63, s47, 0x88000
	s_add_u32 s6, s38, s62
	v_lshl_add_u64 v[66:67], v[0:1], 0, v[2:3]
	v_lshlrev_b64 v[0:1], 8, v[12:13]
	v_ashrrev_i32_e32 v15, 31, v14
	s_addc_u32 s7, s39, s63
	v_lshlrev_b32_e32 v71, 4, v70
	v_lshl_add_u64 v[0:1], s[64:65], 0, v[0:1]
	v_lshlrev_b64 v[52:53], 7, v[14:15]
	v_and_b32_e32 v16, 0x70, v71
	v_lshl_add_u64 v[4:5], v[0:1], 0, v[2:3]
	v_lshl_add_u64 v[8:9], s[6:7], 0, v[52:53]
	v_mov_b32_e32 v17, v163
	global_load_dwordx4 v[0:3], v[66:67], off
	s_nop 0
	global_load_dwordx4 v[4:7], v[4:5], off
	v_lshl_add_u64 v[68:69], v[8:9], 0, v[16:17]
	global_load_dwordx4 v[8:11], v[68:69], off
	v_ashrrev_i32_e32 v13, 1, v70
	v_bfi_b32 v18, s68, v13, v70
	v_ashrrev_i32_e32 v19, 31, v18
	v_lshlrev_b64 v[18:19], 7, v[18:19]
	v_lshrrev_b32_e32 v13, 1, v70
	v_lshl_add_u64 v[18:19], s[0:1], 0, v[18:19]
	v_and_b32_e32 v162, 16, v13
	v_lshl_add_u64 v[18:19], v[18:19], 0, v[162:163]
	global_load_dwordx4 v[108:111], v[18:19], off
	global_load_dwordx4 v[104:107], v[18:19], off offset:32
	global_load_dwordx4 v[100:103], v[18:19], off offset:64
	global_load_dwordx4 v[96:99], v[18:19], off offset:96
	v_and_b32_e32 v13, 0xfffff0, v48
	v_lshlrev_b32_e32 v15, 1, v48
	v_and_or_b32 v13, v15, 8, v13
	v_lshrrev_b32_e32 v13, 1, v13
	v_bfe_u32 v17, v20, 5, 2
	v_lshrrev_b32_e32 v15, 1, v48
	v_or_b32_e32 v13, v13, v17
	v_and_b32_e32 v73, 3, v48
	v_lshlrev_b32_e32 v72, 9, v13
	v_and_or_b32 v13, v15, 4, v73
	v_and_b32_e32 v15, 0xfffff0, v12
	v_lshlrev_b32_e32 v12, 1, v12
	v_and_or_b32 v12, v12, 8, v15
	v_lshrrev_b32_e32 v12, 1, v12
	v_or_b32_e32 v12, v12, v17
	v_lshlrev_b32_e32 v13, 6, v13
	v_and_b32_e32 v74, 48, v71
	v_lshlrev_b32_e32 v75, 9, v12
	v_or3_b32 v18, v72, v13, v74
	v_or3_b32 v17, v75, v13, v74
	v_lshlrev_b32_e32 v12, 7, v14
	v_and_b32_e32 v13, 0x70, v70
	v_bitop3_b32 v76, v16, v12, v13 bitop3:0xde
	v_add_co_u32_e32 v12, vcc, s75, v66
	s_movk_i32 s0, 0x6000
	s_nop 0
	v_addc_co_u32_e32 v13, vcc, 0, v67, vcc
	global_load_dwordx4 v[54:57], v[12:13], off
	v_add_co_u32_e32 v12, vcc, s0, v66
	v_and_b32_e32 v49, 31, v70
	s_nop 0
	v_addc_co_u32_e32 v13, vcc, 0, v67, vcc
	v_add_co_u32_e32 v14, vcc, s45, v68
	v_lshlrev_b32_e32 v80, 7, v49
	s_nop 0
	v_addc_co_u32_e32 v15, vcc, 0, v69, vcc
	global_load_dwordx4 v[58:61], v[12:13], off
	global_load_dwordx4 v[62:65], v[14:15], off
	v_and_b32_e32 v81, 0x70, v20
	v_add_u32_e32 v77, 0, v18
	v_add_u32_e32 v78, 0, v17
	v_bitop3_b32 v171, v162, v80, v81 bitop3:0xde
	s_waitcnt vmcnt(3)
	v_add_u32_e32 v79, 0, v76
	v_or_b32_e32 v83, 32, v162
	s_add_i32 s48, 0, 0x12000
	v_bitop3_b32 v175, v83, v80, v81 bitop3:0xde
	v_and_b32_e32 v82, 63, v70
	s_mov_b32 s0, 0xa000
	v_and_b32_e32 v177, 0xc0, v71
	v_or_b32_e32 v71, 64, v162
	v_bitop3_b32 v174, v71, v80, v81 bitop3:0xde
	v_or_b32_e32 v84, 0x60, v162
	v_bitop3_b32 v173, v84, v80, v81 bitop3:0xde
	s_mov_b32 s8, 0
	s_mov_b32 s9, s8
	s_mov_b32 s10, s8
	s_mov_b32 s11, s8
	s_mov_b32 s12, s8
	s_mov_b32 s13, s8
	s_mov_b32 s14, s8
	s_mov_b32 s15, s8
	s_mov_b32 s16, s8
	s_mov_b32 s17, s8
	s_waitcnt vmcnt(9)
	ds_write_b128 v77, v[0:3]
	s_waitcnt vmcnt(8)
	ds_write_b128 v78, v[4:7]
	v_add_u32_e32 v4, 0, v171
	s_waitcnt vmcnt(7)
	ds_write_b128 v79, v[8:11] offset:49152
	s_waitcnt lgkmcnt(0)
	s_barrier
	ds_read_b128 v[0:3], v4 offset:49152
	ds_read_b128 v[4:7], v4 offset:53248
	v_and_b32_e32 v8, 0x3fffffc0, v70
	v_lshl_add_u32 v168, v8, 2, s48
	v_add_u32_e32 v8, 0, v175
	s_waitcnt vmcnt(6) lgkmcnt(1)
	v_mfma_f32_32x32x16_bf16 v[16:31], v[0:3], v[108:111], 0
	ds_read_b128 v[0:3], v8 offset:49152
	s_mov_b32 s18, s8
	s_mov_b32 s19, s8
	s_mov_b32 s20, s8
	s_mov_b32 s21, s8
	s_mov_b32 s22, s8
	s_mov_b32 s23, s8
	s_waitcnt lgkmcnt(1)
	v_mfma_f32_32x32x16_bf16 v[32:47], v[4:7], v[108:111], 0
	v_lshlrev_b32_e32 v4, 3, v82
	v_lshlrev_b32_e32 v5, 1, v70
	v_and_b32_e32 v176, 24, v4
	v_and_b32_e32 v178, 32, v5
	v_and_b32_e32 v179, 0x100, v4
	ds_read_b128 v[4:7], v8 offset:53248
	v_add_co_u32_e32 v8, vcc, s75, v68
	s_waitcnt vmcnt(5) lgkmcnt(0)
	v_mfma_f32_32x32x16_bf16 v[32:47], v[4:7], v[104:107], v[32:47]
	v_addc_co_u32_e32 v9, vcc, 0, v69, vcc
	v_add_co_u32_e32 v10, vcc, s0, v66
	s_mov_b32 s0, 0x8000
	s_nop 0
	v_addc_co_u32_e32 v11, vcc, 0, v67, vcc
	v_add_co_u32_e32 v4, vcc, s0, v66
	v_add_u32_e32 v6, 0, v174
	s_nop 0
	v_addc_co_u32_e32 v5, vcc, 0, v67, vcc
	v_mfma_f32_32x32x16_bf16 v[16:31], v[0:3], v[104:107], v[16:31]
	ds_read_b128 v[0:3], v6 offset:49152
	global_load_dwordx4 v[120:123], v[8:9], off
	global_load_dwordx4 v[112:115], v[10:11], off
	global_load_dwordx4 v[116:119], v[4:5], off
	v_add_u32_e32 v8, 0, v173
	ds_read_b128 v[4:7], v6 offset:53248
	ds_read_b128 v[66:69], v8 offset:53248
	s_mov_b32 s0, 0x10000
	s_waitcnt vmcnt(7) lgkmcnt(2)
; #define SWRITE(b, i) do { *(bf16x8*)(V_lds + (b) * AT_SHM_V + vst0) = sr_[i].vs0; *(bf16x8*)(V_lds + (b) * AT_SHM_V + vst1) = sr_[i].vs1; \
;     *(bf16x8*)(K_lds + (b) * AT_SHM_K + kst) = sr_[i].ks0; } while (0)
; #define SWAIT() asm volatile("s_waitcnt vmcnt(3)" ::: "memory")
; DEV void partialSM(f32x16& p0, f32x16& p1, float& m_reg, float& mn, float& alpha) {
;   constexpr float C = AT_SCALE * 1.4426950408889634f;
;   float pmax = p0[0];
; #pragma unroll
;   for (int r = 1; r < 16; ++r) pmax = fmaxf(pmax, p0[r]);
; #pragma unroll
;   for (int r = 0; r < 16; ++r) pmax = fmaxf(pmax, p1[r]);
;   { auto rr = __builtin_amdgcn_permlane32_swap(__float_as_uint(pmax), __float_as_uint(pmax), false, false);
;     pmax = fmaxf(__uint_as_float(rr[0]), __uint_as_float(rr[1])); }
;   if (__builtin_expect(__all(pmax - m_reg <= AT_THR / AT_SCALE), 1)) { mn = m_reg; alpha = 1.f; }
;   else { mn = fmaxf(m_reg, pmax); alpha = __builtin_amdgcn_exp2f((m_reg - mn) * C); m_reg = mn; }
;   float mnC = -mn * C;
; #pragma unroll
;   for (int r = 0; r < 16; ++r) p0[r] = fmaf(p0[r], C, mnC);
; #pragma unroll
;   for (int r = 0; r < 16; ++r) p1[r] = fmaf(p1[r], C, mnC);
; #pragma unroll
;   for (int r = 0; r < 16; ++r) p0[r] = __builtin_amdgcn_exp2f(p0[r]);
; }
; DEV void attn_pass(const u16* __restrict__ Qb, const u16* __restrict__ Kh, const u16* __restrict__ Vh, int seq, f32x16* o, float* rli) {
;     ...
;   qkt(pA0, pA1, K_lds, qr, r32, hi); partialSM(pA0, pA1, m_reg, mnA, alA);
;   SWAIT(); SWRITE(1, SO); __syncthreads();
	v_mfma_f32_32x32x16_bf16 v[16:31], v[0:3], v[100:103], v[16:31]
	ds_read_b128 v[0:3], v8 offset:49152
	s_waitcnt vmcnt(3)
	s_waitcnt vmcnt(5)
	ds_write_b128 v77, v[54:57] offset:16384
	s_waitcnt vmcnt(4)
	ds_write_b128 v78, v[58:61] offset:16384
	s_waitcnt vmcnt(3)
	ds_write_b128 v79, v[62:65] offset:57344
	v_mov_b32_e32 v54, 0xf149f2ca
	v_bitop3_b32 v183, v162, s0, v81 bitop3:0xde
	v_bitop3_b32 v185, v83, s0, v81 bitop3:0xde
	v_bitop3_b32 v199, v71, s0, v81 bitop3:0xde
	s_waitcnt lgkmcnt(5)
	v_mfma_f32_32x32x16_bf16 v[32:47], v[4:7], v[100:103], v[32:47]
	v_bitop3_b32 v201, v84, s0, v81 bitop3:0xde
	v_lshl_add_u32 v169, v49, 2, v168
	s_mov_b32 s45, 4
	s_mov_b32 s50, 3
	s_mov_b32 s51, 1
	s_mov_b32 s66, 2
	v_cmp_gt_u32_e64 s[6:7], 32, v82
	s_waitcnt lgkmcnt(3)
	v_mfma_f32_32x32x16_bf16 v[16:31], v[0:3], v[96:99], v[16:31]
	v_mov_b64_e32 v[0:1], s[8:9]
	v_mov_b64_e32 v[2:3], s[10:11]
	v_mov_b64_e32 v[4:5], s[12:13]
	v_mov_b64_e32 v[6:7], s[14:15]
	v_mov_b64_e32 v[8:9], s[16:17]
	v_mov_b64_e32 v[10:11], s[18:19]
	v_mov_b64_e32 v[12:13], s[20:21]
	v_mfma_f32_32x32x16_bf16 v[32:47], v[66:69], v[96:99], v[32:47]
	s_nop 3
	v_max_f32_e32 v66, v17, v17
	v_max_f32_e32 v67, v16, v16
	v_max_f32_e32 v66, v67, v66
	v_max3_f32 v66, v66, v18, v19
	v_max3_f32 v66, v66, v20, v21
	v_max3_f32 v66, v66, v22, v23
	v_max3_f32 v66, v66, v24, v25
	v_max3_f32 v66, v66, v26, v27
	v_max3_f32 v66, v66, v28, v29
	v_max3_f32 v66, v66, v30, v31
	v_max3_f32 v66, v66, v32, v33
	v_max3_f32 v66, v66, v34, v35
	v_max3_f32 v66, v66, v36, v37
	v_max3_f32 v66, v66, v38, v39
	v_max3_f32 v66, v66, v40, v41
	v_max3_f32 v66, v66, v42, v43
	v_max3_f32 v66, v66, v44, v45
	v_max3_f32 v66, v66, v46, v47
	v_mov_b32_e32 v67, v66
	s_nop 1
	v_permlane32_swap_b32_e32 v66, v67
	v_max_f32_e32 v67, v67, v67
	v_max_f32_e32 v66, v66, v66
	v_max_f32_e32 v66, v66, v67
	v_mov_b64_e32 v[14:15], s[22:23]
	v_add_f32_e32 v67, 0x7149f2ca, v66
	s_mov_b32 s18, 0x4138aa3b
	v_cmp_ge_f32_e32 vcc, s18, v67
	s_cmp_eq_u64 vcc, exec
	v_max_f32_e32 v55, 0xf149f2ca, v66
	s_cselect_b64 vcc, -1, 0
	v_cndmask_b32_e32 v140, v55, v54, vcc
	v_mul_f32_e32 v54, 0xbf800000, v140
	v_mov_b32_e32 v236, v54
	v_mov_b32_e32 v237, v54
	v_mov_b32_e32 v238, v54
	v_mov_b32_e32 v239, v54
	v_mov_b32_e32 v240, v54
	v_mov_b32_e32 v241, v54
	v_mov_b32_e32 v242, v54
	v_mov_b32_e32 v243, v54
	v_mov_b32_e32 v244, v54
	v_mov_b32_e32 v245, v54
	v_mov_b32_e32 v246, v54
	v_mov_b32_e32 v247, v54
	v_mov_b32_e32 v248, v54
	v_mov_b32_e32 v249, v54
	v_mov_b32_e32 v250, v54
	v_mov_b32_e32 v251, v54
	v_fmamk_f32 v16, v16, 0x3f800000, v54
	v_exp_f32_e32 v150, v16
	v_fmamk_f32 v16, v17, 0x3f800000, v54
	v_exp_f32_e32 v160, v16
	v_fmamk_f32 v16, v18, 0x3f800000, v54
	v_exp_f32_e32 v151, v16
	v_fmamk_f32 v16, v19, 0x3f800000, v54
	v_exp_f32_e32 v161, v16
	v_fmamk_f32 v16, v20, 0x3f800000, v54
	v_exp_f32_e32 v158, v16
	v_fmamk_f32 v16, v21, 0x3f800000, v54
	v_exp_f32_e32 v214, v16
	v_fmamk_f32 v16, v22, 0x3f800000, v54
	v_exp_f32_e32 v159, v16
	v_fmamk_f32 v16, v23, 0x3f800000, v54
	v_exp_f32_e32 v215, v16
	v_fmamk_f32 v16, v24, 0x3f800000, v54
	v_exp_f32_e32 v142, v16
	v_fmamk_f32 v16, v25, 0x3f800000, v54
	v_exp_f32_e32 v146, v16
	v_fmamk_f32 v16, v26, 0x3f800000, v54
	v_exp_f32_e32 v143, v16
	v_fmamk_f32 v16, v27, 0x3f800000, v54
	v_exp_f32_e32 v147, v16
	v_fmamk_f32 v16, v28, 0x3f800000, v54
	v_exp_f32_e32 v144, v16
	v_fmamk_f32 v16, v29, 0x3f800000, v54
	v_exp_f32_e32 v148, v16
	v_fmamk_f32 v16, v30, 0x3f800000, v54
	v_exp_f32_e32 v145, v16
	v_add3_u32 v16, v179, 0, v177
	v_add3_u32 v184, v16, v178, v176
	v_lshlrev_b32_e32 v16, 5, v48
	v_and_b32_e32 v16, 0x100, v16
	v_lshlrev_b32_e32 v17, 6, v73
	v_or3_b32 v18, v75, v16, v17
	v_or3_b32 v19, v72, v16, v17
	v_mov_b32_e32 v16, 0x88000
	v_pk_fma_f32 v[132:133], v[38:39], s[86:87], v[54:55] op_sel_hi:[1,0,0]
	v_sub_f32_e32 v38, 0xf149f2ca, v55
	v_mad_i64_i32 v[16:17], s[0:1], s47, v16, v[52:53]
	v_and_b32_e32 v20, 7, v70
	v_mul_f32_e32 v38, 0x3f800000, v38
	v_lshl_or_b32 v16, v20, 4, v16
	v_exp_f32_e32 v38, v38
	v_lshl_add_u64 v[154:155], s[96:97], 0, v[16:17]
	v_mov_b32_e32 v16, 0x110000
	v_pk_fma_f32 v[124:125], v[46:47], s[86:87], v[54:55] op_sel_hi:[1,0,0]
	v_pk_fma_f32 v[126:127], v[44:45], s[86:87], v[54:55] op_sel_hi:[1,0,0]
	v_pk_fma_f32 v[128:129], v[42:43], s[86:87], v[54:55] op_sel_hi:[1,0,0]
	v_pk_fma_f32 v[130:131], v[40:41], s[86:87], v[54:55] op_sel_hi:[1,0,0]
	v_pk_fma_f32 v[134:135], v[36:37], s[86:87], v[54:55] op_sel_hi:[1,0,0]
	v_pk_fma_f32 v[136:137], v[34:35], s[86:87], v[54:55] op_sel_hi:[1,0,0]
	v_pk_fma_f32 v[138:139], v[32:33], s[86:87], v[54:55] op_sel_hi:[1,0,0]
	v_fmac_f32_e32 v54, 0x3f800000, v31
	v_mad_i64_i32 v[16:17], s[0:1], s49, v16, v[50:51]
	v_and_b32_e32 v20, 15, v70
	v_exp_f32_e32 v149, v54
	v_lshl_or_b32 v16, v20, 4, v16
	s_add_i32 s49, 0, 0x4000
	v_lshl_add_u64 v[156:157], s[96:97], 0, v[16:17]
	v_add3_u32 v16, v179, s49, v177
	v_cndmask_b32_e64 v182, v38, 1.0, vcc
	s_mov_b32 s9, 0xe000
	v_add_u32_e32 v203, 0x8000, v18
	v_add_u32_e32 v204, 0x8000, v19
	v_add_u32_e32 v206, 0xc000, v18
	v_add_u32_e32 v207, 0xc000, v19
	v_add3_u32 v208, v16, v178, v176
	v_mov_b64_e32 v[62:63], v[14:15]
	v_mov_b64_e32 v[46:47], v[14:15]
	v_mov_b64_e32 v[30:31], v[14:15]
	v_add_u32_e32 v180, 0x10000, v76
	v_add_u32_e32 v181, 0, v80
	v_bitop3_b32 v198, v162, s9, v81 bitop3:0xde
	v_bitop3_b32 v200, v83, s9, v81 bitop3:0xde
	v_add_u32_e32 v202, 0, v74
	v_add_u32_e32 v205, 0x12000, v76
	v_bitop3_b32 v209, v71, s9, v81 bitop3:0xde
	v_bitop3_b32 v210, v84, s9, v81 bitop3:0xde
	v_mov_b32_e32 v170, 0
	s_mov_b32 s9, s8
	v_mov_b64_e32 v[60:61], v[12:13]
	v_mov_b64_e32 v[58:59], v[10:11]
	v_mov_b64_e32 v[56:57], v[8:9]
	v_mov_b64_e32 v[54:55], v[6:7]
	v_mov_b64_e32 v[52:53], v[4:5]
	v_mov_b64_e32 v[50:51], v[2:3]
	v_mov_b64_e32 v[48:49], v[0:1]
	v_mov_b64_e32 v[44:45], v[12:13]
	v_mov_b64_e32 v[42:43], v[10:11]
	v_mov_b64_e32 v[40:41], v[8:9]
	v_mov_b64_e32 v[38:39], v[6:7]
	v_mov_b64_e32 v[36:37], v[4:5]
	v_mov_b64_e32 v[34:35], v[2:3]
	v_mov_b64_e32 v[32:33], v[0:1]
	v_mov_b64_e32 v[28:29], v[12:13]
	v_mov_b64_e32 v[26:27], v[10:11]
	v_mov_b64_e32 v[24:25], v[8:9]
	v_mov_b64_e32 v[22:23], v[6:7]
	v_mov_b64_e32 v[20:21], v[4:5]
	v_mov_b64_e32 v[18:19], v[2:3]
	v_mov_b64_e32 v[16:17], v[0:1]
	s_waitcnt lgkmcnt(0)
	s_barrier
; DEV void qkt(f32x16& p0, f32x16& p1, const char* Ks, const bf16x8* qr, int r32, int hi) {
;   p0 = f32x16{}; p1 = f32x16{};
; #pragma unroll
;   for (int d0 = 0; d0 < 4; ++d0) { int cb = (d0 * 16 + hi * 8) * 2;
;     bf16x8 b0 = *reinterpret_cast<const bf16x8*>(Ks + KSWZ64(r32, cb));
;     bf16x8 b1 = *reinterpret_cast<const bf16x8*>(Ks + KSWZ64(32 + r32, cb));
;     p0 = __builtin_amdgcn_mfma_f32_32x32x16_bf16(b0, qr[d0], p0, 0, 0, 0);
;     p1 = __builtin_amdgcn_mfma_f32_32x32x16_bf16(b1, qr[d0], p1, 0, 0, 0); }
; }
; DEV int v_st(int k, int c) { const int kk = (k & ~0xC) | ((k & 4) << 1) | ((k & 8) >> 1); return ((kk >> 3) * 4 + (c >> 5)) * 512 + ((kk & 7) * 32 + (c & 31)) * 2; }
; DEV int v_rd_base(int lane) { return ((lane & 3) << 3) | (((lane >> 2) & 3) << 6) | (((lane >> 4) & 1) << 5) | (((lane >> 5) & 1) << 8); }
; template <int OFF> DEV s16x4 tr_read(int vb) {
;   s16x4 r; asm volatile("ds_read_b64_tr_b16 %0, %1 offset:%2" : "=&v"(r) : "v"(vb), "i"(OFF) : "memory"); return r;
; }
; template <int D0> DEV void pv_one(f32x16& od, int vb, bf16x8 pa0, bf16x8 pa1, bf16x8 pa2, bf16x8 pa3) {
;   const s16x4 l0 = tr_read<v_rd_off(D0, 0, 0)>(vb), h0 = tr_read<v_rd_off(D0, 0, 1)>(vb), l1 = tr_read<v_rd_off(D0, 1, 0)>(vb), h1 = tr_read<v_rd_off(D0, 1, 1)>(vb);
;   const s16x4 l2 = tr_read<v_rd_off(D0, 2, 0)>(vb), h2 = tr_read<v_rd_off(D0, 2, 1)>(vb), l3 = tr_read<v_rd_off(D0, 3, 0)>(vb), h3 = tr_read<v_rd_off(D0, 3, 1)>(vb);
;   asm volatile("s_waitcnt lgkmcnt(0)" ::: "memory"); SBAR();
;     ...
;   od = __builtin_amdgcn_mfma_f32_32x32x16_bf16(pa0, PK(l0, h0), od, 0, 0, 0);
;   od = __builtin_amdgcn_mfma_f32_32x32x16_bf16(pa1, PK(l1, h1), od, 0, 0, 0);
;   od = __builtin_amdgcn_mfma_f32_32x32x16_bf16(pa2, PK(l2, h2), od, 0, 0, 0);
;   od = __builtin_amdgcn_mfma_f32_32x32x16_bf16(pa3, PK(l3, h3), od, 0, 0, 0);
;     ...
; }
; DEV void pv_d0(f32x16* o, int vb, bf16x8 pa0, bf16x8 pa1, bf16x8 pa2, bf16x8 pa3) {
;   pv_one<0>(o[0], vb, pa0, pa1, pa2, pa3); pv_one<1>(o[1], vb, pa0, pa1, pa2, pa3); pv_one<2>(o[2], vb, pa0, pa1, pa2, pa3); pv_one<3>(o[3], vb, pa0, pa1, pa2, pa3);
; DEV void attn_pass(const u16* __restrict__ Qb, const u16* __restrict__ Kh, const u16* __restrict__ Vh, int seq, f32x16* o, float* rli) {
;     ...
;   f32x16 pA0, pA1, pB0, pB1; float mnA, mnB, alA, alB; bf16x8 pa0, pa1, pa2, pa3; const int NT = seq / 64;
;   constexpr int SE = 0, SO = 1;
.LBB0_70:
	s_mul_hi_u32 s1, s9, 0xaaaaaaab
	s_lshr_b32 s1, s1, 1
	s_mul_i32 s1, s1, 0xc000
	v_subrev_u32_e32 v190, s1, v184
	s_mul_hi_u32 s1, s51, 0xaaaaaaab
	s_mul_hi_u32 s0, s66, 0xaaaaaaab
	s_lshr_b32 s12, s1, 1
	s_lshr_b32 s0, s0, 1
	s_mul_i32 s1, s12, 0x6000
	s_mul_i32 s15, s0, 0x6000
	v_subrev_u32_e32 v64, s1, v198
	s_mul_i32 s0, s0, 0xc000
	v_subrev_u32_e32 v216, s15, v180
	v_subrev_u32_e32 v164, s1, v200
	v_subrev_u32_e32 v217, s0, v203
	v_subrev_u32_e32 v218, s0, v204
	v_subrev_u32_e32 v191, s1, v209
	v_subrev_u32_e32 v192, s1, v210
	v_add_u32_e32 v141, s14, v181
	v_add_u32_e32 v68, v141, v64
	ds_read_b128 v[64:67], v68
	ds_read_b128 v[68:71], v68 offset:4096
	v_add_u32_e32 v186, v141, v164
	ds_read_b128 v[164:167], v186
	ds_read_b128 v[186:189], v186 offset:4096
	s_waitcnt vmcnt(0)
	v_add_u32_e32 v72, s8, v202
	v_add_u32_e32 v73, v72, v218
	ds_write_b128 v73, v[116:119]
	v_add_u32_e32 v73, v72, v217
	s_add_i32 s13, s14, 0
	ds_write_b128 v73, v[112:115]
	v_add_u32_e32 v73, s13, v216
	ds_write_b128 v73, v[120:123]
	v_exp_f32_e32 v134, v134
	s_waitcnt lgkmcnt(6)
	v_mfma_f32_32x32x16_bf16 v[80:95], v[64:67], v[108:111], v[236:251]
	v_exp_f32_e32 v135, v135
	v_exp_f32_e32 v132, v132
	v_exp_f32_e32 v133, v133
	v_exp_f32_e32 v130, v130
	v_exp_f32_e32 v131, v131
	v_exp_f32_e32 v128, v128
	v_exp_f32_e32 v129, v129
	s_waitcnt lgkmcnt(5)
	v_mfma_f32_32x32x16_bf16 v[64:79], v[68:71], v[108:111], v[236:251]
	v_exp_f32_e32 v126, v126
	v_exp_f32_e32 v127, v127
	v_exp_f32_e32 v124, v124
	v_exp_f32_e32 v125, v125
	s_waitcnt lgkmcnt(4)
	v_mfma_f32_32x32x16_bf16 v[80:95], v[164:167], v[104:107], v[80:95]
	s_waitcnt lgkmcnt(3)
	v_mfma_f32_32x32x16_bf16 v[64:79], v[186:189], v[104:107], v[64:79]
	v_add_u32_e32 v186, v141, v191
	ds_read_b128 v[164:167], v186
	ds_read_b128 v[186:189], v186 offset:4096
	s_waitcnt lgkmcnt(1)
	v_mfma_f32_32x32x16_bf16 v[80:95], v[164:167], v[100:103], v[80:95]
	s_waitcnt lgkmcnt(0)
	v_mfma_f32_32x32x16_bf16 v[64:79], v[186:189], v[100:103], v[64:79]
	v_add_u32_e32 v186, v141, v192
	ds_read_b128 v[164:167], v186
	ds_read_b128 v[186:189], v186 offset:4096
	s_waitcnt lgkmcnt(1)
	v_mfma_f32_32x32x16_bf16 v[80:95], v[164:167], v[96:99], v[80:95]
	v_exp_f32_e32 v166, v136
	v_add_f32_e32 v136, v160, v150
	v_add_f32_e32 v136, v151, v136
	v_add_f32_e32 v136, v161, v136
	v_add_f32_e32 v136, v158, v136
	v_add_f32_e32 v136, v214, v136
	v_add_f32_e32 v136, v159, v136
	v_add_f32_e32 v136, v215, v136
	v_add_f32_e32 v136, v142, v136
	v_add_f32_e32 v136, v146, v136
	v_add_f32_e32 v136, v143, v136
	v_add_f32_e32 v136, v147, v136
	v_exp_f32_e32 v164, v138
	v_add_f32_e32 v136, v144, v136
	v_exp_f32_e32 v165, v139
	v_add_f32_e32 v136, v148, v136
	v_add_f32_e32 v136, v145, v136
	v_exp_f32_e32 v167, v137
	v_add_f32_e32 v136, v149, v136
	v_add_f32_e32 v136, v164, v136
	v_add_f32_e32 v136, v165, v136
	v_add_f32_e32 v136, v166, v136
	v_add_f32_e32 v136, v167, v136
	v_add_f32_e32 v136, v134, v136
	v_add_f32_e32 v136, v135, v136
	v_add_f32_e32 v136, v132, v136
	v_add_f32_e32 v136, v133, v136
	v_add_f32_e32 v136, v130, v136
	v_add_f32_e32 v136, v131, v136
	s_waitcnt lgkmcnt(0)
	v_mfma_f32_32x32x16_bf16 v[64:79], v[186:189], v[96:99], v[64:79]
	v_add_f32_e32 v136, v128, v136
	v_add_f32_e32 v136, v129, v136
	v_add_f32_e32 v136, v126, v136
	v_add_f32_e32 v136, v127, v136
	v_add_f32_e32 v136, v124, v136
	v_add_f32_e32 v211, v125, v136
	v_mov_b32_e32 v212, v211
	v_cvt_pk_bf16_f32 v136, v150, v160
	v_cvt_pk_bf16_f32 v138, v158, v214
	s_nop 1
	v_permlane32_swap_b32_e32 v211, v212
	v_cvt_pk_bf16_f32 v137, v151, v161
	v_cvt_pk_bf16_f32 v139, v159, v215
	v_permlane32_swap_b32_e32 v136, v138
	v_cvt_pk_bf16_f32 v142, v142, v146
	v_cvt_pk_bf16_f32 v143, v143, v147
	v_cvt_pk_bf16_f32 v144, v144, v148
	v_cvt_pk_bf16_f32 v145, v145, v149
	v_cvt_pk_bf16_f32 v146, v164, v165
	v_cvt_pk_bf16_f32 v147, v166, v167
	v_cvt_pk_bf16_f32 v148, v134, v135
	v_cvt_pk_bf16_f32 v149, v132, v133
	v_cvt_pk_bf16_f32 v164, v130, v131
	v_cvt_pk_bf16_f32 v165, v128, v129
	v_cvt_pk_bf16_f32 v166, v126, v127
	v_cvt_pk_bf16_f32 v167, v124, v125
	v_permlane32_swap_b32_e32 v137, v139
	v_permlane32_swap_b32_e32 v142, v144
	v_permlane32_swap_b32_e32 v143, v145
	v_permlane32_swap_b32_e32 v146, v148
	v_permlane32_swap_b32_e32 v147, v149
	v_permlane32_swap_b32_e32 v164, v166
	v_permlane32_swap_b32_e32 v165, v167
	v_lshl_add_u64 v[158:159], v[156:157], 0, s[82:83]
	v_add_co_u32_e32 v124, vcc, s94, v158
	v_lshl_add_u64 v[160:161], v[154:155], 0, s[82:83]
	s_nop 0
	v_addc_co_u32_e32 v125, vcc, 0, v159, vcc
	v_add_co_u32_e32 v128, vcc, s95, v158
	s_mov_b32 s0, 0x18606000
	s_nop 0
	v_addc_co_u32_e32 v129, vcc, 0, v159, vcc
	v_add_co_u32_e32 v132, vcc, s0, v160
	global_load_dwordx4 v[124:127], v[124:125], off
	s_nop 0
	global_load_dwordx4 v[128:131], v[128:129], off
	v_addc_co_u32_e32 v133, vcc, 0, v161, vcc
	global_load_dwordx4 v[132:135], v[132:133], off
	v_add_u32_e32 v150, s8, v190
	ds_read_b64_tr_b16 v[186:187], v150 offset:0
	ds_read_b64_tr_b16 v[188:189], v150 offset:0x800
	ds_read_b64_tr_b16 v[190:191], v150 offset:0x1000
	ds_read_b64_tr_b16 v[192:193], v150 offset:0x1800
	ds_read_b64_tr_b16 v[220:221], v150 offset:0x2000
	ds_read_b64_tr_b16 v[222:223], v150 offset:0x2800
	ds_read_b64_tr_b16 v[224:225], v150 offset:0x3000
	ds_read_b64_tr_b16 v[226:227], v150 offset:0x3800
	s_waitcnt lgkmcnt(0)
; #define SBAR() __builtin_amdgcn_sched_barrier(0)
; #define SLOAD(i, k0) do { sr_[i].vs0 = *reinterpret_cast<const bf16x8*>(&Vh[(size_t)((k0) + sr) * 128 + sc]); sr_[i].vs1 = *reinterpret_cast<const bf16x8*>(&Vh[(size_t)((k0) + 32 + sr) * 128 + sc]); \
;     sr_[i].ks0 = *reinterpret_cast<const bf16x8*>(&Kh[(size_t)((k0) + kr) * 64 + kc]); } while (0)
; #define SWRITE(b, i) do { *(bf16x8*)(V_lds + (b) * AT_SHM_V + vst0) = sr_[i].vs0; *(bf16x8*)(V_lds + (b) * AT_SHM_V + vst1) = sr_[i].vs1; \
;     *(bf16x8*)(K_lds + (b) * AT_SHM_K + kst) = sr_[i].ks0; } while (0)
; #define SWAIT() asm volatile("s_waitcnt vmcnt(3)" ::: "memory")
; DEV void partialSM(f32x16& p0, f32x16& p1, float& m_reg, float& mn, float& alpha) {
;   constexpr float C = AT_SCALE * 1.4426950408889634f;
;   float pmax = p0[0];
; #pragma unroll
;   for (int r = 1; r < 16; ++r) pmax = fmaxf(pmax, p0[r]);
; #pragma unroll
;   for (int r = 0; r < 16; ++r) pmax = fmaxf(pmax, p1[r]);
;   { auto rr = __builtin_amdgcn_permlane32_swap(__float_as_uint(pmax), __float_as_uint(pmax), false, false);
;     pmax = fmaxf(__uint_as_float(rr[0]), __uint_as_float(rr[1])); }
;   if (__builtin_expect(__all(pmax - m_reg <= AT_THR / AT_SCALE), 1)) { mn = m_reg; alpha = 1.f; }
;   else { mn = fmaxf(m_reg, pmax); alpha = __builtin_amdgcn_exp2f((m_reg - mn) * C); m_reg = mn; }
; DEV void attn_pass(const u16* __restrict__ Qb, const u16* __restrict__ Kh, const u16* __restrict__ Vh, int seq, f32x16* o, float* rli) {
;     ...
;   f32x16 pA0, pA1, pB0, pB1; float mnA, mnB, alA, alB; bf16x8 pa0, pa1, pa2, pa3; const int NT = seq / 64;
;   constexpr int SE = 0, SO = 1;
;   SLOAD(SE, 0); SLOAD(SO, 64);
;   asm volatile("s_waitcnt vmcnt(3)" ::: "memory"); SWRITE(0, SE); __syncthreads();
;   if (2 < NT) SLOAD(SE, 2 * 64);
;   qkt(pA0, pA1, K_lds, qr, r32, hi); partialSM(pA0, pA1, m_reg, mnA, alA);
;   SWAIT(); SWRITE(1, SO); __syncthreads();
; #pragma unroll 1
;   for (int j = 1; j + 1 < NT; j += 2) {
;     const int bm1 = (j - 1) % 3, b0 = j % 3, b1 = (j + 1) % 3, b2 = (j + 2) % 3;
;     SBAR(); qkt(pB0, pB1, K_lds + b0 * AT_SHM_K, qr, r32, hi);
;     finishSM(pA0, pA1, alA, l_reg, pa0, pa1, pa2, pa3); SBAR();
;     SLOAD(SO, (j + 2) * 64); SBAR();
;     pv_d0(o, vb0 + bm1 * AT_SHM_V, pa0, pa1, pa2, pa3); partialSM(pB0, pB1, m_reg, mnB, alB);
;     SWAIT(); SWRITE(b1, SE);
;     RESC(alB); __syncthreads();
	s_nop 0
	v_mfma_f32_32x32x16_bf16 v[0:15], v[136:139], v[186:189], v[0:15]
	ds_read_b64_tr_b16 v[186:187], v150 offset:0x200
	ds_read_b64_tr_b16 v[188:189], v150 offset:0xa00
	v_mfma_f32_32x32x16_bf16 v[0:15], v[142:145], v[190:193], v[0:15]
	ds_read_b64_tr_b16 v[190:191], v150 offset:0x1200
	ds_read_b64_tr_b16 v[192:193], v150 offset:0x1a00
	v_mfma_f32_32x32x16_bf16 v[0:15], v[146:149], v[220:223], v[0:15]
	ds_read_b64_tr_b16 v[220:221], v150 offset:0x2200
	ds_read_b64_tr_b16 v[222:223], v150 offset:0x2a00
	v_mfma_f32_32x32x16_bf16 v[0:15], v[164:167], v[224:227], v[0:15]
	ds_read_b64_tr_b16 v[224:225], v150 offset:0x3200
	ds_read_b64_tr_b16 v[226:227], v150 offset:0x3a00
	s_waitcnt lgkmcnt(0)
	v_mfma_f32_32x32x16_bf16 v[48:63], v[136:139], v[186:189], v[48:63]
	ds_read_b64_tr_b16 v[186:187], v150 offset:0x400
	ds_read_b64_tr_b16 v[188:189], v150 offset:0xc00
	v_mfma_f32_32x32x16_bf16 v[48:63], v[142:145], v[190:193], v[48:63]
	ds_read_b64_tr_b16 v[190:191], v150 offset:0x1400
	ds_read_b64_tr_b16 v[192:193], v150 offset:0x1c00
	v_mfma_f32_32x32x16_bf16 v[48:63], v[146:149], v[220:223], v[48:63]
	ds_read_b64_tr_b16 v[220:221], v150 offset:0x2400
	ds_read_b64_tr_b16 v[222:223], v150 offset:0x2c00
	v_mfma_f32_32x32x16_bf16 v[48:63], v[164:167], v[224:227], v[48:63]
	ds_read_b64_tr_b16 v[224:225], v150 offset:0x3400
	ds_read_b64_tr_b16 v[226:227], v150 offset:0x3c00
	s_waitcnt lgkmcnt(0)
	v_mfma_f32_32x32x16_bf16 v[32:47], v[136:139], v[186:189], v[32:47]
	ds_read_b64_tr_b16 v[186:187], v150 offset:0x600
	ds_read_b64_tr_b16 v[188:189], v150 offset:0xe00
	v_mfma_f32_32x32x16_bf16 v[32:47], v[142:145], v[190:193], v[32:47]
	ds_read_b64_tr_b16 v[190:191], v150 offset:0x1600
	ds_read_b64_tr_b16 v[192:193], v150 offset:0x1e00
	v_mfma_f32_32x32x16_bf16 v[32:47], v[146:149], v[220:223], v[32:47]
	ds_read_b64_tr_b16 v[220:221], v150 offset:0x2600
	ds_read_b64_tr_b16 v[222:223], v150 offset:0x2e00
	v_mfma_f32_32x32x16_bf16 v[32:47], v[164:167], v[224:227], v[32:47]
	ds_read_b64_tr_b16 v[224:225], v150 offset:0x3600
	ds_read_b64_tr_b16 v[226:227], v150 offset:0x3e00
	s_waitcnt lgkmcnt(0)
	v_mfma_f32_32x32x16_bf16 v[16:31], v[136:139], v[186:189], v[16:31]
	v_max_f32_e32 v136, v80, v81
	v_max3_f32 v136, v136, v82, v83
	v_max3_f32 v136, v136, v84, v85
	v_max3_f32 v136, v136, v86, v87
	v_max3_f32 v136, v136, v88, v89
	v_max3_f32 v136, v136, v90, v91
	v_max3_f32 v136, v136, v92, v93
	v_max3_f32 v136, v136, v94, v95
	v_mfma_f32_32x32x16_bf16 v[16:31], v[142:145], v[190:193], v[16:31]
	v_max3_f32 v136, v136, v64, v65
	v_max3_f32 v136, v136, v66, v67
	v_max3_f32 v136, v136, v68, v69
	v_max3_f32 v136, v136, v70, v71
	v_max3_f32 v136, v136, v72, v73
	v_max3_f32 v136, v136, v74, v75
	v_max3_f32 v136, v136, v76, v77
	v_max3_f32 v136, v136, v78, v79
	v_mfma_f32_32x32x16_bf16 v[16:31], v[146:149], v[220:223], v[16:31]
	v_mov_b32_e32 v137, v136
	s_nop 1
	v_permlane32_swap_b32_e32 v136, v137
	v_max_f32_e32 v136, v136, v137
	v_cmp_ge_f32_e32 vcc, s18, v136
	v_mfma_f32_32x32x16_bf16 v[16:31], v[164:167], v[224:227], v[16:31]
	s_cmp_eq_u64 vcc, exec
	s_cselect_b64 s[0:1], -1, 0
	s_cbranch_scc1 .Lattn_fast1
	v_max_f32_e32 v136, 0, v136
	v_exp_f32_e64 v137, -v136
.Lattn_fast1:
	v_add_u32_e32 v214, s8, v202
	v_cndmask_b32_e64 v213, v137, 1.0, s[0:1]
	v_cmp_gt_f32_e32 vcc, 1.0, v213
	s_cbranch_vccz .LBB0_74
	s_and_saveexec_b64 s[10:11], s[6:7]
	ds_write_b32 v169, v213 offset:128
	s_or_b64 exec, exec, s[10:11]
	s_waitcnt lgkmcnt(0)
	v_add_u32_e32 v137, v168, v162
	ds_read_b128 v[142:145], v137 offset:224
	ds_read_b128 v[146:149], v137 offset:192
	ds_read_b128 v[164:167], v137 offset:160
	ds_read_b128 v[186:189], v137 offset:128
	s_waitcnt lgkmcnt(3)
	v_pk_mul_f32 v[12:13], v[12:13], v[142:143]
	s_waitcnt lgkmcnt(2)
	v_pk_mul_f32 v[8:9], v[8:9], v[146:147]
	s_waitcnt lgkmcnt(1)
	v_pk_mul_f32 v[4:5], v[4:5], v[164:165]
	v_pk_mul_f32 v[14:15], v[14:15], v[144:145]
	v_pk_mul_f32 v[10:11], v[10:11], v[148:149]
	v_pk_mul_f32 v[6:7], v[6:7], v[166:167]
	s_waitcnt lgkmcnt(0)
	v_pk_mul_f32 v[2:3], v[2:3], v[188:189]
	v_pk_mul_f32 v[0:1], v[0:1], v[186:187]
	v_pk_mul_f32 v[60:61], v[60:61], v[142:143]
	v_pk_mul_f32 v[56:57], v[56:57], v[146:147]
	v_pk_mul_f32 v[52:53], v[52:53], v[164:165]
	v_pk_mul_f32 v[62:63], v[62:63], v[144:145]
	v_pk_mul_f32 v[58:59], v[58:59], v[148:149]
	v_pk_mul_f32 v[54:55], v[54:55], v[166:167]
	v_pk_mul_f32 v[50:51], v[50:51], v[188:189]
	v_pk_mul_f32 v[48:49], v[48:49], v[186:187]
	v_pk_mul_f32 v[44:45], v[44:45], v[142:143]
	v_pk_mul_f32 v[40:41], v[40:41], v[146:147]
	v_pk_mul_f32 v[36:37], v[36:37], v[164:165]
	v_pk_mul_f32 v[46:47], v[46:47], v[144:145]
	v_pk_mul_f32 v[42:43], v[42:43], v[148:149]
	v_pk_mul_f32 v[38:39], v[38:39], v[166:167]
	v_pk_mul_f32 v[34:35], v[34:35], v[188:189]
	v_pk_mul_f32 v[32:33], v[32:33], v[186:187]
	v_pk_mul_f32 v[28:29], v[28:29], v[142:143]
	v_pk_mul_f32 v[24:25], v[24:25], v[146:147]
	v_pk_mul_f32 v[20:21], v[20:21], v[164:165]
	v_pk_mul_f32 v[30:31], v[30:31], v[144:145]
	v_pk_mul_f32 v[26:27], v[26:27], v[148:149]
	v_pk_mul_f32 v[22:23], v[22:23], v[166:167]
	v_pk_mul_f32 v[18:19], v[18:19], v[188:189]
	v_pk_mul_f32 v[16:17], v[16:17], v[186:187]
	v_sub_f32_e32 v80, v80, v136
	v_sub_f32_e32 v81, v81, v136
	v_sub_f32_e32 v82, v82, v136
	v_sub_f32_e32 v83, v83, v136
	v_sub_f32_e32 v84, v84, v136
	v_sub_f32_e32 v85, v85, v136
	v_sub_f32_e32 v86, v86, v136
	v_sub_f32_e32 v87, v87, v136
	v_sub_f32_e32 v88, v88, v136
	v_sub_f32_e32 v89, v89, v136
	v_sub_f32_e32 v90, v90, v136
	v_sub_f32_e32 v91, v91, v136
	v_sub_f32_e32 v92, v92, v136
	v_sub_f32_e32 v93, v93, v136
	v_sub_f32_e32 v94, v94, v136
	v_sub_f32_e32 v95, v95, v136
	v_sub_f32_e32 v64, v64, v136
	v_sub_f32_e32 v65, v65, v136
	v_sub_f32_e32 v66, v66, v136
	v_sub_f32_e32 v67, v67, v136
	v_sub_f32_e32 v68, v68, v136
	v_sub_f32_e32 v69, v69, v136
	v_sub_f32_e32 v70, v70, v136
	v_sub_f32_e32 v71, v71, v136
	v_sub_f32_e32 v72, v72, v136
	v_sub_f32_e32 v73, v73, v136
	v_sub_f32_e32 v74, v74, v136
	v_sub_f32_e32 v75, v75, v136
	v_sub_f32_e32 v76, v76, v136
	v_sub_f32_e32 v77, v77, v136
	v_sub_f32_e32 v78, v78, v136
	v_sub_f32_e32 v79, v79, v136
	v_sub_f32_e32 v236, v236, v136
	v_sub_f32_e32 v237, v237, v136
	v_sub_f32_e32 v238, v238, v136
	v_sub_f32_e32 v239, v239, v136
	v_sub_f32_e32 v240, v240, v136
	v_sub_f32_e32 v241, v241, v136
	v_sub_f32_e32 v242, v242, v136
	v_sub_f32_e32 v243, v243, v136
	v_sub_f32_e32 v244, v244, v136
	v_sub_f32_e32 v245, v245, v136
	v_sub_f32_e32 v246, v246, v136
	v_sub_f32_e32 v247, v247, v136
	v_sub_f32_e32 v248, v248, v136
	v_sub_f32_e32 v249, v249, v136
	v_sub_f32_e32 v250, v250, v136
	v_sub_f32_e32 v251, v251, v136
; #define SBAR() __builtin_amdgcn_sched_barrier(0)
; DEV void partialSM(f32x16& p0, f32x16& p1, float& m_reg, float& mn, float& alpha) {
;   constexpr float C = AT_SCALE * 1.4426950408889634f;
;   float pmax = p0[0];
; #pragma unroll
;   for (int r = 1; r < 16; ++r) pmax = fmaxf(pmax, p0[r]);
; #pragma unroll
;   for (int r = 0; r < 16; ++r) pmax = fmaxf(pmax, p1[r]);
;   { auto rr = __builtin_amdgcn_permlane32_swap(__float_as_uint(pmax), __float_as_uint(pmax), false, false);
;     pmax = fmaxf(__uint_as_float(rr[0]), __uint_as_float(rr[1])); }
;   if (__builtin_expect(__all(pmax - m_reg <= AT_THR / AT_SCALE), 1)) { mn = m_reg; alpha = 1.f; }
;   else { mn = fmaxf(m_reg, pmax); alpha = __builtin_amdgcn_exp2f((m_reg - mn) * C); m_reg = mn; }
;   float mnC = -mn * C;
; #pragma unroll
;   for (int r = 0; r < 16; ++r) p0[r] = fmaf(p0[r], C, mnC);
; #pragma unroll
;   for (int r = 0; r < 16; ++r) p1[r] = fmaf(p1[r], C, mnC);
; #pragma unroll
;   for (int r = 0; r < 16; ++r) p0[r] = __builtin_amdgcn_exp2f(p0[r]);
; }
; DEV void finishSM(f32x16& p0, f32x16& p1, float alpha, float& l_reg, bf16x8& pa0, bf16x8& pa1, bf16x8& pa2, bf16x8& pa3) {
; #pragma unroll
;   for (int r = 0; r < 16; ++r) p1[r] = __builtin_amdgcn_exp2f(p1[r]);
;   float ps = 0;
; #pragma unroll
;   for (int r = 0; r < 16; ++r) ps += p0[r];
; #pragma unroll
;   for (int r = 0; r < 16; ++r) ps += p1[r];
;   { auto rr = __builtin_amdgcn_permlane32_swap(__float_as_uint(ps), __float_as_uint(ps), false, false);
;     ps = __uint_as_float(rr[0]) + __uint_as_float(rr[1]); }
;   l_reg = l_reg * alpha + ps;
;     ...
;   PK4(p0, 0, pa0); PK4(p0, 8, pa1); PK4(p1, 0, pa2); PK4(p1, 8, pa3);
;     ...
; }
; DEV void qkt(f32x16& p0, f32x16& p1, const char* Ks, const bf16x8* qr, int r32, int hi) {
;   p0 = f32x16{}; p1 = f32x16{};
; #pragma unroll
;   for (int d0 = 0; d0 < 4; ++d0) { int cb = (d0 * 16 + hi * 8) * 2;
;     bf16x8 b0 = *reinterpret_cast<const bf16x8*>(Ks + KSWZ64(r32, cb));
;     bf16x8 b1 = *reinterpret_cast<const bf16x8*>(Ks + KSWZ64(32 + r32, cb));
;     p0 = __builtin_amdgcn_mfma_f32_32x32x16_bf16(b0, qr[d0], p0, 0, 0, 0);
;     p1 = __builtin_amdgcn_mfma_f32_32x32x16_bf16(b1, qr[d0], p1, 0, 0, 0); }
; }
; DEV void attn_pass(const u16* __restrict__ Qb, const u16* __restrict__ Kh, const u16* __restrict__ Vh, int seq, f32x16* o, float* rli) {
;     ...
;     SLOAD(SO, (j + 2) * 64); SBAR();
.LBB0_74:
	v_subrev_u32_e32 v137, s15, v183
	v_subrev_u32_e32 v138, s15, v185
	v_subrev_u32_e32 v146, s15, v199
	v_subrev_u32_e32 v147, s15, v201
	v_mov_b32_e32 v149, v64
	v_mov_b32_e32 v150, v65
	v_mov_b32_e32 v151, v66
	v_mov_b32_e32 v164, v67
	v_mov_b32_e32 v165, v68
	v_mov_b32_e32 v166, v69
	v_mov_b32_e32 v167, v70
	v_mov_b32_e32 v186, v71
	v_mov_b32_e32 v187, v72
	v_mov_b32_e32 v188, v73
	v_mov_b32_e32 v189, v74
	v_mov_b32_e32 v190, v75
	v_mov_b32_e32 v191, v76
	v_mov_b32_e32 v192, v77
	v_mov_b32_e32 v193, v78
	v_mov_b32_e32 v148, v79
	v_exp_f32_e32 v194, v80
	v_exp_f32_e32 v195, v81
	v_exp_f32_e32 v218, v82
	v_exp_f32_e32 v219, v83
	v_exp_f32_e32 v220, v84
	v_exp_f32_e32 v221, v85
	v_exp_f32_e32 v222, v86
	v_exp_f32_e32 v223, v87
	v_exp_f32_e32 v224, v88
	v_exp_f32_e32 v225, v89
	v_exp_f32_e32 v226, v90
	v_exp_f32_e32 v227, v91
	v_exp_f32_e32 v228, v92
	v_exp_f32_e32 v229, v93
	v_exp_f32_e32 v230, v94
	v_exp_f32_e32 v231, v95
	s_waitcnt lgkmcnt(0)
	s_barrier
	v_add_u32_e32 v68, v141, v137
	ds_read_b128 v[64:67], v68
	ds_read_b128 v[68:71], v68 offset:4096
	v_add_u32_e32 v140, v141, v138
	ds_read_b128 v[136:139], v140
	ds_read_b128 v[142:145], v140 offset:4096
	v_add_u32_e32 v140, v141, v146
	s_waitcnt vmcnt(0)
	s_mul_hi_u32 s0, s50, 0xaaaaaaab
	s_lshr_b32 s0, s0, 1
	s_mul_i32 s1, s0, 0x6000
	s_mul_i32 s0, s0, 0xc000
	v_subrev_u32_e32 v72, s0, v207
	v_add_u32_e32 v72, v214, v72
	ds_write_b128 v72, v[124:127]
	v_subrev_u32_e32 v72, s0, v206
	v_add_u32_e32 v72, v214, v72
	ds_write_b128 v72, v[128:131]
	v_subrev_u32_e32 v72, s1, v205
	v_add_u32_e32 v72, s13, v72
	ds_write_b128 v72, v[132:135]
	s_waitcnt lgkmcnt(6)
	v_mfma_f32_32x32x16_bf16 v[80:95], v[64:67], v[108:111], v[236:251]
	v_exp_f32_e32 v146, v151
	v_exp_f32_e32 v151, v167
	v_exp_f32_e32 v167, v189
	v_exp_f32_e32 v189, v193
	s_waitcnt lgkmcnt(5)
	v_mfma_f32_32x32x16_bf16 v[64:79], v[68:71], v[108:111], v[236:251]
	s_waitcnt lgkmcnt(4)
	v_mfma_f32_32x32x16_bf16 v[80:95], v[136:139], v[104:107], v[80:95]
	s_waitcnt lgkmcnt(3)
	v_mfma_f32_32x32x16_bf16 v[64:79], v[142:145], v[104:107], v[64:79]
	ds_read_b128 v[136:139], v140
	ds_read_b128 v[142:145], v140 offset:4096
	v_add_u32_e32 v140, v141, v147
	v_exp_f32_e32 v147, v164
	v_exp_f32_e32 v164, v186
	v_exp_f32_e32 v186, v190
	v_exp_f32_e32 v190, v148
	s_waitcnt lgkmcnt(1)
	v_mfma_f32_32x32x16_bf16 v[80:95], v[136:139], v[100:103], v[80:95]
	s_waitcnt lgkmcnt(0)
	v_mfma_f32_32x32x16_bf16 v[64:79], v[142:145], v[100:103], v[64:79]
	ds_read_b128 v[136:139], v140
	ds_read_b128 v[140:143], v140 offset:4096
	v_exp_f32_e32 v144, v149
	v_exp_f32_e32 v145, v150
	v_exp_f32_e32 v149, v165
	v_exp_f32_e32 v150, v166
	v_exp_f32_e32 v165, v187
	v_exp_f32_e32 v166, v188
	s_waitcnt lgkmcnt(1)
	v_mfma_f32_32x32x16_bf16 v[80:95], v[136:139], v[96:99], v[80:95]
	v_add_f32_e32 v136, v195, v194
	v_add_f32_e32 v136, v218, v136
	v_add_f32_e32 v136, v219, v136
	v_add_f32_e32 v136, v220, v136
	v_add_f32_e32 v136, v221, v136
	v_add_f32_e32 v136, v222, v136
	v_add_f32_e32 v136, v223, v136
	v_add_f32_e32 v136, v224, v136
	v_add_f32_e32 v136, v225, v136
	v_add_f32_e32 v136, v226, v136
	v_add_f32_e32 v136, v227, v136
	v_add_f32_e32 v136, v228, v136
	v_add_f32_e32 v136, v229, v136
	v_add_f32_e32 v136, v230, v136
	v_add_f32_e32 v136, v231, v136
	v_add_f32_e32 v136, v144, v136
	v_add_f32_e32 v136, v145, v136
	v_add_f32_e32 v136, v146, v136
	v_add_f32_e32 v136, v147, v136
	v_add_f32_e32 v136, v149, v136
	v_add_f32_e32 v136, v150, v136
	v_add_f32_e32 v136, v151, v136
	v_add_f32_e32 v136, v164, v136
	v_exp_f32_e32 v187, v191
	v_add_f32_e32 v136, v165, v136
	v_exp_f32_e32 v188, v192
	v_add_f32_e32 v136, v166, v136
	s_waitcnt lgkmcnt(0)
	v_mfma_f32_32x32x16_bf16 v[64:79], v[140:143], v[96:99], v[64:79]
	v_add_f32_e32 v136, v167, v136
	v_add_f32_e32 v136, v186, v136
	v_add_f32_e32 v136, v187, v136
	v_add_f32_e32 v136, v188, v136
	v_add_f32_e32 v136, v189, v136
	v_add_f32_e32 v216, v190, v136
	v_mov_b32_e32 v217, v216
	v_cvt_pk_bf16_f32 v136, v194, v195
	v_cvt_pk_bf16_f32 v137, v218, v219
	v_cvt_pk_bf16_f32 v138, v220, v221
	v_cvt_pk_bf16_f32 v139, v222, v223
	v_cvt_pk_bf16_f32 v140, v224, v225
	v_cvt_pk_bf16_f32 v141, v226, v227
	v_cvt_pk_bf16_f32 v142, v228, v229
	v_cvt_pk_bf16_f32 v143, v230, v231
	v_cvt_pk_bf16_f32 v144, v144, v145
	v_cvt_pk_bf16_f32 v145, v146, v147
	v_cvt_pk_bf16_f32 v146, v149, v150
	v_cvt_pk_bf16_f32 v147, v151, v164
	v_cvt_pk_bf16_f32 v148, v165, v166
	v_cvt_pk_bf16_f32 v149, v167, v186
	v_cvt_pk_bf16_f32 v150, v187, v188
	v_cvt_pk_bf16_f32 v151, v189, v190
	s_nop 1
	v_permlane32_swap_b32_e32 v216, v217
	v_permlane32_swap_b32_e32 v136, v138
	v_permlane32_swap_b32_e32 v137, v139
	v_permlane32_swap_b32_e32 v140, v142
	v_permlane32_swap_b32_e32 v141, v143
	v_permlane32_swap_b32_e32 v144, v146
	v_permlane32_swap_b32_e32 v145, v147
	v_permlane32_swap_b32_e32 v148, v150
	v_permlane32_swap_b32_e32 v149, v151
	s_cmp_ge_u32 s45, s44
	s_cselect_b64 s[10:11], -1, 0
	s_and_b64 vcc, exec, s[10:11]
	s_cbranch_vccnz .LBB0_76
	v_add_co_u32_e32 v112, vcc, 0x1a810000, v158
	s_nop 1
	v_addc_co_u32_e32 v113, vcc, 0, v159, vcc
	v_add_co_u32_e32 v114, vcc, 0x1a812000, v158
	s_nop 1
	v_addc_co_u32_e32 v115, vcc, 0, v159, vcc
	v_add_co_u32_e32 v120, vcc, 0x18608000, v160
	global_load_dwordx4 v[116:119], v[112:113], off
	s_nop 0
	global_load_dwordx4 v[112:115], v[114:115], off
	v_addc_co_u32_e32 v121, vcc, 0, v161, vcc
	global_load_dwordx4 v[120:123], v[120:121], off
; #define SBAR() __builtin_amdgcn_sched_barrier(0)
; DEV void partialSM(f32x16& p0, f32x16& p1, float& m_reg, float& mn, float& alpha) {
;   constexpr float C = AT_SCALE * 1.4426950408889634f;
;   float pmax = p0[0];
; #pragma unroll
;   for (int r = 1; r < 16; ++r) pmax = fmaxf(pmax, p0[r]);
; #pragma unroll
;   for (int r = 0; r < 16; ++r) pmax = fmaxf(pmax, p1[r]);
;   { auto rr = __builtin_amdgcn_permlane32_swap(__float_as_uint(pmax), __float_as_uint(pmax), false, false);
;     pmax = fmaxf(__uint_as_float(rr[0]), __uint_as_float(rr[1])); }
;   if (__builtin_expect(__all(pmax - m_reg <= AT_THR / AT_SCALE), 1)) { mn = m_reg; alpha = 1.f; }
;   else { mn = fmaxf(m_reg, pmax); alpha = __builtin_amdgcn_exp2f((m_reg - mn) * C); m_reg = mn; }
; template <int OFF> DEV s16x4 tr_read(int vb) {
;   s16x4 r; asm volatile("ds_read_b64_tr_b16 %0, %1 offset:%2" : "=&v"(r) : "v"(vb), "i"(OFF) : "memory"); return r;
; }
; template <int D0> DEV void pv_one(f32x16& od, int vb, bf16x8 pa0, bf16x8 pa1, bf16x8 pa2, bf16x8 pa3) {
;   const s16x4 l0 = tr_read<v_rd_off(D0, 0, 0)>(vb), h0 = tr_read<v_rd_off(D0, 0, 1)>(vb), l1 = tr_read<v_rd_off(D0, 1, 0)>(vb), h1 = tr_read<v_rd_off(D0, 1, 1)>(vb);
;   const s16x4 l2 = tr_read<v_rd_off(D0, 2, 0)>(vb), h2 = tr_read<v_rd_off(D0, 2, 1)>(vb), l3 = tr_read<v_rd_off(D0, 3, 0)>(vb), h3 = tr_read<v_rd_off(D0, 3, 1)>(vb);
;   asm volatile("s_waitcnt lgkmcnt(0)" ::: "memory"); SBAR();
;     ...
;   od = __builtin_amdgcn_mfma_f32_32x32x16_bf16(pa0, PK(l0, h0), od, 0, 0, 0);
;   od = __builtin_amdgcn_mfma_f32_32x32x16_bf16(pa1, PK(l1, h1), od, 0, 0, 0);
;   od = __builtin_amdgcn_mfma_f32_32x32x16_bf16(pa2, PK(l2, h2), od, 0, 0, 0);
;   od = __builtin_amdgcn_mfma_f32_32x32x16_bf16(pa3, PK(l3, h3), od, 0, 0, 0);
;     ...
; }
; DEV void pv_d0(f32x16* o, int vb, bf16x8 pa0, bf16x8 pa1, bf16x8 pa2, bf16x8 pa3) {
;   pv_one<0>(o[0], vb, pa0, pa1, pa2, pa3); pv_one<1>(o[1], vb, pa0, pa1, pa2, pa3); pv_one<2>(o[2], vb, pa0, pa1, pa2, pa3); pv_one<3>(o[3], vb, pa0, pa1, pa2, pa3);
.LBB0_76:
	s_mul_hi_u32 s0, s50, 0xaaaaaaab
	s_lshr_b32 s0, s0, 1
	s_mul_i32 s1, s0, 0x6000
	s_mul_i32 s0, s0, 0xc000
	s_mul_i32 s12, s12, 0xc000
	v_subrev_u32_e32 v158, s12, v208
	v_add_u32_e32 v219, s8, v158
	ds_read_b64_tr_b16 v[158:159], v219 offset:0
	ds_read_b64_tr_b16 v[160:161], v219 offset:0x800
	ds_read_b64_tr_b16 v[164:165], v219 offset:0x1000
	ds_read_b64_tr_b16 v[166:167], v219 offset:0x1800
	ds_read_b64_tr_b16 v[186:187], v219 offset:0x2000
	ds_read_b64_tr_b16 v[188:189], v219 offset:0x2800
	ds_read_b64_tr_b16 v[190:191], v219 offset:0x3000
	ds_read_b64_tr_b16 v[192:193], v219 offset:0x3800
	s_waitcnt lgkmcnt(0)
	s_nop 0
	v_mfma_f32_32x32x16_bf16 v[0:15], v[136:139], v[158:161], v[0:15]
	ds_read_b64_tr_b16 v[158:159], v219 offset:0x200
	ds_read_b64_tr_b16 v[160:161], v219 offset:0xa00
	v_mfma_f32_32x32x16_bf16 v[0:15], v[140:143], v[164:167], v[0:15]
	ds_read_b64_tr_b16 v[164:165], v219 offset:0x1200
	ds_read_b64_tr_b16 v[166:167], v219 offset:0x1a00
	v_mfma_f32_32x32x16_bf16 v[0:15], v[144:147], v[186:189], v[0:15]
	ds_read_b64_tr_b16 v[186:187], v219 offset:0x2200
	ds_read_b64_tr_b16 v[188:189], v219 offset:0x2a00
	v_mfma_f32_32x32x16_bf16 v[0:15], v[148:151], v[190:193], v[0:15]
	ds_read_b64_tr_b16 v[190:191], v219 offset:0x3200
	ds_read_b64_tr_b16 v[192:193], v219 offset:0x3a00
	s_waitcnt lgkmcnt(0)
	v_mfma_f32_32x32x16_bf16 v[48:63], v[136:139], v[158:161], v[48:63]
	ds_read_b64_tr_b16 v[158:159], v219 offset:0x400
	ds_read_b64_tr_b16 v[160:161], v219 offset:0xc00
	v_mfma_f32_32x32x16_bf16 v[48:63], v[140:143], v[164:167], v[48:63]
	ds_read_b64_tr_b16 v[164:165], v219 offset:0x1400
	ds_read_b64_tr_b16 v[166:167], v219 offset:0x1c00
	v_mfma_f32_32x32x16_bf16 v[48:63], v[144:147], v[186:189], v[48:63]
	ds_read_b64_tr_b16 v[186:187], v219 offset:0x2400
	ds_read_b64_tr_b16 v[188:189], v219 offset:0x2c00
	v_mfma_f32_32x32x16_bf16 v[48:63], v[148:151], v[190:193], v[48:63]
	ds_read_b64_tr_b16 v[190:191], v219 offset:0x3400
	ds_read_b64_tr_b16 v[192:193], v219 offset:0x3c00
	s_waitcnt lgkmcnt(0)
	v_mfma_f32_32x32x16_bf16 v[32:47], v[136:139], v[158:161], v[32:47]
	ds_read_b64_tr_b16 v[158:159], v219 offset:0x600
	ds_read_b64_tr_b16 v[160:161], v219 offset:0xe00
	v_mfma_f32_32x32x16_bf16 v[32:47], v[140:143], v[164:167], v[32:47]
	ds_read_b64_tr_b16 v[164:165], v219 offset:0x1600
	ds_read_b64_tr_b16 v[166:167], v219 offset:0x1e00
	v_mfma_f32_32x32x16_bf16 v[32:47], v[144:147], v[186:189], v[32:47]
	ds_read_b64_tr_b16 v[186:187], v219 offset:0x2600
	ds_read_b64_tr_b16 v[188:189], v219 offset:0x2e00
	v_mfma_f32_32x32x16_bf16 v[32:47], v[148:151], v[190:193], v[32:47]
	ds_read_b64_tr_b16 v[190:191], v219 offset:0x3600
	ds_read_b64_tr_b16 v[192:193], v219 offset:0x3e00
	s_waitcnt lgkmcnt(0)
	v_mfma_f32_32x32x16_bf16 v[16:31], v[136:139], v[158:161], v[16:31]
	v_max_f32_e32 v136, v80, v81
	v_max3_f32 v136, v136, v82, v83
	v_max3_f32 v136, v136, v84, v85
	v_max3_f32 v136, v136, v86, v87
	v_max3_f32 v136, v136, v88, v89
	v_max3_f32 v136, v136, v90, v91
	v_max3_f32 v136, v136, v92, v93
	v_max3_f32 v136, v136, v94, v95
	v_mfma_f32_32x32x16_bf16 v[16:31], v[140:143], v[164:167], v[16:31]
	v_max3_f32 v136, v136, v64, v65
	v_max3_f32 v136, v136, v66, v67
	v_max3_f32 v136, v136, v68, v69
	v_max3_f32 v136, v136, v70, v71
	v_max3_f32 v136, v136, v72, v73
	v_max3_f32 v136, v136, v74, v75
	v_max3_f32 v136, v136, v76, v77
	v_max3_f32 v136, v136, v78, v79
	v_mfma_f32_32x32x16_bf16 v[16:31], v[144:147], v[186:189], v[16:31]
	v_mov_b32_e32 v137, v136
	s_nop 1
	v_permlane32_swap_b32_e32 v136, v137
	v_max_f32_e32 v136, v136, v137
	v_cmp_ge_f32_e32 vcc, s18, v136
	v_mfma_f32_32x32x16_bf16 v[16:31], v[148:151], v[190:193], v[16:31]
	s_cmp_eq_u64 vcc, exec
	s_cselect_b64 s[0:1], -1, 0
	s_cbranch_scc1 .Lattn_fast2
	v_max_f32_e32 v136, 0, v136
	v_exp_f32_e64 v137, -v136
	s_nop 0
.Lattn_fast2:
	v_cndmask_b32_e64 v141, v137, 1.0, s[0:1]
	v_cmp_gt_f32_e32 vcc, 1.0, v141
	s_cbranch_vccz .LBB0_80
	s_and_saveexec_b64 s[12:13], s[6:7]
	ds_write_b32 v169, v141 offset:128
	s_or_b64 exec, exec, s[12:13]
	s_waitcnt lgkmcnt(0)
	v_add_u32_e32 v137, v168, v162
	ds_read_b128 v[124:127], v137 offset:224
	ds_read_b128 v[128:131], v137 offset:192
	ds_read_b128 v[132:135], v137 offset:160
	ds_read_b128 v[142:145], v137 offset:128
	s_waitcnt lgkmcnt(3)
	v_pk_mul_f32 v[12:13], v[12:13], v[124:125]
	s_waitcnt lgkmcnt(2)
	v_pk_mul_f32 v[8:9], v[8:9], v[128:129]
	s_waitcnt lgkmcnt(1)
	v_pk_mul_f32 v[4:5], v[4:5], v[132:133]
	v_pk_mul_f32 v[14:15], v[14:15], v[126:127]
	v_pk_mul_f32 v[10:11], v[10:11], v[130:131]
	v_pk_mul_f32 v[6:7], v[6:7], v[134:135]
	s_waitcnt lgkmcnt(0)
; #define SBAR() __builtin_amdgcn_sched_barrier(0)
; #define SLOAD(i, k0) do { sr_[i].vs0 = *reinterpret_cast<const bf16x8*>(&Vh[(size_t)((k0) + sr) * 128 + sc]); sr_[i].vs1 = *reinterpret_cast<const bf16x8*>(&Vh[(size_t)((k0) + 32 + sr) * 128 + sc]); \
;     sr_[i].ks0 = *reinterpret_cast<const bf16x8*>(&Kh[(size_t)((k0) + kr) * 64 + kc]); } while (0)
; #define SWRITE(b, i) do { *(bf16x8*)(V_lds + (b) * AT_SHM_V + vst0) = sr_[i].vs0; *(bf16x8*)(V_lds + (b) * AT_SHM_V + vst1) = sr_[i].vs1; \
;     *(bf16x8*)(K_lds + (b) * AT_SHM_K + kst) = sr_[i].ks0; } while (0)
; #define SWAIT() asm volatile("s_waitcnt vmcnt(3)" ::: "memory")
; DEV void partialSM(f32x16& p0, f32x16& p1, float& m_reg, float& mn, float& alpha) {
;   constexpr float C = AT_SCALE * 1.4426950408889634f;
;   float pmax = p0[0];
; #pragma unroll
;   for (int r = 1; r < 16; ++r) pmax = fmaxf(pmax, p0[r]);
; #pragma unroll
;   for (int r = 0; r < 16; ++r) pmax = fmaxf(pmax, p1[r]);
;   { auto rr = __builtin_amdgcn_permlane32_swap(__float_as_uint(pmax), __float_as_uint(pmax), false, false);
;     pmax = fmaxf(__uint_as_float(rr[0]), __uint_as_float(rr[1])); }
;   if (__builtin_expect(__all(pmax - m_reg <= AT_THR / AT_SCALE), 1)) { mn = m_reg; alpha = 1.f; }
;   else { mn = fmaxf(m_reg, pmax); alpha = __builtin_amdgcn_exp2f((m_reg - mn) * C); m_reg = mn; }
;   float mnC = -mn * C;
; #pragma unroll
;   for (int r = 0; r < 16; ++r) p0[r] = fmaf(p0[r], C, mnC);
; #pragma unroll
;   for (int r = 0; r < 16; ++r) p1[r] = fmaf(p1[r], C, mnC);
; #pragma unroll
;   for (int r = 0; r < 16; ++r) p0[r] = __builtin_amdgcn_exp2f(p0[r]);
; }
; DEV void attn_pass(const u16* __restrict__ Qb, const u16* __restrict__ Kh, const u16* __restrict__ Vh, int seq, f32x16* o, float* rli) {
;     ...
;     pv_d0(o, vb0 + bm1 * AT_SHM_V, pa0, pa1, pa2, pa3); partialSM(pB0, pB1, m_reg, mnB, alB);
;     SWAIT(); SWRITE(b1, SE);
;     RESC(alB); __syncthreads();
;     SBAR(); qkt(pA0, pA1, K_lds + b1 * AT_SHM_K, qr, r32, hi);
;     finishSM(pB0, pB1, alB, l_reg, pa0, pa1, pa2, pa3); SBAR();
;     if (j + 3 < NT) SLOAD(SE, (j + 3) * 64); SBAR();
;     pv_d0(o, vb0 + b0 * AT_SHM_V, pa0, pa1, pa2, pa3); partialSM(pA0, pA1, m_reg, mnA, alA);
;     SWAIT(); SWRITE(b2, SO);
;     RESC(alA); __syncthreads();
;   }
;   { const int bl = (NT - 1) % 3, bp = (NT - 2) % 3;
;     SBAR(); qkt(pB0, pB1, K_lds + bl * AT_SHM_K, qr, r32, hi);
	v_pk_mul_f32 v[2:3], v[2:3], v[144:145]
	v_pk_mul_f32 v[0:1], v[0:1], v[142:143]
	v_pk_mul_f32 v[60:61], v[60:61], v[124:125]
	v_pk_mul_f32 v[56:57], v[56:57], v[128:129]
	v_pk_mul_f32 v[52:53], v[52:53], v[132:133]
	v_pk_mul_f32 v[62:63], v[62:63], v[126:127]
	v_pk_mul_f32 v[58:59], v[58:59], v[130:131]
	v_pk_mul_f32 v[54:55], v[54:55], v[134:135]
	v_pk_mul_f32 v[50:51], v[50:51], v[144:145]
	v_pk_mul_f32 v[48:49], v[48:49], v[142:143]
	v_pk_mul_f32 v[44:45], v[44:45], v[124:125]
	v_pk_mul_f32 v[40:41], v[40:41], v[128:129]
	v_pk_mul_f32 v[36:37], v[36:37], v[132:133]
	v_pk_mul_f32 v[46:47], v[46:47], v[126:127]
	v_pk_mul_f32 v[42:43], v[42:43], v[130:131]
	v_pk_mul_f32 v[38:39], v[38:39], v[134:135]
	v_pk_mul_f32 v[34:35], v[34:35], v[144:145]
	v_pk_mul_f32 v[32:33], v[32:33], v[142:143]
	v_pk_mul_f32 v[28:29], v[28:29], v[124:125]
	v_pk_mul_f32 v[24:25], v[24:25], v[128:129]
	v_pk_mul_f32 v[20:21], v[20:21], v[132:133]
	v_pk_mul_f32 v[30:31], v[30:31], v[126:127]
	v_pk_mul_f32 v[26:27], v[26:27], v[130:131]
	v_pk_mul_f32 v[22:23], v[22:23], v[134:135]
	v_pk_mul_f32 v[18:19], v[18:19], v[144:145]
	v_pk_mul_f32 v[16:17], v[16:17], v[142:143]
	v_sub_f32_e32 v80, v80, v136
	v_sub_f32_e32 v81, v81, v136
	v_sub_f32_e32 v82, v82, v136
	v_sub_f32_e32 v83, v83, v136
	v_sub_f32_e32 v84, v84, v136
	v_sub_f32_e32 v85, v85, v136
	v_sub_f32_e32 v86, v86, v136
	v_sub_f32_e32 v87, v87, v136
	v_sub_f32_e32 v88, v88, v136
	v_sub_f32_e32 v89, v89, v136
	v_sub_f32_e32 v90, v90, v136
	v_sub_f32_e32 v91, v91, v136
	v_sub_f32_e32 v92, v92, v136
	v_sub_f32_e32 v93, v93, v136
	v_sub_f32_e32 v94, v94, v136
	v_sub_f32_e32 v95, v95, v136
	v_sub_f32_e32 v64, v64, v136
	v_sub_f32_e32 v65, v65, v136
	v_sub_f32_e32 v66, v66, v136
	v_sub_f32_e32 v67, v67, v136
	v_sub_f32_e32 v68, v68, v136
	v_sub_f32_e32 v69, v69, v136
	v_sub_f32_e32 v70, v70, v136
	v_sub_f32_e32 v71, v71, v136
	v_sub_f32_e32 v72, v72, v136
	v_sub_f32_e32 v73, v73, v136
	v_sub_f32_e32 v74, v74, v136
	v_sub_f32_e32 v75, v75, v136
	v_sub_f32_e32 v76, v76, v136
	v_sub_f32_e32 v77, v77, v136
	v_sub_f32_e32 v78, v78, v136
	v_sub_f32_e32 v79, v79, v136
	v_sub_f32_e32 v236, v236, v136
	v_sub_f32_e32 v237, v237, v136
	v_sub_f32_e32 v238, v238, v136
	v_sub_f32_e32 v239, v239, v136
	v_sub_f32_e32 v240, v240, v136
	v_sub_f32_e32 v241, v241, v136
	v_sub_f32_e32 v242, v242, v136
	v_sub_f32_e32 v243, v243, v136
	v_sub_f32_e32 v244, v244, v136
	v_sub_f32_e32 v245, v245, v136
	v_sub_f32_e32 v246, v246, v136
	v_sub_f32_e32 v247, v247, v136
	v_sub_f32_e32 v248, v248, v136
	v_sub_f32_e32 v249, v249, v136
	v_sub_f32_e32 v250, v250, v136
	v_sub_f32_e32 v251, v251, v136
.LBB0_80:
	v_exp_f32_e32 v150, v80
	v_exp_f32_e32 v160, v81
	v_exp_f32_e32 v151, v82
	v_exp_f32_e32 v161, v83
	v_exp_f32_e32 v158, v84
	v_exp_f32_e32 v214, v85
	v_exp_f32_e32 v159, v86
	v_exp_f32_e32 v215, v87
	v_exp_f32_e32 v142, v88
	v_exp_f32_e32 v146, v89
	v_exp_f32_e32 v143, v90
	v_exp_f32_e32 v147, v91
	v_exp_f32_e32 v144, v92
	v_exp_f32_e32 v148, v93
	v_exp_f32_e32 v145, v94
	v_exp_f32_e32 v149, v95
	v_mov_b64_e32 v[138:139], v[64:65]
	v_add_f32_e32 v64, v211, v212
	s_mov_b64 s[0:1], 0x4000
	v_fmac_f32_e32 v64, v182, v170
	v_add_f32_e32 v170, v216, v217
	v_lshl_add_u64 v[154:155], v[154:155], 0, s[0:1]
	s_mov_b64 s[0:1], 0x8000
	v_mov_b64_e32 v[136:137], v[66:67]
	v_mov_b64_e32 v[134:135], v[68:69]
	v_mov_b64_e32 v[132:133], v[70:71]
	v_mov_b64_e32 v[130:131], v[72:73]
	v_mov_b64_e32 v[128:129], v[74:75]
	v_mov_b64_e32 v[126:127], v[76:77]
	v_mov_b64_e32 v[124:125], v[78:79]
	v_fmac_f32_e32 v170, v64, v213
	s_addk_i32 s14, 0x4000
	s_add_i32 s66, s66, 2
	s_add_i32 s45, s45, 2
	s_add_i32 s9, s9, 2
	s_add_i32 s8, s8, 0x8000
	v_lshl_add_u64 v[156:157], v[156:157], 0, s[0:1]
	s_add_i32 s50, s50, 2
	s_add_i32 s51, s51, 2
	s_and_b64 vcc, exec, s[10:11]
	s_waitcnt lgkmcnt(0)
	s_barrier
	s_cbranch_vccnz .LBB0_82
	v_mov_b32_e32 v182, v141
	s_branch .LBB0_70
.LBB0_82:
	v_mov_b32_e32 v140, 0
	s_add_i32 s0, s44, 0xffff
	s_and_b32 s1, s0, 0xff
	s_mulk_i32 s1, 0xab
	s_bfe_u32 s1, s1, 0x70009
	s_mul_i32 s1, s1, 3
	s_sub_i32 s0, s0, s1
	s_and_b32 s10, s0, 0xff
	s_add_i32 s0, s44, 0xfffe
	s_and_b32 s1, s0, 0xff
	s_mulk_i32 s1, 0xab
	s_bfe_u32 s1, s1, 0x70009
	v_or_b32_e32 v64, v176, v177
	s_mul_i32 s1, s1, 3
	v_or3_b32 v64, v64, v178, v179
	s_sub_i32 s0, s0, s1
	v_add_u32_e32 v112, 0, v64
	s_and_b32 s0, s0, 0xff
	s_lshl_b32 s1, s10, 13
	s_add_i32 s45, s1, 0
	v_add_u32_e32 v68, s45, v171
	ds_read_b128 v[64:67], v68 offset:49152
	ds_read_b128 v[68:71], v68 offset:53248
	v_add_u32_e32 v113, s45, v175
	v_exp_f32_e32 v118, v129
	v_exp_f32_e32 v119, v126
	s_waitcnt lgkmcnt(1)
	v_mfma_f32_32x32x16_bf16 v[80:95], v[64:67], v[108:111], v[236:251]
	v_exp_f32_e32 v120, v127
	v_exp_f32_e32 v121, v124
	v_exp_f32_e32 v122, v125
	s_waitcnt lgkmcnt(0)
	v_mfma_f32_32x32x16_bf16 v[64:79], v[68:71], v[108:111], v[236:251]
	ds_read_b128 v[108:111], v113 offset:49152
	ds_read_b128 v[114:117], v113 offset:53248
	v_exp_f32_e32 v113, v132
	s_waitcnt lgkmcnt(1)
	v_mfma_f32_32x32x16_bf16 v[80:95], v[108:111], v[104:107], v[80:95]
	v_add_u32_e32 v108, s45, v174
	s_waitcnt lgkmcnt(0)
	v_mfma_f32_32x32x16_bf16 v[64:79], v[114:117], v[104:107], v[64:79]
	ds_read_b128 v[104:107], v108 offset:49152
	ds_read_b128 v[108:111], v108 offset:53248
	v_exp_f32_e32 v114, v133
	v_exp_f32_e32 v115, v130
	v_exp_f32_e32 v116, v131
	v_exp_f32_e32 v117, v128
	s_waitcnt lgkmcnt(1)
	v_mfma_f32_32x32x16_bf16 v[80:95], v[104:107], v[100:103], v[80:95]
	v_add_u32_e32 v104, s45, v173
	s_waitcnt lgkmcnt(0)
; #define SBAR() __builtin_amdgcn_sched_barrier(0)
; #define RESC(a) do { if (__any((a) < 1.f)) { if (hi == 0) al_l[r32] = (a); asm volatile("s_waitcnt lgkmcnt(0)" ::: "memory"); \
;     for (int d = 0; d < 4; ++d) for (int r = 0; r < 16; ++r) o[d][r] *= al_l[crow(r, hi)]; } } while (0)
; DEV void partialSM(f32x16& p0, f32x16& p1, float& m_reg, float& mn, float& alpha) {
;   constexpr float C = AT_SCALE * 1.4426950408889634f;
;   float pmax = p0[0];
; #pragma unroll
;   for (int r = 1; r < 16; ++r) pmax = fmaxf(pmax, p0[r]);
; #pragma unroll
;   for (int r = 0; r < 16; ++r) pmax = fmaxf(pmax, p1[r]);
;   { auto rr = __builtin_amdgcn_permlane32_swap(__float_as_uint(pmax), __float_as_uint(pmax), false, false);
;     pmax = fmaxf(__uint_as_float(rr[0]), __uint_as_float(rr[1])); }
;   if (__builtin_expect(__all(pmax - m_reg <= AT_THR / AT_SCALE), 1)) { mn = m_reg; alpha = 1.f; }
;   else { mn = fmaxf(m_reg, pmax); alpha = __builtin_amdgcn_exp2f((m_reg - mn) * C); m_reg = mn; }
;   float mnC = -mn * C;
; #pragma unroll
;   for (int r = 0; r < 16; ++r) p0[r] = fmaf(p0[r], C, mnC);
; #pragma unroll
;   for (int r = 0; r < 16; ++r) p1[r] = fmaf(p1[r], C, mnC);
; #pragma unroll
;   for (int r = 0; r < 16; ++r) p0[r] = __builtin_amdgcn_exp2f(p0[r]);
; }
; DEV void finishSM(f32x16& p0, f32x16& p1, float alpha, float& l_reg, bf16x8& pa0, bf16x8& pa1, bf16x8& pa2, bf16x8& pa3) {
; #pragma unroll
;   for (int r = 0; r < 16; ++r) p1[r] = __builtin_amdgcn_exp2f(p1[r]);
;   float ps = 0;
; #pragma unroll
;   for (int r = 0; r < 16; ++r) ps += p0[r];
; #pragma unroll
;   for (int r = 0; r < 16; ++r) ps += p1[r];
;   { auto rr = __builtin_amdgcn_permlane32_swap(__float_as_uint(ps), __float_as_uint(ps), false, false);
;     ps = __uint_as_float(rr[0]) + __uint_as_float(rr[1]); }
;   l_reg = l_reg * alpha + ps;
;     ...
;   PK4(p0, 0, pa0); PK4(p0, 8, pa1); PK4(p1, 0, pa2); PK4(p1, 8, pa3);
;     ...
; }
; DEV void attn_pass(const u16* __restrict__ Qb, const u16* __restrict__ Kh, const u16* __restrict__ Vh, int seq, f32x16* o, float* rli) {
;     ...
;   { const int bl = (NT - 1) % 3, bp = (NT - 2) % 3;
;     SBAR(); qkt(pB0, pB1, K_lds + bl * AT_SHM_K, qr, r32, hi);
;     finishSM(pA0, pA1, alA, l_reg, pa0, pa1, pa2, pa3); SBAR();
;     pv_d0(o, vb0 + bp * AT_SHM_V, pa0, pa1, pa2, pa3); partialSM(pB0, pB1, m_reg, mnB, alB);
;     RESC(alB);
	v_mfma_f32_32x32x16_bf16 v[64:79], v[108:111], v[100:103], v[64:79]
	ds_read_b128 v[100:103], v104 offset:49152
	ds_read_b128 v[104:107], v104 offset:53248
	v_exp_f32_e32 v108, v136
	v_exp_f32_e32 v109, v137
	v_exp_f32_e32 v110, v134
	v_exp_f32_e32 v111, v135
	s_waitcnt lgkmcnt(1)
	v_mfma_f32_32x32x16_bf16 v[80:95], v[100:103], v[96:99], v[80:95]
	v_cvt_pk_bf16_f32 v100, v158, v214
	v_cvt_pk_bf16_f32 v101, v159, v215
	v_cvt_pk_bf16_f32 v102, v142, v146
	v_cvt_pk_bf16_f32 v103, v143, v147
	s_waitcnt lgkmcnt(0)
	v_mfma_f32_32x32x16_bf16 v[64:79], v[104:107], v[96:99], v[64:79]
	v_add_f32_e32 v96, v160, v150
	v_add_f32_e32 v96, v151, v96
	v_add_f32_e32 v96, v161, v96
	v_add_f32_e32 v96, v158, v96
	v_add_f32_e32 v96, v214, v96
	v_add_f32_e32 v96, v159, v96
	v_add_f32_e32 v96, v215, v96
	v_add_f32_e32 v96, v142, v96
	v_add_f32_e32 v96, v146, v96
	v_add_f32_e32 v96, v143, v96
	v_add_f32_e32 v96, v147, v96
	v_exp_f32_e32 v106, v138
	v_add_f32_e32 v96, v144, v96
	v_exp_f32_e32 v107, v139
	v_add_f32_e32 v96, v148, v96
	v_add_f32_e32 v96, v145, v96
	v_add_f32_e32 v96, v149, v96
	v_add_f32_e32 v96, v106, v96
	v_add_f32_e32 v96, v107, v96
	v_add_f32_e32 v96, v108, v96
	v_add_f32_e32 v96, v109, v96
	v_add_f32_e32 v96, v110, v96
	v_add_f32_e32 v96, v111, v96
	v_add_f32_e32 v96, v113, v96
	v_add_f32_e32 v96, v114, v96
	v_add_f32_e32 v96, v115, v96
	v_add_f32_e32 v96, v116, v96
	v_add_f32_e32 v96, v117, v96
	v_add_f32_e32 v96, v118, v96
	v_add_f32_e32 v96, v119, v96
	v_add_f32_e32 v96, v120, v96
	v_add_f32_e32 v96, v121, v96
	v_add_f32_e32 v96, v122, v96
	v_mov_b32_e32 v97, v96
	v_cvt_pk_bf16_f32 v98, v150, v160
	v_cvt_pk_bf16_f32 v99, v151, v161
	s_nop 1
	v_permlane32_swap_b32_e32 v96, v97
	v_permlane32_swap_b32_e32 v98, v100
	v_permlane32_swap_b32_e32 v99, v101
	v_cvt_pk_bf16_f32 v104, v144, v148
	v_cvt_pk_bf16_f32 v105, v145, v149
	v_cvt_pk_bf16_f32 v106, v106, v107
	v_cvt_pk_bf16_f32 v107, v108, v109
	v_cvt_pk_bf16_f32 v108, v110, v111
	v_cvt_pk_bf16_f32 v109, v113, v114
	v_cvt_pk_bf16_f32 v114, v115, v116
	v_cvt_pk_bf16_f32 v115, v117, v118
	v_cvt_pk_bf16_f32 v116, v119, v120
	v_cvt_pk_bf16_f32 v117, v121, v122
	s_nop 0
	v_permlane32_swap_b32_e32 v102, v104
	v_permlane32_swap_b32_e32 v103, v105
	v_permlane32_swap_b32_e32 v106, v108
	v_permlane32_swap_b32_e32 v107, v109
	v_permlane32_swap_b32_e32 v114, v116
	v_permlane32_swap_b32_e32 v115, v117
	s_lshl_b32 s50, s0, 14
	v_add_u32_e32 v110, s50, v112
	ds_read_b64_tr_b16 v[118:119], v110 offset:0
	ds_read_b64_tr_b16 v[120:121], v110 offset:0x800
	ds_read_b64_tr_b16 v[122:123], v110 offset:0x1000
	ds_read_b64_tr_b16 v[124:125], v110 offset:0x1800
	ds_read_b64_tr_b16 v[126:127], v110 offset:0x2000
	ds_read_b64_tr_b16 v[128:129], v110 offset:0x2800
	ds_read_b64_tr_b16 v[130:131], v110 offset:0x3000
	ds_read_b64_tr_b16 v[132:133], v110 offset:0x3800
	s_waitcnt lgkmcnt(0)
	s_nop 0
	v_mfma_f32_32x32x16_bf16 v[0:15], v[98:101], v[118:121], v[0:15]
	ds_read_b64_tr_b16 v[118:119], v110 offset:0x200
	ds_read_b64_tr_b16 v[120:121], v110 offset:0xa00
	v_mfma_f32_32x32x16_bf16 v[0:15], v[102:105], v[122:125], v[0:15]
	ds_read_b64_tr_b16 v[122:123], v110 offset:0x1200
	ds_read_b64_tr_b16 v[124:125], v110 offset:0x1a00
	v_mfma_f32_32x32x16_bf16 v[0:15], v[106:109], v[126:129], v[0:15]
	ds_read_b64_tr_b16 v[126:127], v110 offset:0x2200
	ds_read_b64_tr_b16 v[128:129], v110 offset:0x2a00
	v_mfma_f32_32x32x16_bf16 v[0:15], v[114:117], v[130:133], v[0:15]
	ds_read_b64_tr_b16 v[130:131], v110 offset:0x3200
	ds_read_b64_tr_b16 v[132:133], v110 offset:0x3a00
	s_waitcnt lgkmcnt(0)
	v_mfma_f32_32x32x16_bf16 v[48:63], v[98:101], v[118:121], v[48:63]
	ds_read_b64_tr_b16 v[118:119], v110 offset:0x400
	ds_read_b64_tr_b16 v[120:121], v110 offset:0xc00
	v_mfma_f32_32x32x16_bf16 v[48:63], v[102:105], v[122:125], v[48:63]
	ds_read_b64_tr_b16 v[122:123], v110 offset:0x1400
	ds_read_b64_tr_b16 v[124:125], v110 offset:0x1c00
	v_mfma_f32_32x32x16_bf16 v[48:63], v[106:109], v[126:129], v[48:63]
	ds_read_b64_tr_b16 v[126:127], v110 offset:0x2400
	ds_read_b64_tr_b16 v[128:129], v110 offset:0x2c00
	v_mfma_f32_32x32x16_bf16 v[48:63], v[114:117], v[130:133], v[48:63]
	ds_read_b64_tr_b16 v[130:131], v110 offset:0x3400
	ds_read_b64_tr_b16 v[132:133], v110 offset:0x3c00
	s_waitcnt lgkmcnt(0)
	v_mfma_f32_32x32x16_bf16 v[32:47], v[98:101], v[118:121], v[32:47]
	ds_read_b64_tr_b16 v[118:119], v110 offset:0x600
	ds_read_b64_tr_b16 v[120:121], v110 offset:0xe00
	v_mfma_f32_32x32x16_bf16 v[32:47], v[102:105], v[122:125], v[32:47]
	ds_read_b64_tr_b16 v[122:123], v110 offset:0x1600
	ds_read_b64_tr_b16 v[124:125], v110 offset:0x1e00
	v_mfma_f32_32x32x16_bf16 v[32:47], v[106:109], v[126:129], v[32:47]
	ds_read_b64_tr_b16 v[126:127], v110 offset:0x2600
	ds_read_b64_tr_b16 v[128:129], v110 offset:0x2e00
	v_mfma_f32_32x32x16_bf16 v[32:47], v[114:117], v[130:133], v[32:47]
	ds_read_b64_tr_b16 v[130:131], v110 offset:0x3600
	ds_read_b64_tr_b16 v[132:133], v110 offset:0x3e00
	s_waitcnt lgkmcnt(0)
	v_mfma_f32_32x32x16_bf16 v[16:31], v[98:101], v[118:121], v[16:31]
	v_max_f32_e32 v98, v81, v81
	v_max_f32_e32 v99, v80, v80
	v_max_f32_e32 v98, v99, v98
	v_max3_f32 v98, v98, v82, v83
	v_max3_f32 v98, v98, v84, v85
	v_max3_f32 v98, v98, v86, v87
	v_max3_f32 v98, v98, v88, v89
	v_max3_f32 v98, v98, v90, v91
	v_max3_f32 v98, v98, v92, v93
	v_mfma_f32_32x32x16_bf16 v[16:31], v[102:105], v[122:125], v[16:31]
	v_max3_f32 v98, v98, v94, v95
	v_max3_f32 v98, v98, v64, v65
	v_max3_f32 v98, v98, v66, v67
	v_max3_f32 v98, v98, v68, v69
	v_max3_f32 v98, v98, v70, v71
	v_max3_f32 v98, v98, v72, v73
	v_max3_f32 v98, v98, v74, v75
	v_max3_f32 v98, v98, v76, v77
	v_mfma_f32_32x32x16_bf16 v[16:31], v[106:109], v[126:129], v[16:31]
	v_max3_f32 v98, v98, v78, v79
	v_mov_b32_e32 v99, v98
	s_nop 1
	v_permlane32_swap_b32_e32 v98, v99
	v_max_f32_e32 v99, v99, v99
	v_max_f32_e32 v98, v98, v98
	v_max_f32_e32 v98, v98, v99
	v_sub_f32_e32 v99, v98, v140
	v_cmp_ge_f32_e32 vcc, s18, v99
	v_max_f32_e32 v99, v140, v140
	v_max_f32_e32 v99, v99, v98
	v_mfma_f32_32x32x16_bf16 v[16:31], v[114:117], v[130:133], v[16:31]
	v_sub_f32_e32 v98, v140, v99
	v_mul_f32_e32 v98, 0x3f800000, v98
	v_exp_f32_e32 v98, v98
	s_cmp_eq_u64 vcc, exec
	s_cselect_b64 s[0:1], -1, 0
	v_cndmask_b32_e64 v98, v98, 1.0, s[0:1]
	v_cmp_gt_f32_e32 vcc, 1.0, v98
	s_cbranch_vccz .LBB0_86
; #define SBAR() __builtin_amdgcn_sched_barrier(0)
; #define RESC(a) do { if (__any((a) < 1.f)) { if (hi == 0) al_l[r32] = (a); asm volatile("s_waitcnt lgkmcnt(0)" ::: "memory"); \
;     for (int d = 0; d < 4; ++d) for (int r = 0; r < 16; ++r) o[d][r] *= al_l[crow(r, hi)]; } } while (0)
; DEV void attn_pass(const u16* __restrict__ Qb, const u16* __restrict__ Kh, const u16* __restrict__ Vh, int seq, f32x16* o, float* rli) {
;     ...
;   { const int bl = (NT - 1) % 3, bp = (NT - 2) % 3;
;     SBAR(); qkt(pB0, pB1, K_lds + bl * AT_SHM_K, qr, r32, hi);
;     finishSM(pA0, pA1, alA, l_reg, pa0, pa1, pa2, pa3); SBAR();
;     pv_d0(o, vb0 + bp * AT_SHM_V, pa0, pa1, pa2, pa3); partialSM(pB0, pB1, m_reg, mnB, alB);
;     RESC(alB);
;     finishSM(pB0, pB1, alB, l_reg, pa0, pa1, pa2, pa3); SBAR();
	s_and_saveexec_b64 s[8:9], s[6:7]
	s_mov_b32 s66, 0x800000
	ds_write_b32 v169, v98 offset:128
	s_or_b64 exec, exec, s[8:9]
	s_waitcnt lgkmcnt(0)
	v_add_u32_e32 v113, v168, v162
	ds_read_b128 v[100:103], v113 offset:224
	ds_read_b128 v[104:107], v113 offset:192
	ds_read_b128 v[108:111], v113 offset:160
	ds_read_b128 v[114:117], v113 offset:128
	s_waitcnt lgkmcnt(3)
	v_pk_mul_f32 v[12:13], v[12:13], v[100:101]
	s_waitcnt lgkmcnt(2)
	v_pk_mul_f32 v[8:9], v[8:9], v[104:105]
	s_waitcnt lgkmcnt(1)
	v_pk_mul_f32 v[4:5], v[4:5], v[108:109]
	v_pk_mul_f32 v[14:15], v[14:15], v[102:103]
	v_pk_mul_f32 v[10:11], v[10:11], v[106:107]
	v_pk_mul_f32 v[6:7], v[6:7], v[110:111]
	s_waitcnt lgkmcnt(0)
	v_pk_mul_f32 v[2:3], v[2:3], v[116:117]
	v_pk_mul_f32 v[0:1], v[0:1], v[114:115]
	v_pk_mul_f32 v[60:61], v[60:61], v[100:101]
	v_pk_mul_f32 v[56:57], v[56:57], v[104:105]
	v_pk_mul_f32 v[52:53], v[52:53], v[108:109]
	v_pk_mul_f32 v[62:63], v[62:63], v[102:103]
	v_pk_mul_f32 v[58:59], v[58:59], v[106:107]
	v_pk_mul_f32 v[54:55], v[54:55], v[110:111]
	v_pk_mul_f32 v[50:51], v[50:51], v[116:117]
	v_pk_mul_f32 v[48:49], v[48:49], v[114:115]
	v_pk_mul_f32 v[44:45], v[44:45], v[100:101]
	v_pk_mul_f32 v[40:41], v[40:41], v[104:105]
	v_pk_mul_f32 v[36:37], v[36:37], v[108:109]
	v_pk_mul_f32 v[46:47], v[46:47], v[102:103]
	v_pk_mul_f32 v[42:43], v[42:43], v[106:107]
	v_pk_mul_f32 v[38:39], v[38:39], v[110:111]
	v_pk_mul_f32 v[34:35], v[34:35], v[116:117]
	v_pk_mul_f32 v[32:33], v[32:33], v[114:115]
	v_pk_mul_f32 v[28:29], v[28:29], v[100:101]
	v_pk_mul_f32 v[24:25], v[24:25], v[104:105]
	v_pk_mul_f32 v[20:21], v[20:21], v[108:109]
	v_pk_mul_f32 v[30:31], v[30:31], v[102:103]
	v_pk_mul_f32 v[26:27], v[26:27], v[106:107]
	v_pk_mul_f32 v[22:23], v[22:23], v[110:111]
	v_pk_mul_f32 v[18:19], v[18:19], v[116:117]
	v_pk_mul_f32 v[16:17], v[16:17], v[114:115]
	s_branch .LBB0_87

; DEV void finishSM(f32x16& p0, f32x16& p1, float alpha, float& l_reg, bf16x8& pa0, bf16x8& pa1, bf16x8& pa2, bf16x8& pa3) {
; #pragma unroll
;   for (int r = 0; r < 16; ++r) p1[r] = __builtin_amdgcn_exp2f(p1[r]);
;   float ps = 0;
; #pragma unroll
;   for (int r = 0; r < 16; ++r) ps += p0[r];
; #pragma unroll
;   for (int r = 0; r < 16; ++r) ps += p1[r];
;   { auto rr = __builtin_amdgcn_permlane32_swap(__float_as_uint(ps), __float_as_uint(ps), false, false);
;     ps = __uint_as_float(rr[0]) + __uint_as_float(rr[1]); }
;   l_reg = l_reg * alpha + ps;
;     ...
;   PK4(p0, 0, pa0); PK4(p0, 8, pa1); PK4(p1, 0, pa2); PK4(p1, 8, pa3);
;     ...
; }
; DEV void qkt(f32x16& p0, f32x16& p1, const char* Ks, const bf16x8* qr, int r32, int hi) {
;   p0 = f32x16{}; p1 = f32x16{};
; #pragma unroll
;   for (int d0 = 0; d0 < 4; ++d0) { int cb = (d0 * 16 + hi * 8) * 2;
;     bf16x8 b0 = *reinterpret_cast<const bf16x8*>(Ks + KSWZ64(r32, cb));
;     bf16x8 b1 = *reinterpret_cast<const bf16x8*>(Ks + KSWZ64(32 + r32, cb));
;     p0 = __builtin_amdgcn_mfma_f32_32x32x16_bf16(b0, qr[d0], p0, 0, 0, 0);
;     p1 = __builtin_amdgcn_mfma_f32_32x32x16_bf16(b1, qr[d0], p1, 0, 0, 0); }
; }
; DEV int v_st(int k, int c) { const int kk = (k & ~0xC) | ((k & 4) << 1) | ((k & 8) >> 1); return ((kk >> 3) * 4 + (c >> 5)) * 512 + ((kk & 7) * 32 + (c & 31)) * 2; }
; DEV int v_rd_base(int lane) { return ((lane & 3) << 3) | (((lane >> 2) & 3) << 6) | (((lane >> 4) & 1) << 5) | (((lane >> 5) & 1) << 8); }
; template <int OFF> DEV s16x4 tr_read(int vb) {
;   s16x4 r; asm volatile("ds_read_b64_tr_b16 %0, %1 offset:%2" : "=&v"(r) : "v"(vb), "i"(OFF) : "memory"); return r;
; }
; template <int D0> DEV void pv_one(f32x16& od, int vb, bf16x8 pa0, bf16x8 pa1, bf16x8 pa2, bf16x8 pa3) {
;   const s16x4 l0 = tr_read<v_rd_off(D0, 0, 0)>(vb), h0 = tr_read<v_rd_off(D0, 0, 1)>(vb), l1 = tr_read<v_rd_off(D0, 1, 0)>(vb), h1 = tr_read<v_rd_off(D0, 1, 1)>(vb);
;   const s16x4 l2 = tr_read<v_rd_off(D0, 2, 0)>(vb), h2 = tr_read<v_rd_off(D0, 2, 1)>(vb), l3 = tr_read<v_rd_off(D0, 3, 0)>(vb), h3 = tr_read<v_rd_off(D0, 3, 1)>(vb);
;   asm volatile("s_waitcnt lgkmcnt(0)" ::: "memory"); SBAR();
;     ...
;   od = __builtin_amdgcn_mfma_f32_32x32x16_bf16(pa0, PK(l0, h0), od, 0, 0, 0);
;   od = __builtin_amdgcn_mfma_f32_32x32x16_bf16(pa1, PK(l1, h1), od, 0, 0, 0);
;   od = __builtin_amdgcn_mfma_f32_32x32x16_bf16(pa2, PK(l2, h2), od, 0, 0, 0);
.LBB0_87:
	v_cndmask_b32_e64 v99, v99, v140, s[0:1]
	v_mul_f32_e32 v99, 0xbf800000, v99
	v_fmamk_f32 v80, v80, 0x3f800000, v99
	v_fmamk_f32 v81, v81, 0x3f800000, v99
	v_fmamk_f32 v82, v82, 0x3f800000, v99
	v_fmamk_f32 v83, v83, 0x3f800000, v99
	v_fmamk_f32 v84, v84, 0x3f800000, v99
	v_fmamk_f32 v85, v85, 0x3f800000, v99
	v_fmamk_f32 v86, v86, 0x3f800000, v99
	v_fmamk_f32 v87, v87, 0x3f800000, v99
	v_fmamk_f32 v88, v88, 0x3f800000, v99
	v_fmamk_f32 v89, v89, 0x3f800000, v99
	v_fmamk_f32 v90, v90, 0x3f800000, v99
	v_fmamk_f32 v91, v91, 0x3f800000, v99
	v_fmamk_f32 v92, v92, 0x3f800000, v99
	v_fmamk_f32 v93, v93, 0x3f800000, v99
	v_fmamk_f32 v94, v94, 0x3f800000, v99
	v_fmamk_f32 v95, v95, 0x3f800000, v99
	v_fmamk_f32 v64, v64, 0x3f800000, v99
	v_fmamk_f32 v65, v65, 0x3f800000, v99
	v_fmamk_f32 v66, v66, 0x3f800000, v99
	v_fmamk_f32 v67, v67, 0x3f800000, v99
	v_fmamk_f32 v68, v68, 0x3f800000, v99
	v_fmamk_f32 v69, v69, 0x3f800000, v99
	v_fmamk_f32 v70, v70, 0x3f800000, v99
	v_fmamk_f32 v71, v71, 0x3f800000, v99
	v_fmamk_f32 v72, v72, 0x3f800000, v99
	v_fmamk_f32 v73, v73, 0x3f800000, v99
	v_fmamk_f32 v74, v74, 0x3f800000, v99
	v_fmamk_f32 v75, v75, 0x3f800000, v99
	v_fmamk_f32 v76, v76, 0x3f800000, v99
	v_fmamk_f32 v77, v77, 0x3f800000, v99
	v_fmamk_f32 v78, v78, 0x3f800000, v99
	v_fmac_f32_e32 v99, 0x3f800000, v79
	v_exp_f32_e32 v79, v80
	v_exp_f32_e32 v80, v81
	v_exp_f32_e32 v81, v82
	v_exp_f32_e32 v82, v83
	v_exp_f32_e32 v83, v84
	v_exp_f32_e32 v84, v85
	v_exp_f32_e32 v85, v86
	v_exp_f32_e32 v86, v87
	v_exp_f32_e32 v87, v88
	v_exp_f32_e32 v88, v89
	v_exp_f32_e32 v89, v90
	v_exp_f32_e32 v90, v91
	v_exp_f32_e32 v91, v92
	v_exp_f32_e32 v92, v93
	v_exp_f32_e32 v93, v94
	v_exp_f32_e32 v94, v95
	v_exp_f32_e32 v95, v64
	v_add_f32_e32 v64, v80, v79
	v_add_f32_e32 v64, v81, v64
	v_add_f32_e32 v64, v82, v64
	v_add_f32_e32 v64, v83, v64
	v_add_f32_e32 v64, v84, v64
	v_add_f32_e32 v64, v85, v64
	v_add_f32_e32 v64, v86, v64
	v_add_f32_e32 v64, v87, v64
	v_add_f32_e32 v64, v88, v64
	v_add_f32_e32 v64, v89, v64
	v_add_f32_e32 v64, v90, v64
	v_add_f32_e32 v64, v91, v64
	v_exp_f32_e32 v100, v65
	v_add_f32_e32 v64, v92, v64
	v_exp_f32_e32 v101, v66
	v_add_f32_e32 v64, v93, v64
	v_exp_f32_e32 v102, v67
	v_add_f32_e32 v64, v94, v64
	v_exp_f32_e32 v103, v68
	v_add_f32_e32 v64, v95, v64
	v_exp_f32_e32 v104, v69
	v_add_f32_e32 v64, v100, v64
	v_exp_f32_e32 v105, v70
	v_add_f32_e32 v64, v101, v64
	v_exp_f32_e32 v106, v71
	v_add_f32_e32 v64, v102, v64
	v_exp_f32_e32 v107, v72
	v_add_f32_e32 v64, v103, v64
	v_exp_f32_e32 v108, v73
	v_add_f32_e32 v64, v104, v64
	v_exp_f32_e32 v109, v74
	v_add_f32_e32 v64, v105, v64
	v_exp_f32_e32 v110, v75
	v_add_f32_e32 v64, v106, v64
	v_exp_f32_e32 v111, v76
	v_add_f32_e32 v64, v107, v64
	v_exp_f32_e32 v113, v77
	v_add_f32_e32 v64, v108, v64
	v_exp_f32_e32 v114, v78
	v_add_f32_e32 v64, v109, v64
	v_exp_f32_e32 v99, v99
	v_add_f32_e32 v64, v110, v64
	v_add_f32_e32 v64, v111, v64
	v_add_f32_e32 v64, v113, v64
	v_add_f32_e32 v64, v114, v64
	v_add_f32_e32 v64, v99, v64
	v_mov_b32_e32 v65, v64
	s_nop 1
	v_permlane32_swap_b32_e32 v64, v65
	v_cvt_pk_bf16_f32 v66, v79, v80
	v_cvt_pk_bf16_f32 v67, v81, v82
	v_cvt_pk_bf16_f32 v68, v83, v84
	v_cvt_pk_bf16_f32 v69, v85, v86
	v_cvt_pk_bf16_f32 v70, v87, v88
	v_cvt_pk_bf16_f32 v71, v89, v90
	v_cvt_pk_bf16_f32 v72, v91, v92
	v_cvt_pk_bf16_f32 v73, v93, v94
	v_cvt_pk_bf16_f32 v74, v95, v100
	v_cvt_pk_bf16_f32 v75, v101, v102
	v_cvt_pk_bf16_f32 v76, v103, v104
	v_cvt_pk_bf16_f32 v77, v105, v106
	v_cvt_pk_bf16_f32 v78, v107, v108
	v_cvt_pk_bf16_f32 v79, v109, v110
	v_cvt_pk_bf16_f32 v80, v111, v113
	v_cvt_pk_bf16_f32 v81, v114, v99
	s_nop 0
	v_permlane32_swap_b32_e32 v66, v68
	v_permlane32_swap_b32_e32 v67, v69
	v_permlane32_swap_b32_e32 v70, v72
	v_permlane32_swap_b32_e32 v71, v73
	v_permlane32_swap_b32_e32 v74, v76
	v_permlane32_swap_b32_e32 v75, v77
	v_permlane32_swap_b32_e32 v78, v80
	v_permlane32_swap_b32_e32 v79, v81
	s_lshl_b32 s51, s10, 14
	v_add_u32_e32 v94, s51, v112
	ds_read_b64_tr_b16 v[82:83], v94 offset:0
	ds_read_b64_tr_b16 v[84:85], v94 offset:0x800
	ds_read_b64_tr_b16 v[86:87], v94 offset:0x1000
	ds_read_b64_tr_b16 v[88:89], v94 offset:0x1800
	ds_read_b64_tr_b16 v[90:91], v94 offset:0x2000
	ds_read_b64_tr_b16 v[92:93], v94 offset:0x2800
	ds_read_b64_tr_b16 v[100:101], v94 offset:0x3000
	ds_read_b64_tr_b16 v[102:103], v94 offset:0x3800
	s_waitcnt lgkmcnt(0)
	s_nop 0
	v_mfma_f32_32x32x16_bf16 v[0:15], v[66:69], v[82:85], v[0:15]
	ds_read_b64_tr_b16 v[82:83], v94 offset:0x200
	ds_read_b64_tr_b16 v[84:85], v94 offset:0xa00
	v_mfma_f32_32x32x16_bf16 v[0:15], v[70:73], v[86:89], v[0:15]
	ds_read_b64_tr_b16 v[86:87], v94 offset:0x1200
	ds_read_b64_tr_b16 v[88:89], v94 offset:0x1a00
	v_mfma_f32_32x32x16_bf16 v[0:15], v[74:77], v[90:93], v[0:15]
	ds_read_b64_tr_b16 v[90:91], v94 offset:0x2200
	ds_read_b64_tr_b16 v[92:93], v94 offset:0x2a00
	v_mfma_f32_32x32x16_bf16 v[0:15], v[78:81], v[100:103], v[0:15]
	ds_read_b64_tr_b16 v[100:101], v94 offset:0x3200
	ds_read_b64_tr_b16 v[102:103], v94 offset:0x3a00
	s_waitcnt lgkmcnt(0)
	v_mfma_f32_32x32x16_bf16 v[48:63], v[66:69], v[82:85], v[48:63]
	ds_read_b64_tr_b16 v[82:83], v94 offset:0x400
	ds_read_b64_tr_b16 v[84:85], v94 offset:0xc00
	v_mfma_f32_32x32x16_bf16 v[48:63], v[70:73], v[86:89], v[48:63]
	ds_read_b64_tr_b16 v[86:87], v94 offset:0x1400
	ds_read_b64_tr_b16 v[88:89], v94 offset:0x1c00
	v_mfma_f32_32x32x16_bf16 v[48:63], v[74:77], v[90:93], v[48:63]
	ds_read_b64_tr_b16 v[90:91], v94 offset:0x2400
	ds_read_b64_tr_b16 v[92:93], v94 offset:0x2c00
	v_mfma_f32_32x32x16_bf16 v[48:63], v[78:81], v[100:103], v[48:63]
	ds_read_b64_tr_b16 v[100:101], v94 offset:0x3400
	ds_read_b64_tr_b16 v[102:103], v94 offset:0x3c00
	s_waitcnt lgkmcnt(0)
; DEV int crow(int r, int hi) { return (r & 3) + 8 * (r >> 2) + 4 * hi; }
; DEV void attn_pass(const u16* __restrict__ Qb, const u16* __restrict__ Kh, const u16* __restrict__ Vh, int seq, f32x16* o, float* rli) {
;     ...
;   if (hi == 0) li_l[r32] = l_reg; asm volatile("s_waitcnt lgkmcnt(0)" ::: "memory");
; #pragma unroll
;   for (int r = 0; r < 16; ++r) rli[r] = __builtin_amdgcn_rcpf(li_l[crow(r, hi)]);
; DEV void attn_item(const Params& p, int l, int b, int h, int qb, int dry) {
;     ...
;     int lz = 0; asm volatile("" : "+v"(lz));
;     float* sp = scr + (wid * 64) * 64 + lane + lz;
; #pragma unroll
;     for (int d0 = 0; d0 < 4; ++d0)
; #pragma unroll
;       for (int r = 0; r < 16; ++r) sp[(d0 * 16 + r) * 64] = o[d0][r] * rli[r];
	v_mfma_f32_32x32x16_bf16 v[32:47], v[66:69], v[82:85], v[32:47]
	ds_read_b64_tr_b16 v[82:83], v94 offset:0x600
	ds_read_b64_tr_b16 v[84:85], v94 offset:0xe00
	v_mfma_f32_32x32x16_bf16 v[32:47], v[70:73], v[86:89], v[32:47]
	ds_read_b64_tr_b16 v[86:87], v94 offset:0x1600
	ds_read_b64_tr_b16 v[88:89], v94 offset:0x1e00
	v_mfma_f32_32x32x16_bf16 v[32:47], v[74:77], v[90:93], v[32:47]
	ds_read_b64_tr_b16 v[90:91], v94 offset:0x2600
	ds_read_b64_tr_b16 v[92:93], v94 offset:0x2e00
	v_mfma_f32_32x32x16_bf16 v[32:47], v[78:81], v[100:103], v[32:47]
	ds_read_b64_tr_b16 v[100:101], v94 offset:0x3600
	ds_read_b64_tr_b16 v[102:103], v94 offset:0x3e00
	s_waitcnt lgkmcnt(0)
	v_mfma_f32_32x32x16_bf16 v[16:31], v[66:69], v[82:85], v[16:31]
	v_mfma_f32_32x32x16_bf16 v[16:31], v[70:73], v[86:89], v[16:31]
	v_mfma_f32_32x32x16_bf16 v[16:31], v[74:77], v[90:93], v[16:31]
	v_mfma_f32_32x32x16_bf16 v[16:31], v[78:81], v[100:103], v[16:31]
	s_and_saveexec_b64 s[0:1], s[6:7]
	v_add_f32_e32 v66, v96, v97
	v_fmac_f32_e32 v66, v170, v141
	v_add_f32_e32 v64, v64, v65
	v_fmac_f32_e32 v64, v66, v98
	ds_write_b32 v169, v64
	s_or_b64 exec, exec, s[0:1]
	s_waitcnt lgkmcnt(0)
	v_add_u32_e32 v72, v168, v162
	ds_read_b128 v[64:67], v72
	ds_read_b128 v[68:71], v72 offset:32
	v_and_b32_e32 v73, 63, v172
	v_lshlrev_b32_e32 v162, 2, v73
	s_movk_i32 s8, 0x2000
	s_waitcnt lgkmcnt(1)
	v_rcp_f32_e32 v74, v64
	v_rcp_f32_e32 v75, v65
	v_rcp_f32_e32 v76, v66
	v_rcp_f32_e32 v77, v67
	ds_read_b128 v[64:67], v72 offset:64
	s_waitcnt lgkmcnt(1)
	v_rcp_f32_e32 v78, v68
	v_rcp_f32_e32 v79, v69
	v_rcp_f32_e32 v80, v70
	v_rcp_f32_e32 v81, v71
	ds_read_b128 v[68:71], v72 offset:96
	s_waitcnt lgkmcnt(1)
	v_rcp_f32_e32 v82, v65
	v_lshlrev_b32_e32 v65, 6, v172
	v_rcp_f32_e32 v83, v66
	v_and_b32_e32 v66, 0xfffff000, v65
	v_rcp_f32_e32 v84, v67
	v_ashrrev_i32_e32 v67, 31, v66
	v_rcp_f32_e32 v72, v64
	v_mov_b32_e32 v64, v163
	v_lshl_add_u64 v[66:67], v[66:67], 2, s[56:57]
	s_waitcnt lgkmcnt(0)
	s_barrier
	v_lshl_add_u64 v[154:155], v[66:67], 0, v[162:163]
	v_ashrrev_i32_e32 v65, 31, v64
	v_lshl_add_u64 v[64:65], v[64:65], 2, v[154:155]
	v_mul_f32_e32 v0, v0, v74
	global_store_dword v[64:65], v0, off
	v_mul_f32_e32 v0, v1, v75
	global_store_dword v[64:65], v0, off offset:256
	v_mul_f32_e32 v0, v2, v76
	global_store_dword v[64:65], v0, off offset:512
	v_mul_f32_e32 v0, v3, v77
	global_store_dword v[64:65], v0, off offset:768
	v_mul_f32_e32 v0, v4, v78
	global_store_dword v[64:65], v0, off offset:1024
	v_mul_f32_e32 v0, v5, v79
	global_store_dword v[64:65], v0, off offset:1280
	v_mul_f32_e32 v0, v6, v80
	global_store_dword v[64:65], v0, off offset:1536
	v_mul_f32_e32 v0, v7, v81
	v_rcp_f32_e32 v68, v68
	global_store_dword v[64:65], v0, off offset:1792
	v_mul_f32_e32 v0, v8, v72
	v_rcp_f32_e32 v69, v69
	global_store_dword v[64:65], v0, off offset:2048
	v_mul_f32_e32 v0, v9, v82
	v_rcp_f32_e32 v70, v70
	global_store_dword v[64:65], v0, off offset:2304
	v_mul_f32_e32 v0, v10, v83
	v_rcp_f32_e32 v71, v71
	global_store_dword v[64:65], v0, off offset:2560
	v_mul_f32_e32 v0, v11, v84
	global_store_dword v[64:65], v0, off offset:2816
	v_mul_f32_e32 v0, v12, v68
	global_store_dword v[64:65], v0, off offset:3072
	v_mul_f32_e32 v0, v13, v69
	global_store_dword v[64:65], v0, off offset:3328
	v_mul_f32_e32 v0, v14, v70
	global_store_dword v[64:65], v0, off offset:3584
	v_mul_f32_e32 v0, v15, v71
	global_store_dword v[64:65], v0, off offset:3840
	v_add_co_u32_e32 v0, vcc, s87, v64
	v_mul_f32_e32 v4, v48, v74
	s_nop 0
	v_addc_co_u32_e32 v1, vcc, 0, v65, vcc
	v_add_co_u32_e32 v2, vcc, s8, v64
	s_or_b32 s6, s47, 1
	s_nop 0
	v_addc_co_u32_e32 v3, vcc, 0, v65, vcc
	global_store_dword v[2:3], v4, off offset:-4096
	v_mul_f32_e32 v4, v49, v75
	global_store_dword v[0:1], v4, off offset:256
	v_mul_f32_e32 v4, v50, v76
	global_store_dword v[0:1], v4, off offset:512
	v_mul_f32_e32 v4, v51, v77
	global_store_dword v[0:1], v4, off offset:768
	v_mul_f32_e32 v4, v52, v78
	global_store_dword v[0:1], v4, off offset:1024
	v_mul_f32_e32 v4, v53, v79
	global_store_dword v[0:1], v4, off offset:1280
	v_mul_f32_e32 v4, v54, v80
	global_store_dword v[0:1], v4, off offset:1536
	v_mul_f32_e32 v4, v55, v81
	global_store_dword v[0:1], v4, off offset:1792
	v_mul_f32_e32 v4, v56, v72
	global_store_dword v[0:1], v4, off offset:2048
	v_mul_f32_e32 v4, v57, v82
	global_store_dword v[0:1], v4, off offset:2304
	v_mul_f32_e32 v4, v58, v83
	global_store_dword v[0:1], v4, off offset:2560
	v_mul_f32_e32 v4, v59, v84
	global_store_dword v[0:1], v4, off offset:2816
	v_mul_f32_e32 v4, v60, v68
	global_store_dword v[0:1], v4, off offset:3072
	v_mul_f32_e32 v4, v61, v69
	global_store_dword v[0:1], v4, off offset:3328
	v_mul_f32_e32 v4, v62, v70
	global_store_dword v[0:1], v4, off offset:3584
	v_mul_f32_e32 v4, v63, v71
	global_store_dword v[0:1], v4, off offset:3840
	v_mul_f32_e32 v0, v32, v74
	global_store_dword v[2:3], v0, off
	v_mul_f32_e32 v0, v33, v75
	global_store_dword v[2:3], v0, off offset:256
	v_mul_f32_e32 v0, v34, v76
	global_store_dword v[2:3], v0, off offset:512
	v_mul_f32_e32 v0, v35, v77
	global_store_dword v[2:3], v0, off offset:768
	v_mul_f32_e32 v0, v36, v78
	global_store_dword v[2:3], v0, off offset:1024
	v_mul_f32_e32 v0, v37, v79
	global_store_dword v[2:3], v0, off offset:1280
	v_mul_f32_e32 v0, v38, v80
	global_store_dword v[2:3], v0, off offset:1536
	v_mul_f32_e32 v0, v39, v81
	global_store_dword v[2:3], v0, off offset:1792
	v_mul_f32_e32 v0, v40, v72
	global_store_dword v[2:3], v0, off offset:2048
	v_mul_f32_e32 v0, v41, v82
	global_store_dword v[2:3], v0, off offset:2304
	v_mul_f32_e32 v0, v42, v83
	global_store_dword v[2:3], v0, off offset:2560
; DEV int v_st(int k, int c) { const int kk = (k & ~0xC) | ((k & 4) << 1) | ((k & 8) >> 1); return ((kk >> 3) * 4 + (c >> 5)) * 512 + ((kk & 7) * 32 + (c & 31)) * 2; }
; DEV int v_rd_base(int lane) { return ((lane & 3) << 3) | (((lane >> 2) & 3) << 6) | (((lane >> 4) & 1) << 5) | (((lane >> 5) & 1) << 8); }
; #define SLOAD(i, k0) do { sr_[i].vs0 = *reinterpret_cast<const bf16x8*>(&Vh[(size_t)((k0) + sr) * 128 + sc]); sr_[i].vs1 = *reinterpret_cast<const bf16x8*>(&Vh[(size_t)((k0) + 32 + sr) * 128 + sc]); \
;     sr_[i].ks0 = *reinterpret_cast<const bf16x8*>(&Kh[(size_t)((k0) + kr) * 64 + kc]); } while (0)
; #define SWRITE(b, i) do { *(bf16x8*)(V_lds + (b) * AT_SHM_V + vst0) = sr_[i].vs0; *(bf16x8*)(V_lds + (b) * AT_SHM_V + vst1) = sr_[i].vs1; \
;     *(bf16x8*)(K_lds + (b) * AT_SHM_K + kst) = sr_[i].ks0; } while (0)
; DEV void attn_pass(const u16* __restrict__ Qb, const u16* __restrict__ Kh, const u16* __restrict__ Vh, int seq, f32x16* o, float* rli) {
;     ...
;   const u16* Qw = Qb + (size_t)(wid * 32 + r32) * 64 + hi * 8;
; #pragma unroll
;   for (int d0 = 0; d0 < 4; ++d0) qr[d0] = *reinterpret_cast<const bf16x8*>(Qw + d0 * 16);
;   const int sr = tid >> 4, sc = (tid & 15) * 8, vst0 = v_st(sr, sc), vst1 = v_st(32 + sr, sc);
;   const int kr = tid >> 3, kc = (tid & 7) * 8, kst = KSWZ64(kr, kc * 2);
;   const int vb0 = (int)(uintptr_t)(__attribute__((address_space(3))) char*)V_lds + v_rd_base(lane);
;   struct { bf16x8 vs0, vs1, ks0; } sr_[2];
;     ...
;   f32x16 pA0, pA1, pB0, pB1; float mnA, mnB, alA, alB; bf16x8 pa0, pa1, pa2, pa3; const int NT = seq / 64;
;   constexpr int SE = 0, SO = 1;
;   SLOAD(SE, 0); SLOAD(SO, 64);
;   asm volatile("s_waitcnt vmcnt(3)" ::: "memory"); SWRITE(0, SE); __syncthreads();
; DEV void attn_item(const Params& p, int l, int b, int h, int qb, int dry) {
;     ...
;     for (int d0 = 0; d0 < 4; ++d0)
; #pragma unroll
;       for (int r = 0; r < 16; ++r) sp[(d0 * 16 + r) * 64] = o[d0][r] * rli[r];
;   }
;   {
;     const int s = b * 16 + h * 2 + 1;
;     attn_pass(AQ + ((size_t)s * UU + uq) * 64, AK + (size_t)s * UU * 64, Vh, seq, o, rli);
	v_mul_f32_e32 v0, v43, v84
	global_store_dword v[2:3], v0, off offset:2816
	v_mul_f32_e32 v0, v44, v68
	global_store_dword v[2:3], v0, off offset:3072
	v_mul_f32_e32 v0, v45, v69
	global_store_dword v[2:3], v0, off offset:3328
	v_mul_f32_e32 v0, v46, v70
	global_store_dword v[2:3], v0, off offset:3584
	v_mul_f32_e32 v0, v47, v71
	global_store_dword v[2:3], v0, off offset:3840
	v_add_co_u32_e32 v0, vcc, s80, v64
	v_mul_f32_e32 v2, v16, v74
	s_nop 0
	v_addc_co_u32_e32 v1, vcc, 0, v65, vcc
	global_store_dword v[0:1], v2, off
	v_mul_f32_e32 v2, v17, v75
	global_store_dword v[0:1], v2, off offset:256
	v_mul_f32_e32 v2, v18, v76
	global_store_dword v[0:1], v2, off offset:512
	v_mul_f32_e32 v2, v19, v77
	global_store_dword v[0:1], v2, off offset:768
	v_mul_f32_e32 v2, v20, v78
	global_store_dword v[0:1], v2, off offset:1024
	v_mul_f32_e32 v2, v21, v79
	global_store_dword v[0:1], v2, off offset:1280
	v_mul_f32_e32 v2, v22, v80
	global_store_dword v[0:1], v2, off offset:1536
	v_mul_f32_e32 v2, v23, v81
	global_store_dword v[0:1], v2, off offset:1792
	v_mul_f32_e32 v2, v24, v72
	global_store_dword v[0:1], v2, off offset:2048
	v_mul_f32_e32 v2, v25, v82
	global_store_dword v[0:1], v2, off offset:2304
	v_mul_f32_e32 v2, v26, v83
	global_store_dword v[0:1], v2, off offset:2560
	v_mul_f32_e32 v2, v27, v84
	global_store_dword v[0:1], v2, off offset:2816
	v_mul_f32_e32 v2, v28, v68
	global_store_dword v[0:1], v2, off offset:3072
	v_mul_f32_e32 v2, v29, v69
	global_store_dword v[0:1], v2, off offset:3328
	v_mul_f32_e32 v2, v30, v70
	s_mul_i32 s0, s6, 0x1100
	global_store_dword v[0:1], v2, off offset:3584
	v_mul_f32_e32 v2, v31, v71
	s_mul_hi_i32 s1, s6, 0x1100
	s_add_u32 s0, s0, s46
	v_mov_b32_e32 v70, v252
	global_store_dword v[0:1], v2, off offset:3840
	s_addc_u32 s1, s1, 0
	s_lshl_b64 s[0:1], s[0:1], 7
	v_ashrrev_i32_e32 v48, 4, v70
	v_lshlrev_b32_e32 v20, 3, v70
	v_ashrrev_i32_e32 v49, 31, v48
	s_add_u32 s0, s36, s0
	v_and_b32_e32 v2, 0x78, v20
	v_add_u32_e32 v12, 32, v48
	v_lshlrev_b64 v[50:51], 8, v[48:49]
	s_addc_u32 s1, s37, s1
	s_mul_hi_i32 s7, s6, 0x88000
	s_mul_i32 s6, s6, 0x88000
	v_ashrrev_i32_e32 v14, 3, v70
	v_lshl_add_u64 v[0:1], s[64:65], 0, v[50:51]
	v_lshlrev_b32_e32 v2, 1, v2
	v_mov_b32_e32 v3, v163
	v_ashrrev_i32_e32 v13, 31, v12
	s_add_u32 s6, s38, s6
	v_lshl_add_u64 v[66:67], v[0:1], 0, v[2:3]
	v_lshlrev_b64 v[0:1], 8, v[12:13]
	v_ashrrev_i32_e32 v15, 31, v14
	s_addc_u32 s7, s39, s7
	v_lshlrev_b32_e32 v71, 4, v70
	v_lshl_add_u64 v[0:1], s[64:65], 0, v[0:1]
	v_lshlrev_b64 v[52:53], 7, v[14:15]
	v_and_b32_e32 v16, 0x70, v71
	v_lshl_add_u64 v[4:5], v[0:1], 0, v[2:3]
	v_lshl_add_u64 v[8:9], s[6:7], 0, v[52:53]
	v_mov_b32_e32 v17, v163
	global_load_dwordx4 v[0:3], v[66:67], off
	s_nop 0
	global_load_dwordx4 v[4:7], v[4:5], off
	v_lshl_add_u64 v[68:69], v[8:9], 0, v[16:17]
	global_load_dwordx4 v[8:11], v[68:69], off
	v_ashrrev_i32_e32 v13, 1, v70
	v_bfi_b32 v18, s68, v13, v70
	v_ashrrev_i32_e32 v19, 31, v18
	v_lshlrev_b64 v[18:19], 7, v[18:19]
	v_lshrrev_b32_e32 v13, 1, v70
	v_lshl_add_u64 v[18:19], s[0:1], 0, v[18:19]
	v_and_b32_e32 v156, 16, v13
	v_mov_b32_e32 v157, v163
	v_lshl_add_u64 v[18:19], v[18:19], 0, v[156:157]
	global_load_dwordx4 v[108:111], v[18:19], off
	global_load_dwordx4 v[104:107], v[18:19], off offset:32
	global_load_dwordx4 v[100:103], v[18:19], off offset:64
	global_load_dwordx4 v[96:99], v[18:19], off offset:96
	v_and_b32_e32 v13, 0xfffff0, v48
	v_lshlrev_b32_e32 v15, 1, v48
	v_and_or_b32 v13, v15, 8, v13
	v_lshrrev_b32_e32 v13, 1, v13
	v_bfe_u32 v17, v20, 5, 2
	v_lshrrev_b32_e32 v15, 1, v48
	v_or_b32_e32 v13, v13, v17
	v_and_b32_e32 v73, 3, v48
	v_lshlrev_b32_e32 v72, 9, v13
	v_and_or_b32 v13, v15, 4, v73
	v_and_b32_e32 v15, 0xfffff0, v12
	v_lshlrev_b32_e32 v12, 1, v12
	v_and_or_b32 v12, v12, 8, v15
	v_lshrrev_b32_e32 v12, 1, v12
	v_or_b32_e32 v12, v12, v17
	v_lshlrev_b32_e32 v13, 6, v13
	v_and_b32_e32 v74, 48, v71
	v_lshlrev_b32_e32 v75, 9, v12
	v_or3_b32 v18, v72, v13, v74
	v_or3_b32 v17, v75, v13, v74
	v_lshlrev_b32_e32 v12, 7, v14
	v_and_b32_e32 v13, 0x70, v70
	v_bitop3_b32 v76, v16, v12, v13 bitop3:0xde
	v_add_co_u32_e32 v12, vcc, s75, v66
	s_movk_i32 s0, 0x6000
	s_nop 0
	v_addc_co_u32_e32 v13, vcc, 0, v67, vcc
	global_load_dwordx4 v[54:57], v[12:13], off
	v_add_co_u32_e32 v12, vcc, s0, v66
	v_and_b32_e32 v49, 31, v70
	s_nop 0
	v_addc_co_u32_e32 v13, vcc, 0, v67, vcc
	v_add_co_u32_e32 v14, vcc, s8, v68
	v_lshlrev_b32_e32 v80, 7, v49
	s_nop 0
	v_addc_co_u32_e32 v15, vcc, 0, v69, vcc
	global_load_dwordx4 v[58:61], v[12:13], off
	global_load_dwordx4 v[62:65], v[14:15], off
	v_and_b32_e32 v81, 0x70, v20
	v_add_u32_e32 v77, 0, v18
	v_add_u32_e32 v78, 0, v17
	v_bitop3_b32 v175, v156, v80, v81 bitop3:0xde
	s_waitcnt vmcnt(3)
	v_add_u32_e32 v79, 0, v76
	v_or_b32_e32 v83, 32, v156
	v_bitop3_b32 v178, v83, v80, v81 bitop3:0xde
	v_and_b32_e32 v82, 63, v70
	s_mov_b32 s0, 0xa000
	v_and_b32_e32 v180, 0xc0, v71
	v_or_b32_e32 v71, 64, v156
	v_bitop3_b32 v177, v71, v80, v81 bitop3:0xde
	v_or_b32_e32 v84, 0x60, v156
	v_bitop3_b32 v176, v84, v80, v81 bitop3:0xde
	s_mov_b32 s8, 0
	s_mov_b32 s9, s8
	s_mov_b32 s10, s8
	s_mov_b32 s11, s8
	s_mov_b32 s12, s8
	s_mov_b32 s13, s8
	s_mov_b32 s14, s8
	s_mov_b32 s15, s8
	s_mov_b32 s16, s8
	s_mov_b32 s17, s8
	s_waitcnt vmcnt(9)
	ds_write_b128 v77, v[0:3]
	s_waitcnt vmcnt(8)
	ds_write_b128 v78, v[4:7]
	v_add_u32_e32 v4, 0, v175
	v_and_b32_e32 v5, 0x3fffffc0, v70
	s_waitcnt vmcnt(7)
	ds_write_b128 v79, v[8:11] offset:49152
	s_waitcnt lgkmcnt(0)
	s_barrier
; #define SLOAD(i, k0) do { sr_[i].vs0 = *reinterpret_cast<const bf16x8*>(&Vh[(size_t)((k0) + sr) * 128 + sc]); sr_[i].vs1 = *reinterpret_cast<const bf16x8*>(&Vh[(size_t)((k0) + 32 + sr) * 128 + sc]); \
;     sr_[i].ks0 = *reinterpret_cast<const bf16x8*>(&Kh[(size_t)((k0) + kr) * 64 + kc]); } while (0)
; #define SWRITE(b, i) do { *(bf16x8*)(V_lds + (b) * AT_SHM_V + vst0) = sr_[i].vs0; *(bf16x8*)(V_lds + (b) * AT_SHM_V + vst1) = sr_[i].vs1; \
;     *(bf16x8*)(K_lds + (b) * AT_SHM_K + kst) = sr_[i].ks0; } while (0)
; #define SWAIT() asm volatile("s_waitcnt vmcnt(3)" ::: "memory")
; DEV void partialSM(f32x16& p0, f32x16& p1, float& m_reg, float& mn, float& alpha) {
;   constexpr float C = AT_SCALE * 1.4426950408889634f;
;   float pmax = p0[0];
; #pragma unroll
;   for (int r = 1; r < 16; ++r) pmax = fmaxf(pmax, p0[r]);
; #pragma unroll
;   for (int r = 0; r < 16; ++r) pmax = fmaxf(pmax, p1[r]);
;   { auto rr = __builtin_amdgcn_permlane32_swap(__float_as_uint(pmax), __float_as_uint(pmax), false, false);
;     pmax = fmaxf(__uint_as_float(rr[0]), __uint_as_float(rr[1])); }
;   if (__builtin_expect(__all(pmax - m_reg <= AT_THR / AT_SCALE), 1)) { mn = m_reg; alpha = 1.f; }
;   else { mn = fmaxf(m_reg, pmax); alpha = __builtin_amdgcn_exp2f((m_reg - mn) * C); m_reg = mn; }
;   float mnC = -mn * C;
; #pragma unroll
;   for (int r = 0; r < 16; ++r) p0[r] = fmaf(p0[r], C, mnC);
; #pragma unroll
;   for (int r = 0; r < 16; ++r) p1[r] = fmaf(p1[r], C, mnC);
; #pragma unroll
;   for (int r = 0; r < 16; ++r) p0[r] = __builtin_amdgcn_exp2f(p0[r]);
; }
; DEV void attn_pass(const u16* __restrict__ Qb, const u16* __restrict__ Kh, const u16* __restrict__ Vh, int seq, f32x16* o, float* rli) {
;     ...
;   SLOAD(SE, 0); SLOAD(SO, 64);
;   asm volatile("s_waitcnt vmcnt(3)" ::: "memory"); SWRITE(0, SE); __syncthreads();
;   if (2 < NT) SLOAD(SE, 2 * 64);
;   qkt(pA0, pA1, K_lds, qr, r32, hi); partialSM(pA0, pA1, m_reg, mnA, alA);
;   SWAIT(); SWRITE(1, SO); __syncthreads();
	ds_read_b128 v[0:3], v4 offset:49152
	v_lshl_add_u32 v157, v5, 2, s48
	ds_read_b128 v[4:7], v4 offset:53248
	v_add_u32_e32 v8, 0, v178
	s_waitcnt vmcnt(6) lgkmcnt(1)
	v_mfma_f32_32x32x16_bf16 v[16:31], v[0:3], v[108:111], 0
	ds_read_b128 v[0:3], v8 offset:49152
	s_mov_b32 s18, s8
	s_mov_b32 s19, s8
	s_mov_b32 s20, s8
	s_mov_b32 s21, s8
	s_mov_b32 s22, s8
	s_mov_b32 s23, s8
	s_waitcnt lgkmcnt(1)
	v_mfma_f32_32x32x16_bf16 v[32:47], v[4:7], v[108:111], 0
	v_lshlrev_b32_e32 v4, 3, v82
	v_lshlrev_b32_e32 v5, 1, v70
	v_and_b32_e32 v179, 24, v4
	v_and_b32_e32 v181, 32, v5
	v_and_b32_e32 v182, 0x100, v4
	ds_read_b128 v[4:7], v8 offset:53248
	v_add_co_u32_e32 v8, vcc, s75, v68
	s_waitcnt vmcnt(5) lgkmcnt(0)
	v_mfma_f32_32x32x16_bf16 v[32:47], v[4:7], v[104:107], v[32:47]
	v_addc_co_u32_e32 v9, vcc, 0, v69, vcc
	v_add_co_u32_e32 v10, vcc, s0, v66
	s_mov_b32 s0, 0x8000
	s_nop 0
	v_addc_co_u32_e32 v11, vcc, 0, v67, vcc
	v_add_co_u32_e32 v4, vcc, s0, v66
	v_add_u32_e32 v6, 0, v177
	s_nop 0
	v_addc_co_u32_e32 v5, vcc, 0, v67, vcc
	v_mfma_f32_32x32x16_bf16 v[16:31], v[0:3], v[104:107], v[16:31]
	ds_read_b128 v[0:3], v6 offset:49152
	global_load_dwordx4 v[120:123], v[8:9], off
	global_load_dwordx4 v[112:115], v[10:11], off
	global_load_dwordx4 v[116:119], v[4:5], off
	v_add_u32_e32 v8, 0, v176
	ds_read_b128 v[4:7], v6 offset:53248
	ds_read_b128 v[66:69], v8 offset:53248
	v_lshl_add_u32 v173, v49, 2, v157
	s_waitcnt vmcnt(7) lgkmcnt(2)
	v_mfma_f32_32x32x16_bf16 v[16:31], v[0:3], v[100:103], v[16:31]
	ds_read_b128 v[0:3], v8 offset:49152
	s_waitcnt vmcnt(3)
	s_waitcnt vmcnt(5)
	ds_write_b128 v77, v[54:57] offset:16384
	s_waitcnt vmcnt(4)
	ds_write_b128 v78, v[58:61] offset:16384
	s_waitcnt vmcnt(3)
	ds_write_b128 v79, v[62:65] offset:57344
	v_mov_b32_e32 v54, 0xf149f2ca
	s_mov_b32 s0, 0x10000
	s_mov_b32 s1, 0xe000
	s_mov_b32 s46, 2
	s_waitcnt lgkmcnt(5)
	v_mfma_f32_32x32x16_bf16 v[32:47], v[4:7], v[100:103], v[32:47]
	s_mov_b32 s47, 1
	s_mov_b32 s48, 4
	s_mov_b32 s64, 3
	v_cmp_gt_u32_e64 s[6:7], 32, v82
	v_add_u32_e32 v183, 0x10000, v76
	v_add_u32_e32 v184, 0, v80
	v_bitop3_b32 v198, v156, s0, v81 bitop3:0xde
	s_waitcnt lgkmcnt(3)
	v_mfma_f32_32x32x16_bf16 v[16:31], v[0:3], v[96:99], v[16:31]
	v_mov_b64_e32 v[0:1], s[8:9]
	v_mov_b64_e32 v[2:3], s[10:11]
	v_mov_b64_e32 v[4:5], s[12:13]
	v_mov_b64_e32 v[6:7], s[14:15]
	v_mov_b64_e32 v[8:9], s[16:17]
	v_mov_b64_e32 v[10:11], s[18:19]
	v_mov_b64_e32 v[12:13], s[20:21]
	v_mfma_f32_32x32x16_bf16 v[32:47], v[66:69], v[96:99], v[32:47]
	s_nop 3
	v_max_f32_e32 v66, v17, v17
	v_max_f32_e32 v67, v16, v16
	v_max_f32_e32 v66, v67, v66
	v_max3_f32 v66, v66, v18, v19
	v_max3_f32 v66, v66, v20, v21
	v_max3_f32 v66, v66, v22, v23
	v_max3_f32 v66, v66, v24, v25
	v_max3_f32 v66, v66, v26, v27
	v_max3_f32 v66, v66, v28, v29
	v_max3_f32 v66, v66, v30, v31
	v_max3_f32 v66, v66, v32, v33
	v_max3_f32 v66, v66, v34, v35
	v_max3_f32 v66, v66, v36, v37
	v_max3_f32 v66, v66, v38, v39
	v_max3_f32 v66, v66, v40, v41
	v_max3_f32 v66, v66, v42, v43
	v_max3_f32 v66, v66, v44, v45
	v_max3_f32 v66, v66, v46, v47
	v_mov_b32_e32 v67, v66
	s_nop 1
	v_permlane32_swap_b32_e32 v66, v67
	v_max_f32_e32 v67, v67, v67
	v_max_f32_e32 v66, v66, v66
	v_max_f32_e32 v66, v66, v67
	v_mov_b64_e32 v[14:15], s[22:23]
	v_add_f32_e32 v67, 0x7149f2ca, v66
	s_mov_b32 s18, 0x4138aa3b
	v_cmp_ge_f32_e32 vcc, s18, v67
	s_cmp_eq_u64 vcc, exec
	v_max_f32_e32 v55, 0xf149f2ca, v66
	s_cselect_b64 vcc, -1, 0
	v_cndmask_b32_e32 v140, v55, v54, vcc
	v_mul_f32_e32 v54, 0xbf800000, v140
	v_mov_b32_e32 v236, v54
	v_mov_b32_e32 v237, v54
	v_mov_b32_e32 v238, v54
	v_mov_b32_e32 v239, v54
	v_mov_b32_e32 v240, v54
	v_mov_b32_e32 v241, v54
	v_mov_b32_e32 v242, v54
	v_mov_b32_e32 v243, v54
	v_mov_b32_e32 v244, v54
	v_mov_b32_e32 v245, v54
	v_mov_b32_e32 v246, v54
	v_mov_b32_e32 v247, v54
	v_mov_b32_e32 v248, v54
	v_mov_b32_e32 v249, v54
	v_mov_b32_e32 v250, v54
	v_mov_b32_e32 v251, v54
	v_fmamk_f32 v16, v16, 0x3f800000, v54
	v_exp_f32_e32 v150, v16
	v_fmamk_f32 v16, v17, 0x3f800000, v54
	v_exp_f32_e32 v170, v16
	v_fmamk_f32 v16, v18, 0x3f800000, v54
	v_exp_f32_e32 v151, v16
	v_fmamk_f32 v16, v19, 0x3f800000, v54
	v_exp_f32_e32 v171, v16
	v_fmamk_f32 v16, v20, 0x3f800000, v54
	v_exp_f32_e32 v168, v16
	v_fmamk_f32 v16, v21, 0x3f800000, v54
	v_exp_f32_e32 v217, v16
	v_fmamk_f32 v16, v22, 0x3f800000, v54
	v_exp_f32_e32 v169, v16
	v_fmamk_f32 v16, v23, 0x3f800000, v54
	v_exp_f32_e32 v218, v16
	v_fmamk_f32 v16, v24, 0x3f800000, v54
	v_exp_f32_e32 v142, v16
	v_fmamk_f32 v16, v25, 0x3f800000, v54
	v_exp_f32_e32 v146, v16
	v_fmamk_f32 v16, v26, 0x3f800000, v54
	v_exp_f32_e32 v143, v16
	v_fmamk_f32 v16, v27, 0x3f800000, v54
	v_exp_f32_e32 v147, v16
	v_fmamk_f32 v16, v28, 0x3f800000, v54
	v_exp_f32_e32 v144, v16
	v_fmamk_f32 v16, v29, 0x3f800000, v54
	v_exp_f32_e32 v148, v16
	v_fmamk_f32 v16, v30, 0x3f800000, v54
	v_exp_f32_e32 v145, v16
	v_add3_u32 v16, v182, 0, v180
	v_add3_u32 v199, v16, v181, v179
	v_lshlrev_b32_e32 v16, 5, v48
	v_pk_fma_f32 v[132:133], v[38:39], s[86:87], v[54:55] op_sel_hi:[1,0,0]
	v_sub_f32_e32 v38, 0xf149f2ca, v55
	v_and_b32_e32 v16, 0x100, v16
	v_lshlrev_b32_e32 v17, 6, v73
	v_and_b32_e32 v18, 7, v70
	v_mul_f32_e32 v38, 0x3f800000, v38
	v_or3_b32 v20, v75, v16, v17
	v_or3_b32 v21, v72, v16, v17
	v_lshl_add_u64 v[16:17], s[62:63], 0, v[52:53]
	v_lshlrev_b32_e32 v18, 4, v18
	v_mov_b32_e32 v19, v163
	v_exp_f32_e32 v38, v38
	v_lshl_add_u64 v[16:17], v[16:17], 0, v[18:19]
	v_and_b32_e32 v18, 15, v70
	v_pk_fma_f32 v[124:125], v[46:47], s[86:87], v[54:55] op_sel_hi:[1,0,0]
	v_pk_fma_f32 v[126:127], v[44:45], s[86:87], v[54:55] op_sel_hi:[1,0,0]
; #define SBAR() __builtin_amdgcn_sched_barrier(0)
; #define SLOAD(i, k0) do { sr_[i].vs0 = *reinterpret_cast<const bf16x8*>(&Vh[(size_t)((k0) + sr) * 128 + sc]); sr_[i].vs1 = *reinterpret_cast<const bf16x8*>(&Vh[(size_t)((k0) + 32 + sr) * 128 + sc]); \
;     sr_[i].ks0 = *reinterpret_cast<const bf16x8*>(&Kh[(size_t)((k0) + kr) * 64 + kc]); } while (0)
; #define SWRITE(b, i) do { *(bf16x8*)(V_lds + (b) * AT_SHM_V + vst0) = sr_[i].vs0; *(bf16x8*)(V_lds + (b) * AT_SHM_V + vst1) = sr_[i].vs1; \
;     *(bf16x8*)(K_lds + (b) * AT_SHM_K + kst) = sr_[i].ks0; } while (0)
; #define SWAIT() asm volatile("s_waitcnt vmcnt(3)" ::: "memory")
; DEV void partialSM(f32x16& p0, f32x16& p1, float& m_reg, float& mn, float& alpha) {
;   constexpr float C = AT_SCALE * 1.4426950408889634f;
;   float pmax = p0[0];
; #pragma unroll
;   for (int r = 1; r < 16; ++r) pmax = fmaxf(pmax, p0[r]);
; #pragma unroll
;   for (int r = 0; r < 16; ++r) pmax = fmaxf(pmax, p1[r]);
;   { auto rr = __builtin_amdgcn_permlane32_swap(__float_as_uint(pmax), __float_as_uint(pmax), false, false);
;     pmax = fmaxf(__uint_as_float(rr[0]), __uint_as_float(rr[1])); }
;   if (__builtin_expect(__all(pmax - m_reg <= AT_THR / AT_SCALE), 1)) { mn = m_reg; alpha = 1.f; }
;   else { mn = fmaxf(m_reg, pmax); alpha = __builtin_amdgcn_exp2f((m_reg - mn) * C); m_reg = mn; }
;   float mnC = -mn * C;
; #pragma unroll
;   for (int r = 0; r < 16; ++r) p0[r] = fmaf(p0[r], C, mnC);
; #pragma unroll
;   for (int r = 0; r < 16; ++r) p1[r] = fmaf(p1[r], C, mnC);
; #pragma unroll
;   for (int r = 0; r < 16; ++r) p0[r] = __builtin_amdgcn_exp2f(p0[r]);
; }
; DEV void attn_pass(const u16* __restrict__ Qb, const u16* __restrict__ Kh, const u16* __restrict__ Vh, int seq, f32x16* o, float* rli) {
;     ...
;   SWAIT(); SWRITE(1, SO); __syncthreads();
; #pragma unroll 1
;   for (int j = 1; j + 1 < NT; j += 2) {
;     const int bm1 = (j - 1) % 3, b0 = j % 3, b1 = (j + 1) % 3, b2 = (j + 2) % 3;
;     SBAR(); qkt(pB0, pB1, K_lds + b0 * AT_SHM_K, qr, r32, hi);
;     finishSM(pA0, pA1, alA, l_reg, pa0, pa1, pa2, pa3); SBAR();
;     SLOAD(SO, (j + 2) * 64); SBAR();
;     pv_d0(o, vb0 + bm1 * AT_SHM_V, pa0, pa1, pa2, pa3); partialSM(pB0, pB1, m_reg, mnB, alB);
;     SWAIT(); SWRITE(b1, SE);
	v_pk_fma_f32 v[128:129], v[42:43], s[86:87], v[54:55] op_sel_hi:[1,0,0]
	v_pk_fma_f32 v[130:131], v[40:41], s[86:87], v[54:55] op_sel_hi:[1,0,0]
	v_pk_fma_f32 v[134:135], v[36:37], s[86:87], v[54:55] op_sel_hi:[1,0,0]
	v_pk_fma_f32 v[136:137], v[34:35], s[86:87], v[54:55] op_sel_hi:[1,0,0]
	v_pk_fma_f32 v[138:139], v[32:33], s[86:87], v[54:55] op_sel_hi:[1,0,0]
	v_fmac_f32_e32 v54, 0x3f800000, v31
	v_lshl_add_u64 v[158:159], s[96:97], 0, v[16:17]
	v_lshl_add_u64 v[16:17], s[52:53], 0, v[50:51]
	v_lshlrev_b32_e32 v18, 4, v18
	v_exp_f32_e32 v149, v54
	v_lshl_add_u64 v[16:17], v[16:17], 0, v[18:19]
	v_lshl_add_u64 v[160:161], s[96:97], 0, v[16:17]
	v_add3_u32 v16, v182, s49, v180
	v_cndmask_b32_e64 v185, v38, 1.0, vcc
	v_add_u32_e32 v206, 0x8000, v20
	v_add_u32_e32 v207, 0x8000, v21
	v_add_u32_e32 v209, 0xc000, v20
	v_add_u32_e32 v210, 0xc000, v21
	v_add3_u32 v211, v16, v181, v179
	v_mov_b64_e32 v[62:63], v[14:15]
	v_mov_b64_e32 v[46:47], v[14:15]
	v_mov_b64_e32 v[30:31], v[14:15]
	v_bitop3_b32 v200, v83, s0, v81 bitop3:0xde
	v_bitop3_b32 v201, v156, s1, v81 bitop3:0xde
	v_bitop3_b32 v202, v71, s0, v81 bitop3:0xde
	v_bitop3_b32 v203, v83, s1, v81 bitop3:0xde
	v_bitop3_b32 v204, v84, s0, v81 bitop3:0xde
	v_add_u32_e32 v205, 0, v74
	v_add_u32_e32 v208, 0x12000, v76
	v_bitop3_b32 v212, v71, s1, v81 bitop3:0xde
	v_bitop3_b32 v213, v84, s1, v81 bitop3:0xde
	v_mov_b32_e32 v174, 0
	v_mov_b64_e32 v[60:61], v[12:13]
	v_mov_b64_e32 v[58:59], v[10:11]
	v_mov_b64_e32 v[56:57], v[8:9]
	v_mov_b64_e32 v[54:55], v[6:7]
	v_mov_b64_e32 v[52:53], v[4:5]
	v_mov_b64_e32 v[50:51], v[2:3]
	v_mov_b64_e32 v[48:49], v[0:1]
	v_mov_b64_e32 v[44:45], v[12:13]
	v_mov_b64_e32 v[42:43], v[10:11]
	v_mov_b64_e32 v[40:41], v[8:9]
	v_mov_b64_e32 v[38:39], v[6:7]
	v_mov_b64_e32 v[36:37], v[4:5]
	v_mov_b64_e32 v[34:35], v[2:3]
	v_mov_b64_e32 v[32:33], v[0:1]
	v_mov_b64_e32 v[28:29], v[12:13]
	v_mov_b64_e32 v[26:27], v[10:11]
	v_mov_b64_e32 v[24:25], v[8:9]
	v_mov_b64_e32 v[22:23], v[6:7]
	v_mov_b64_e32 v[20:21], v[4:5]
	v_mov_b64_e32 v[18:19], v[2:3]
	v_mov_b64_e32 v[16:17], v[0:1]
	s_waitcnt lgkmcnt(0)
	s_barrier
.LBB0_90:
	s_mul_hi_u32 s1, s9, 0xaaaaaaab
	s_lshr_b32 s1, s1, 1
	s_mul_i32 s1, s1, 0xc000
	v_subrev_u32_e32 v190, s1, v199
	s_mul_hi_u32 s1, s47, 0xaaaaaaab
	s_mul_hi_u32 s0, s46, 0xaaaaaaab
	s_lshr_b32 s12, s1, 1
	s_lshr_b32 s0, s0, 1
	s_mul_i32 s1, s12, 0x6000
	s_mul_i32 s15, s0, 0x6000
	v_subrev_u32_e32 v64, s1, v201
	s_mul_i32 s0, s0, 0xc000
	v_subrev_u32_e32 v219, s15, v183
	v_subrev_u32_e32 v164, s1, v203
	v_subrev_u32_e32 v220, s0, v206
	v_subrev_u32_e32 v221, s0, v207
	v_subrev_u32_e32 v191, s1, v212
	v_subrev_u32_e32 v192, s1, v213
	v_add_u32_e32 v141, s14, v184
	v_add_u32_e32 v68, v141, v64
	ds_read_b128 v[64:67], v68
	ds_read_b128 v[68:71], v68 offset:4096
	v_add_u32_e32 v186, v141, v164
	ds_read_b128 v[164:167], v186
	ds_read_b128 v[186:189], v186 offset:4096
	s_waitcnt vmcnt(0)
	v_add_u32_e32 v72, s8, v205
	v_add_u32_e32 v73, v72, v221
	ds_write_b128 v73, v[116:119]
	v_add_u32_e32 v73, v72, v220
	s_add_i32 s13, s14, 0
	ds_write_b128 v73, v[112:115]
	v_add_u32_e32 v73, s13, v219
	ds_write_b128 v73, v[120:123]
	v_exp_f32_e32 v134, v134
	s_waitcnt lgkmcnt(6)
	v_mfma_f32_32x32x16_bf16 v[80:95], v[64:67], v[108:111], v[236:251]
	v_exp_f32_e32 v135, v135
	v_exp_f32_e32 v132, v132
	v_exp_f32_e32 v133, v133
	v_exp_f32_e32 v130, v130
	v_exp_f32_e32 v131, v131
	v_exp_f32_e32 v128, v128
	v_exp_f32_e32 v129, v129
	s_waitcnt lgkmcnt(5)
	v_mfma_f32_32x32x16_bf16 v[64:79], v[68:71], v[108:111], v[236:251]
	v_exp_f32_e32 v126, v126
	v_exp_f32_e32 v127, v127
	v_exp_f32_e32 v124, v124
	v_exp_f32_e32 v125, v125
	s_waitcnt lgkmcnt(4)
	v_mfma_f32_32x32x16_bf16 v[80:95], v[164:167], v[104:107], v[80:95]
	s_waitcnt lgkmcnt(3)
	v_mfma_f32_32x32x16_bf16 v[64:79], v[186:189], v[104:107], v[64:79]
	v_add_u32_e32 v186, v141, v191
	ds_read_b128 v[164:167], v186
	ds_read_b128 v[186:189], v186 offset:4096
	s_waitcnt lgkmcnt(1)
	v_mfma_f32_32x32x16_bf16 v[80:95], v[164:167], v[100:103], v[80:95]
	s_waitcnt lgkmcnt(0)
	v_mfma_f32_32x32x16_bf16 v[64:79], v[186:189], v[100:103], v[64:79]
	v_add_u32_e32 v186, v141, v192
	ds_read_b128 v[164:167], v186
	ds_read_b128 v[186:189], v186 offset:4096
	s_waitcnt lgkmcnt(1)
	v_mfma_f32_32x32x16_bf16 v[80:95], v[164:167], v[96:99], v[80:95]
	v_exp_f32_e32 v166, v136
	v_add_f32_e32 v136, v170, v150
	v_add_f32_e32 v136, v151, v136
	v_add_f32_e32 v136, v171, v136
	v_add_f32_e32 v136, v168, v136
	v_add_f32_e32 v136, v217, v136
	v_add_f32_e32 v136, v169, v136
	v_add_f32_e32 v136, v218, v136
	v_add_f32_e32 v136, v142, v136
	v_add_f32_e32 v136, v146, v136
	v_add_f32_e32 v136, v143, v136
	v_add_f32_e32 v136, v147, v136
	v_exp_f32_e32 v164, v138
	v_add_f32_e32 v136, v144, v136
	v_exp_f32_e32 v165, v139
	v_add_f32_e32 v136, v148, v136
	v_add_f32_e32 v136, v145, v136
	v_exp_f32_e32 v167, v137
	v_add_f32_e32 v136, v149, v136
	v_add_f32_e32 v136, v164, v136
	v_add_f32_e32 v136, v165, v136
	v_add_f32_e32 v136, v166, v136
	v_add_f32_e32 v136, v167, v136
	v_add_f32_e32 v136, v134, v136
	v_add_f32_e32 v136, v135, v136
	v_add_f32_e32 v136, v132, v136
	v_add_f32_e32 v136, v133, v136
	v_add_f32_e32 v136, v130, v136
	v_add_f32_e32 v136, v131, v136
	s_waitcnt lgkmcnt(0)
; DEV void finishSM(f32x16& p0, f32x16& p1, float alpha, float& l_reg, bf16x8& pa0, bf16x8& pa1, bf16x8& pa2, bf16x8& pa3) {
; #pragma unroll
;   for (int r = 0; r < 16; ++r) p1[r] = __builtin_amdgcn_exp2f(p1[r]);
;   float ps = 0;
; #pragma unroll
;   for (int r = 0; r < 16; ++r) ps += p0[r];
; #pragma unroll
;   for (int r = 0; r < 16; ++r) ps += p1[r];
;   { auto rr = __builtin_amdgcn_permlane32_swap(__float_as_uint(ps), __float_as_uint(ps), false, false);
;     ps = __uint_as_float(rr[0]) + __uint_as_float(rr[1]); }
;   l_reg = l_reg * alpha + ps;
;     ...
;   PK4(p0, 0, pa0); PK4(p0, 8, pa1); PK4(p1, 0, pa2); PK4(p1, 8, pa3);
;     ...
; }
; DEV void qkt(f32x16& p0, f32x16& p1, const char* Ks, const bf16x8* qr, int r32, int hi) {
;   p0 = f32x16{}; p1 = f32x16{};
; #pragma unroll
;   for (int d0 = 0; d0 < 4; ++d0) { int cb = (d0 * 16 + hi * 8) * 2;
;     bf16x8 b0 = *reinterpret_cast<const bf16x8*>(Ks + KSWZ64(r32, cb));
;     bf16x8 b1 = *reinterpret_cast<const bf16x8*>(Ks + KSWZ64(32 + r32, cb));
;     p0 = __builtin_amdgcn_mfma_f32_32x32x16_bf16(b0, qr[d0], p0, 0, 0, 0);
;     p1 = __builtin_amdgcn_mfma_f32_32x32x16_bf16(b1, qr[d0], p1, 0, 0, 0); }
; }
; DEV int v_st(int k, int c) { const int kk = (k & ~0xC) | ((k & 4) << 1) | ((k & 8) >> 1); return ((kk >> 3) * 4 + (c >> 5)) * 512 + ((kk & 7) * 32 + (c & 31)) * 2; }
; DEV int v_rd_base(int lane) { return ((lane & 3) << 3) | (((lane >> 2) & 3) << 6) | (((lane >> 4) & 1) << 5) | (((lane >> 5) & 1) << 8); }
; template <int OFF> DEV s16x4 tr_read(int vb) {
;   s16x4 r; asm volatile("ds_read_b64_tr_b16 %0, %1 offset:%2" : "=&v"(r) : "v"(vb), "i"(OFF) : "memory"); return r;
; }
; template <int D0> DEV void pv_one(f32x16& od, int vb, bf16x8 pa0, bf16x8 pa1, bf16x8 pa2, bf16x8 pa3) {
;   const s16x4 l0 = tr_read<v_rd_off(D0, 0, 0)>(vb), h0 = tr_read<v_rd_off(D0, 0, 1)>(vb), l1 = tr_read<v_rd_off(D0, 1, 0)>(vb), h1 = tr_read<v_rd_off(D0, 1, 1)>(vb);
;   const s16x4 l2 = tr_read<v_rd_off(D0, 2, 0)>(vb), h2 = tr_read<v_rd_off(D0, 2, 1)>(vb), l3 = tr_read<v_rd_off(D0, 3, 0)>(vb), h3 = tr_read<v_rd_off(D0, 3, 1)>(vb);
;   asm volatile("s_waitcnt lgkmcnt(0)" ::: "memory"); SBAR();
;     ...
;   od = __builtin_amdgcn_mfma_f32_32x32x16_bf16(pa0, PK(l0, h0), od, 0, 0, 0);
;   od = __builtin_amdgcn_mfma_f32_32x32x16_bf16(pa1, PK(l1, h1), od, 0, 0, 0);
;   od = __builtin_amdgcn_mfma_f32_32x32x16_bf16(pa2, PK(l2, h2), od, 0, 0, 0);
	v_mfma_f32_32x32x16_bf16 v[64:79], v[186:189], v[96:99], v[64:79]
	v_add_f32_e32 v136, v128, v136
	v_add_f32_e32 v136, v129, v136
	v_add_f32_e32 v136, v126, v136
	v_add_f32_e32 v136, v127, v136
	v_add_f32_e32 v136, v124, v136
	v_add_f32_e32 v214, v125, v136
	v_mov_b32_e32 v215, v214
	v_cvt_pk_bf16_f32 v136, v150, v170
	v_cvt_pk_bf16_f32 v138, v168, v217
	s_nop 1
	v_permlane32_swap_b32_e32 v214, v215
	v_cvt_pk_bf16_f32 v137, v151, v171
	v_cvt_pk_bf16_f32 v139, v169, v218
	v_permlane32_swap_b32_e32 v136, v138
	v_cvt_pk_bf16_f32 v142, v142, v146
	v_cvt_pk_bf16_f32 v143, v143, v147
	v_cvt_pk_bf16_f32 v144, v144, v148
	v_cvt_pk_bf16_f32 v145, v145, v149
	v_cvt_pk_bf16_f32 v146, v164, v165
	v_cvt_pk_bf16_f32 v147, v166, v167
	v_cvt_pk_bf16_f32 v148, v134, v135
	v_cvt_pk_bf16_f32 v149, v132, v133
	v_cvt_pk_bf16_f32 v164, v130, v131
	v_cvt_pk_bf16_f32 v165, v128, v129
	v_cvt_pk_bf16_f32 v166, v126, v127
	v_cvt_pk_bf16_f32 v167, v124, v125
	v_permlane32_swap_b32_e32 v137, v139
	v_permlane32_swap_b32_e32 v142, v144
	v_permlane32_swap_b32_e32 v143, v145
	v_permlane32_swap_b32_e32 v146, v148
	v_permlane32_swap_b32_e32 v147, v149
	v_permlane32_swap_b32_e32 v164, v166
	v_permlane32_swap_b32_e32 v165, v167
	v_lshl_add_u64 v[168:169], v[160:161], 0, s[82:83]
	v_add_co_u32_e32 v124, vcc, s94, v168
	v_lshl_add_u64 v[170:171], v[158:159], 0, s[82:83]
	s_nop 0
	v_addc_co_u32_e32 v125, vcc, 0, v169, vcc
	v_add_co_u32_e32 v128, vcc, s95, v168
	s_mov_b32 s0, 0x1868e000
	s_nop 0
	v_addc_co_u32_e32 v129, vcc, 0, v169, vcc
	v_add_co_u32_e32 v132, vcc, s0, v170
	global_load_dwordx4 v[124:127], v[124:125], off
	s_nop 0
	global_load_dwordx4 v[128:131], v[128:129], off
	v_addc_co_u32_e32 v133, vcc, 0, v171, vcc
	global_load_dwordx4 v[132:135], v[132:133], off
	v_add_u32_e32 v150, s8, v190
	ds_read_b64_tr_b16 v[186:187], v150 offset:0
	ds_read_b64_tr_b16 v[188:189], v150 offset:0x800
	ds_read_b64_tr_b16 v[190:191], v150 offset:0x1000
	ds_read_b64_tr_b16 v[192:193], v150 offset:0x1800
	ds_read_b64_tr_b16 v[222:223], v150 offset:0x2000
	ds_read_b64_tr_b16 v[224:225], v150 offset:0x2800
	ds_read_b64_tr_b16 v[226:227], v150 offset:0x3000
	ds_read_b64_tr_b16 v[228:229], v150 offset:0x3800
	s_waitcnt lgkmcnt(0)
	s_nop 0
	v_mfma_f32_32x32x16_bf16 v[0:15], v[136:139], v[186:189], v[0:15]
	ds_read_b64_tr_b16 v[186:187], v150 offset:0x200
	ds_read_b64_tr_b16 v[188:189], v150 offset:0xa00
	v_mfma_f32_32x32x16_bf16 v[0:15], v[142:145], v[190:193], v[0:15]
	ds_read_b64_tr_b16 v[190:191], v150 offset:0x1200
	ds_read_b64_tr_b16 v[192:193], v150 offset:0x1a00
	v_mfma_f32_32x32x16_bf16 v[0:15], v[146:149], v[222:225], v[0:15]
	ds_read_b64_tr_b16 v[222:223], v150 offset:0x2200
	ds_read_b64_tr_b16 v[224:225], v150 offset:0x2a00
	v_mfma_f32_32x32x16_bf16 v[0:15], v[164:167], v[226:229], v[0:15]
	ds_read_b64_tr_b16 v[226:227], v150 offset:0x3200
	ds_read_b64_tr_b16 v[228:229], v150 offset:0x3a00
	s_waitcnt lgkmcnt(0)
	v_mfma_f32_32x32x16_bf16 v[48:63], v[136:139], v[186:189], v[48:63]
	ds_read_b64_tr_b16 v[186:187], v150 offset:0x400
	ds_read_b64_tr_b16 v[188:189], v150 offset:0xc00
	v_mfma_f32_32x32x16_bf16 v[48:63], v[142:145], v[190:193], v[48:63]
	ds_read_b64_tr_b16 v[190:191], v150 offset:0x1400
	ds_read_b64_tr_b16 v[192:193], v150 offset:0x1c00
	v_mfma_f32_32x32x16_bf16 v[48:63], v[146:149], v[222:225], v[48:63]
	ds_read_b64_tr_b16 v[222:223], v150 offset:0x2400
	ds_read_b64_tr_b16 v[224:225], v150 offset:0x2c00
	v_mfma_f32_32x32x16_bf16 v[48:63], v[164:167], v[226:229], v[48:63]
	ds_read_b64_tr_b16 v[226:227], v150 offset:0x3400
	ds_read_b64_tr_b16 v[228:229], v150 offset:0x3c00
	s_waitcnt lgkmcnt(0)
	v_mfma_f32_32x32x16_bf16 v[32:47], v[136:139], v[186:189], v[32:47]
	ds_read_b64_tr_b16 v[186:187], v150 offset:0x600
	ds_read_b64_tr_b16 v[188:189], v150 offset:0xe00
	v_mfma_f32_32x32x16_bf16 v[32:47], v[142:145], v[190:193], v[32:47]
	ds_read_b64_tr_b16 v[190:191], v150 offset:0x1600
	ds_read_b64_tr_b16 v[192:193], v150 offset:0x1e00
	v_mfma_f32_32x32x16_bf16 v[32:47], v[146:149], v[222:225], v[32:47]
	ds_read_b64_tr_b16 v[222:223], v150 offset:0x2600
	ds_read_b64_tr_b16 v[224:225], v150 offset:0x2e00
	v_mfma_f32_32x32x16_bf16 v[32:47], v[164:167], v[226:229], v[32:47]
	ds_read_b64_tr_b16 v[226:227], v150 offset:0x3600
	ds_read_b64_tr_b16 v[228:229], v150 offset:0x3e00
	s_waitcnt lgkmcnt(0)
	v_mfma_f32_32x32x16_bf16 v[16:31], v[136:139], v[186:189], v[16:31]
	v_max_f32_e32 v136, v80, v81
	v_max3_f32 v136, v136, v82, v83
	v_max3_f32 v136, v136, v84, v85
	v_max3_f32 v136, v136, v86, v87
	v_max3_f32 v136, v136, v88, v89
	v_max3_f32 v136, v136, v90, v91
	v_max3_f32 v136, v136, v92, v93
	v_max3_f32 v136, v136, v94, v95
	v_mfma_f32_32x32x16_bf16 v[16:31], v[142:145], v[190:193], v[16:31]
	v_max3_f32 v136, v136, v64, v65
	v_max3_f32 v136, v136, v66, v67
	v_max3_f32 v136, v136, v68, v69
	v_max3_f32 v136, v136, v70, v71
	v_max3_f32 v136, v136, v72, v73
	v_max3_f32 v136, v136, v74, v75
	v_max3_f32 v136, v136, v76, v77
	v_max3_f32 v136, v136, v78, v79
	v_mfma_f32_32x32x16_bf16 v[16:31], v[146:149], v[222:225], v[16:31]
	v_mov_b32_e32 v137, v136
	s_nop 1
	v_permlane32_swap_b32_e32 v136, v137
	v_max_f32_e32 v136, v136, v137
	v_cmp_ge_f32_e32 vcc, s18, v136
	v_mfma_f32_32x32x16_bf16 v[16:31], v[164:167], v[226:229], v[16:31]
	s_cmp_eq_u64 vcc, exec
	s_cselect_b64 s[0:1], -1, 0
	s_cbranch_scc1 .Lattn_fast3
	v_max_f32_e32 v136, 0, v136
	v_exp_f32_e64 v137, -v136
; #define SWRITE(b, i) do { *(bf16x8*)(V_lds + (b) * AT_SHM_V + vst0) = sr_[i].vs0; *(bf16x8*)(V_lds + (b) * AT_SHM_V + vst1) = sr_[i].vs1; \
;     *(bf16x8*)(K_lds + (b) * AT_SHM_K + kst) = sr_[i].ks0; } while (0)
; #define SWAIT() asm volatile("s_waitcnt vmcnt(3)" ::: "memory")
; #define RESC(a) do { if (__any((a) < 1.f)) { if (hi == 0) al_l[r32] = (a); asm volatile("s_waitcnt lgkmcnt(0)" ::: "memory"); \
;     for (int d = 0; d < 4; ++d) for (int r = 0; r < 16; ++r) o[d][r] *= al_l[crow(r, hi)]; } } while (0)
; DEV void partialSM(f32x16& p0, f32x16& p1, float& m_reg, float& mn, float& alpha) {
;   constexpr float C = AT_SCALE * 1.4426950408889634f;
;   float pmax = p0[0];
; #pragma unroll
;   for (int r = 1; r < 16; ++r) pmax = fmaxf(pmax, p0[r]);
; #pragma unroll
;   for (int r = 0; r < 16; ++r) pmax = fmaxf(pmax, p1[r]);
;   { auto rr = __builtin_amdgcn_permlane32_swap(__float_as_uint(pmax), __float_as_uint(pmax), false, false);
;     pmax = fmaxf(__uint_as_float(rr[0]), __uint_as_float(rr[1])); }
;   if (__builtin_expect(__all(pmax - m_reg <= AT_THR / AT_SCALE), 1)) { mn = m_reg; alpha = 1.f; }
;   else { mn = fmaxf(m_reg, pmax); alpha = __builtin_amdgcn_exp2f((m_reg - mn) * C); m_reg = mn; }
;   float mnC = -mn * C;
; #pragma unroll
;   for (int r = 0; r < 16; ++r) p0[r] = fmaf(p0[r], C, mnC);
; #pragma unroll
;   for (int r = 0; r < 16; ++r) p1[r] = fmaf(p1[r], C, mnC);
; #pragma unroll
;   for (int r = 0; r < 16; ++r) p0[r] = __builtin_amdgcn_exp2f(p0[r]);
; }
; DEV void attn_pass(const u16* __restrict__ Qb, const u16* __restrict__ Kh, const u16* __restrict__ Vh, int seq, f32x16* o, float* rli) {
;     ...
;     pv_d0(o, vb0 + bm1 * AT_SHM_V, pa0, pa1, pa2, pa3); partialSM(pB0, pB1, m_reg, mnB, alB);
;     SWAIT(); SWRITE(b1, SE);
;     RESC(alB); __syncthreads();
.Lattn_fast3:
	v_add_u32_e32 v217, s8, v205
	v_cndmask_b32_e64 v216, v137, 1.0, s[0:1]
	v_cmp_gt_f32_e32 vcc, 1.0, v216
	s_cbranch_vccz .LBB0_94
	s_and_saveexec_b64 s[10:11], s[6:7]
	ds_write_b32 v173, v216 offset:128
	s_or_b64 exec, exec, s[10:11]
	s_waitcnt lgkmcnt(0)
	v_add_u32_e32 v137, v157, v156
	ds_read_b128 v[142:145], v137 offset:224
	ds_read_b128 v[146:149], v137 offset:192
	ds_read_b128 v[164:167], v137 offset:160
	ds_read_b128 v[186:189], v137 offset:128
	s_waitcnt lgkmcnt(3)
	v_pk_mul_f32 v[12:13], v[12:13], v[142:143]
	s_waitcnt lgkmcnt(2)
	v_pk_mul_f32 v[8:9], v[8:9], v[146:147]
	s_waitcnt lgkmcnt(1)
	v_pk_mul_f32 v[4:5], v[4:5], v[164:165]
	v_pk_mul_f32 v[14:15], v[14:15], v[144:145]
	v_pk_mul_f32 v[10:11], v[10:11], v[148:149]
	v_pk_mul_f32 v[6:7], v[6:7], v[166:167]
	s_waitcnt lgkmcnt(0)
	v_pk_mul_f32 v[2:3], v[2:3], v[188:189]
	v_pk_mul_f32 v[0:1], v[0:1], v[186:187]
	v_pk_mul_f32 v[60:61], v[60:61], v[142:143]
	v_pk_mul_f32 v[56:57], v[56:57], v[146:147]
	v_pk_mul_f32 v[52:53], v[52:53], v[164:165]
	v_pk_mul_f32 v[62:63], v[62:63], v[144:145]
	v_pk_mul_f32 v[58:59], v[58:59], v[148:149]
	v_pk_mul_f32 v[54:55], v[54:55], v[166:167]
	v_pk_mul_f32 v[50:51], v[50:51], v[188:189]
	v_pk_mul_f32 v[48:49], v[48:49], v[186:187]
	v_pk_mul_f32 v[44:45], v[44:45], v[142:143]
	v_pk_mul_f32 v[40:41], v[40:41], v[146:147]
	v_pk_mul_f32 v[36:37], v[36:37], v[164:165]
	v_pk_mul_f32 v[46:47], v[46:47], v[144:145]
	v_pk_mul_f32 v[42:43], v[42:43], v[148:149]
	v_pk_mul_f32 v[38:39], v[38:39], v[166:167]
	v_pk_mul_f32 v[34:35], v[34:35], v[188:189]
	v_pk_mul_f32 v[32:33], v[32:33], v[186:187]
	v_pk_mul_f32 v[28:29], v[28:29], v[142:143]
	v_pk_mul_f32 v[24:25], v[24:25], v[146:147]
	v_pk_mul_f32 v[20:21], v[20:21], v[164:165]
	v_pk_mul_f32 v[30:31], v[30:31], v[144:145]
	v_pk_mul_f32 v[26:27], v[26:27], v[148:149]
	v_pk_mul_f32 v[22:23], v[22:23], v[166:167]
	v_pk_mul_f32 v[18:19], v[18:19], v[188:189]
	v_pk_mul_f32 v[16:17], v[16:17], v[186:187]
	v_sub_f32_e32 v80, v80, v136
	v_sub_f32_e32 v81, v81, v136
	v_sub_f32_e32 v82, v82, v136
	v_sub_f32_e32 v83, v83, v136
	v_sub_f32_e32 v84, v84, v136
	v_sub_f32_e32 v85, v85, v136
	v_sub_f32_e32 v86, v86, v136
	v_sub_f32_e32 v87, v87, v136
	v_sub_f32_e32 v88, v88, v136
	v_sub_f32_e32 v89, v89, v136
	v_sub_f32_e32 v90, v90, v136
	v_sub_f32_e32 v91, v91, v136
	v_sub_f32_e32 v92, v92, v136
	v_sub_f32_e32 v93, v93, v136
	v_sub_f32_e32 v94, v94, v136
	v_sub_f32_e32 v95, v95, v136
	v_sub_f32_e32 v64, v64, v136
	v_sub_f32_e32 v65, v65, v136
	v_sub_f32_e32 v66, v66, v136
	v_sub_f32_e32 v67, v67, v136
	v_sub_f32_e32 v68, v68, v136
	v_sub_f32_e32 v69, v69, v136
	v_sub_f32_e32 v70, v70, v136
	v_sub_f32_e32 v71, v71, v136
	v_sub_f32_e32 v72, v72, v136
	v_sub_f32_e32 v73, v73, v136
	v_sub_f32_e32 v74, v74, v136
	v_sub_f32_e32 v75, v75, v136
	v_sub_f32_e32 v76, v76, v136
	v_sub_f32_e32 v77, v77, v136
	v_sub_f32_e32 v78, v78, v136
	v_sub_f32_e32 v79, v79, v136
	v_sub_f32_e32 v236, v236, v136
	v_sub_f32_e32 v237, v237, v136
	v_sub_f32_e32 v238, v238, v136
	v_sub_f32_e32 v239, v239, v136
	v_sub_f32_e32 v240, v240, v136
	v_sub_f32_e32 v241, v241, v136
	v_sub_f32_e32 v242, v242, v136
	v_sub_f32_e32 v243, v243, v136
	v_sub_f32_e32 v244, v244, v136
	v_sub_f32_e32 v245, v245, v136
	v_sub_f32_e32 v246, v246, v136
	v_sub_f32_e32 v247, v247, v136
	v_sub_f32_e32 v248, v248, v136
	v_sub_f32_e32 v249, v249, v136
	v_sub_f32_e32 v250, v250, v136
	v_sub_f32_e32 v251, v251, v136
.LBB0_94:
	v_subrev_u32_e32 v137, s15, v198
	v_subrev_u32_e32 v138, s15, v200
	v_subrev_u32_e32 v146, s15, v202
	v_subrev_u32_e32 v147, s15, v204
	v_mov_b32_e32 v149, v64
	v_mov_b32_e32 v150, v65
	v_mov_b32_e32 v151, v66
	v_mov_b32_e32 v164, v67
	v_mov_b32_e32 v165, v68
	v_mov_b32_e32 v166, v69
	v_mov_b32_e32 v167, v70
	v_mov_b32_e32 v186, v71
	v_mov_b32_e32 v187, v72
	v_mov_b32_e32 v188, v73
	v_mov_b32_e32 v189, v74
	v_mov_b32_e32 v190, v75
	v_mov_b32_e32 v191, v76
	v_mov_b32_e32 v192, v77
	v_mov_b32_e32 v193, v78
	v_mov_b32_e32 v148, v79
	v_exp_f32_e32 v194, v80
	v_exp_f32_e32 v195, v81
	v_exp_f32_e32 v221, v82
	v_exp_f32_e32 v222, v83
	v_exp_f32_e32 v223, v84
	v_exp_f32_e32 v224, v85
	v_exp_f32_e32 v225, v86
	v_exp_f32_e32 v226, v87
	v_exp_f32_e32 v227, v88
	v_exp_f32_e32 v228, v89
	v_exp_f32_e32 v229, v90
	v_exp_f32_e32 v230, v91
	v_exp_f32_e32 v231, v92
	v_exp_f32_e32 v232, v93
	v_exp_f32_e32 v233, v94
	v_exp_f32_e32 v234, v95
	s_waitcnt lgkmcnt(0)
	s_barrier
; #define SBAR() __builtin_amdgcn_sched_barrier(0)
; DEV void partialSM(f32x16& p0, f32x16& p1, float& m_reg, float& mn, float& alpha) {
;   constexpr float C = AT_SCALE * 1.4426950408889634f;
;   float pmax = p0[0];
; #pragma unroll
;   for (int r = 1; r < 16; ++r) pmax = fmaxf(pmax, p0[r]);
; #pragma unroll
;   for (int r = 0; r < 16; ++r) pmax = fmaxf(pmax, p1[r]);
;   { auto rr = __builtin_amdgcn_permlane32_swap(__float_as_uint(pmax), __float_as_uint(pmax), false, false);
;     pmax = fmaxf(__uint_as_float(rr[0]), __uint_as_float(rr[1])); }
;   if (__builtin_expect(__all(pmax - m_reg <= AT_THR / AT_SCALE), 1)) { mn = m_reg; alpha = 1.f; }
;   else { mn = fmaxf(m_reg, pmax); alpha = __builtin_amdgcn_exp2f((m_reg - mn) * C); m_reg = mn; }
;   float mnC = -mn * C;
; #pragma unroll
;   for (int r = 0; r < 16; ++r) p0[r] = fmaf(p0[r], C, mnC);
; #pragma unroll
;   for (int r = 0; r < 16; ++r) p1[r] = fmaf(p1[r], C, mnC);
; #pragma unroll
;   for (int r = 0; r < 16; ++r) p0[r] = __builtin_amdgcn_exp2f(p0[r]);
; }
; DEV void finishSM(f32x16& p0, f32x16& p1, float alpha, float& l_reg, bf16x8& pa0, bf16x8& pa1, bf16x8& pa2, bf16x8& pa3) {
; #pragma unroll
;   for (int r = 0; r < 16; ++r) p1[r] = __builtin_amdgcn_exp2f(p1[r]);
;   float ps = 0;
; #pragma unroll
;   for (int r = 0; r < 16; ++r) ps += p0[r];
; #pragma unroll
;   for (int r = 0; r < 16; ++r) ps += p1[r];
;   { auto rr = __builtin_amdgcn_permlane32_swap(__float_as_uint(ps), __float_as_uint(ps), false, false);
;     ps = __uint_as_float(rr[0]) + __uint_as_float(rr[1]); }
;   l_reg = l_reg * alpha + ps;
;     ...
;   PK4(p0, 0, pa0); PK4(p0, 8, pa1); PK4(p1, 0, pa2); PK4(p1, 8, pa3);
;     ...
; }
; DEV void qkt(f32x16& p0, f32x16& p1, const char* Ks, const bf16x8* qr, int r32, int hi) {
;   p0 = f32x16{}; p1 = f32x16{};
; #pragma unroll
;   for (int d0 = 0; d0 < 4; ++d0) { int cb = (d0 * 16 + hi * 8) * 2;
;     bf16x8 b0 = *reinterpret_cast<const bf16x8*>(Ks + KSWZ64(r32, cb));
;     bf16x8 b1 = *reinterpret_cast<const bf16x8*>(Ks + KSWZ64(32 + r32, cb));
;     p0 = __builtin_amdgcn_mfma_f32_32x32x16_bf16(b0, qr[d0], p0, 0, 0, 0);
;     p1 = __builtin_amdgcn_mfma_f32_32x32x16_bf16(b1, qr[d0], p1, 0, 0, 0); }
; }
; DEV void attn_pass(const u16* __restrict__ Qb, const u16* __restrict__ Kh, const u16* __restrict__ Vh, int seq, f32x16* o, float* rli) {
;     ...
;     SBAR(); qkt(pA0, pA1, K_lds + b1 * AT_SHM_K, qr, r32, hi);
	v_add_u32_e32 v68, v141, v137
	ds_read_b128 v[64:67], v68
	ds_read_b128 v[68:71], v68 offset:4096
	v_add_u32_e32 v140, v141, v138
	ds_read_b128 v[136:139], v140
	ds_read_b128 v[142:145], v140 offset:4096
	v_add_u32_e32 v140, v141, v146
	s_waitcnt vmcnt(0)
	s_mul_hi_u32 s0, s64, 0xaaaaaaab
	s_lshr_b32 s0, s0, 1
	s_mul_i32 s1, s0, 0x6000
	s_mul_i32 s0, s0, 0xc000
	v_subrev_u32_e32 v72, s0, v210
	v_add_u32_e32 v72, v217, v72
	ds_write_b128 v72, v[124:127]
	v_subrev_u32_e32 v72, s0, v209
	v_add_u32_e32 v72, v217, v72
	ds_write_b128 v72, v[128:131]
	v_subrev_u32_e32 v72, s1, v208
	v_add_u32_e32 v72, s13, v72
	ds_write_b128 v72, v[132:135]
	s_waitcnt lgkmcnt(6)
	v_mfma_f32_32x32x16_bf16 v[80:95], v[64:67], v[108:111], v[236:251]
	v_exp_f32_e32 v146, v151
	v_exp_f32_e32 v151, v167
	v_exp_f32_e32 v167, v189
	v_exp_f32_e32 v189, v193
	s_waitcnt lgkmcnt(5)
	v_mfma_f32_32x32x16_bf16 v[64:79], v[68:71], v[108:111], v[236:251]
	s_waitcnt lgkmcnt(4)
	v_mfma_f32_32x32x16_bf16 v[80:95], v[136:139], v[104:107], v[80:95]
	s_waitcnt lgkmcnt(3)
	v_mfma_f32_32x32x16_bf16 v[64:79], v[142:145], v[104:107], v[64:79]
	ds_read_b128 v[136:139], v140
	ds_read_b128 v[142:145], v140 offset:4096
	v_add_u32_e32 v140, v141, v147
	v_exp_f32_e32 v147, v164
	v_exp_f32_e32 v164, v186
	v_exp_f32_e32 v186, v190
	v_exp_f32_e32 v190, v148
	s_waitcnt lgkmcnt(1)
	v_mfma_f32_32x32x16_bf16 v[80:95], v[136:139], v[100:103], v[80:95]
	s_waitcnt lgkmcnt(0)
	v_mfma_f32_32x32x16_bf16 v[64:79], v[142:145], v[100:103], v[64:79]
	ds_read_b128 v[136:139], v140
	ds_read_b128 v[140:143], v140 offset:4096
	v_exp_f32_e32 v144, v149
	v_exp_f32_e32 v145, v150
	v_exp_f32_e32 v149, v165
	v_exp_f32_e32 v150, v166
	v_exp_f32_e32 v165, v187
	v_exp_f32_e32 v166, v188
	s_waitcnt lgkmcnt(1)
	v_mfma_f32_32x32x16_bf16 v[80:95], v[136:139], v[96:99], v[80:95]
	v_add_f32_e32 v136, v195, v194
	v_add_f32_e32 v136, v221, v136
	v_add_f32_e32 v136, v222, v136
	v_add_f32_e32 v136, v223, v136
	v_add_f32_e32 v136, v224, v136
	v_add_f32_e32 v136, v225, v136
	v_add_f32_e32 v136, v226, v136
	v_add_f32_e32 v136, v227, v136
	v_add_f32_e32 v136, v228, v136
	v_add_f32_e32 v136, v229, v136
	v_add_f32_e32 v136, v230, v136
	v_add_f32_e32 v136, v231, v136
	v_add_f32_e32 v136, v232, v136
	v_add_f32_e32 v136, v233, v136
	v_add_f32_e32 v136, v234, v136
	v_add_f32_e32 v136, v144, v136
	v_add_f32_e32 v136, v145, v136
	v_add_f32_e32 v136, v146, v136
	v_add_f32_e32 v136, v147, v136
	v_add_f32_e32 v136, v149, v136
	v_add_f32_e32 v136, v150, v136
	v_add_f32_e32 v136, v151, v136
	v_add_f32_e32 v136, v164, v136
	v_exp_f32_e32 v187, v191
	v_add_f32_e32 v136, v165, v136
	v_exp_f32_e32 v188, v192
	v_add_f32_e32 v136, v166, v136
	s_waitcnt lgkmcnt(0)
	v_mfma_f32_32x32x16_bf16 v[64:79], v[140:143], v[96:99], v[64:79]
	v_add_f32_e32 v136, v167, v136
	v_add_f32_e32 v136, v186, v136
	v_add_f32_e32 v136, v187, v136
	v_add_f32_e32 v136, v188, v136
	v_add_f32_e32 v136, v189, v136
	v_add_f32_e32 v219, v190, v136
	v_mov_b32_e32 v220, v219
	v_cvt_pk_bf16_f32 v136, v194, v195
	v_cvt_pk_bf16_f32 v137, v221, v222
	v_cvt_pk_bf16_f32 v138, v223, v224
	v_cvt_pk_bf16_f32 v139, v225, v226
	v_cvt_pk_bf16_f32 v140, v227, v228
	v_cvt_pk_bf16_f32 v141, v229, v230
	v_cvt_pk_bf16_f32 v142, v231, v232
	v_cvt_pk_bf16_f32 v143, v233, v234
	v_cvt_pk_bf16_f32 v144, v144, v145
	v_cvt_pk_bf16_f32 v145, v146, v147
	v_cvt_pk_bf16_f32 v146, v149, v150
	v_cvt_pk_bf16_f32 v147, v151, v164
	v_cvt_pk_bf16_f32 v148, v165, v166
	v_cvt_pk_bf16_f32 v149, v167, v186
	v_cvt_pk_bf16_f32 v150, v187, v188
	v_cvt_pk_bf16_f32 v151, v189, v190
	s_nop 1
	v_permlane32_swap_b32_e32 v219, v220
	v_permlane32_swap_b32_e32 v136, v138
	v_permlane32_swap_b32_e32 v137, v139
	v_permlane32_swap_b32_e32 v140, v142
	v_permlane32_swap_b32_e32 v141, v143
	v_permlane32_swap_b32_e32 v144, v146
	v_permlane32_swap_b32_e32 v145, v147
	v_permlane32_swap_b32_e32 v148, v150
	v_permlane32_swap_b32_e32 v149, v151
	s_cmp_ge_u32 s48, s44
	s_cselect_b64 s[10:11], -1, 0
	s_and_b64 vcc, exec, s[10:11]
	s_cbranch_vccnz .LBB0_96
	v_add_co_u32_e32 v112, vcc, 0x1a810000, v168
	s_nop 1
	v_addc_co_u32_e32 v113, vcc, 0, v169, vcc
	v_add_co_u32_e32 v114, vcc, 0x1a812000, v168
	s_nop 1
	v_addc_co_u32_e32 v115, vcc, 0, v169, vcc
	v_add_co_u32_e32 v120, vcc, 0x18690000, v170
	global_load_dwordx4 v[116:119], v[112:113], off
	s_nop 0
	global_load_dwordx4 v[112:115], v[114:115], off
	v_addc_co_u32_e32 v121, vcc, 0, v171, vcc
	global_load_dwordx4 v[120:123], v[120:121], off
; #define SBAR() __builtin_amdgcn_sched_barrier(0)
; DEV void partialSM(f32x16& p0, f32x16& p1, float& m_reg, float& mn, float& alpha) {
;   constexpr float C = AT_SCALE * 1.4426950408889634f;
;   float pmax = p0[0];
; #pragma unroll
;   for (int r = 1; r < 16; ++r) pmax = fmaxf(pmax, p0[r]);
; #pragma unroll
;   for (int r = 0; r < 16; ++r) pmax = fmaxf(pmax, p1[r]);
;   { auto rr = __builtin_amdgcn_permlane32_swap(__float_as_uint(pmax), __float_as_uint(pmax), false, false);
;     pmax = fmaxf(__uint_as_float(rr[0]), __uint_as_float(rr[1])); }
;   if (__builtin_expect(__all(pmax - m_reg <= AT_THR / AT_SCALE), 1)) { mn = m_reg; alpha = 1.f; }
;   else { mn = fmaxf(m_reg, pmax); alpha = __builtin_amdgcn_exp2f((m_reg - mn) * C); m_reg = mn; }
; template <int OFF> DEV s16x4 tr_read(int vb) {
;   s16x4 r; asm volatile("ds_read_b64_tr_b16 %0, %1 offset:%2" : "=&v"(r) : "v"(vb), "i"(OFF) : "memory"); return r;
; }
; template <int D0> DEV void pv_one(f32x16& od, int vb, bf16x8 pa0, bf16x8 pa1, bf16x8 pa2, bf16x8 pa3) {
;   const s16x4 l0 = tr_read<v_rd_off(D0, 0, 0)>(vb), h0 = tr_read<v_rd_off(D0, 0, 1)>(vb), l1 = tr_read<v_rd_off(D0, 1, 0)>(vb), h1 = tr_read<v_rd_off(D0, 1, 1)>(vb);
;   const s16x4 l2 = tr_read<v_rd_off(D0, 2, 0)>(vb), h2 = tr_read<v_rd_off(D0, 2, 1)>(vb), l3 = tr_read<v_rd_off(D0, 3, 0)>(vb), h3 = tr_read<v_rd_off(D0, 3, 1)>(vb);
;   asm volatile("s_waitcnt lgkmcnt(0)" ::: "memory"); SBAR();
;     ...
;   od = __builtin_amdgcn_mfma_f32_32x32x16_bf16(pa0, PK(l0, h0), od, 0, 0, 0);
;   od = __builtin_amdgcn_mfma_f32_32x32x16_bf16(pa1, PK(l1, h1), od, 0, 0, 0);
;   od = __builtin_amdgcn_mfma_f32_32x32x16_bf16(pa2, PK(l2, h2), od, 0, 0, 0);
;   od = __builtin_amdgcn_mfma_f32_32x32x16_bf16(pa3, PK(l3, h3), od, 0, 0, 0);
;     ...
; }
; DEV void pv_d0(f32x16* o, int vb, bf16x8 pa0, bf16x8 pa1, bf16x8 pa2, bf16x8 pa3) {
;   pv_one<0>(o[0], vb, pa0, pa1, pa2, pa3); pv_one<1>(o[1], vb, pa0, pa1, pa2, pa3); pv_one<2>(o[2], vb, pa0, pa1, pa2, pa3); pv_one<3>(o[3], vb, pa0, pa1, pa2, pa3);
.LBB0_96:
	s_mul_hi_u32 s0, s64, 0xaaaaaaab
	s_lshr_b32 s0, s0, 1
	s_mul_i32 s1, s0, 0x6000
	s_mul_i32 s0, s0, 0xc000
	s_mul_i32 s12, s12, 0xc000
	v_subrev_u32_e32 v164, s12, v211
	v_add_u32_e32 v222, s8, v164
	ds_read_b64_tr_b16 v[164:165], v222 offset:0
	ds_read_b64_tr_b16 v[166:167], v222 offset:0x800
	ds_read_b64_tr_b16 v[168:169], v222 offset:0x1000
	ds_read_b64_tr_b16 v[170:171], v222 offset:0x1800
	ds_read_b64_tr_b16 v[186:187], v222 offset:0x2000
	ds_read_b64_tr_b16 v[188:189], v222 offset:0x2800
	ds_read_b64_tr_b16 v[190:191], v222 offset:0x3000
	ds_read_b64_tr_b16 v[192:193], v222 offset:0x3800
	s_waitcnt lgkmcnt(0)
	s_nop 0
	v_mfma_f32_32x32x16_bf16 v[0:15], v[136:139], v[164:167], v[0:15]
	ds_read_b64_tr_b16 v[164:165], v222 offset:0x200
	ds_read_b64_tr_b16 v[166:167], v222 offset:0xa00
	v_mfma_f32_32x32x16_bf16 v[0:15], v[140:143], v[168:171], v[0:15]
	ds_read_b64_tr_b16 v[168:169], v222 offset:0x1200
	ds_read_b64_tr_b16 v[170:171], v222 offset:0x1a00
	v_mfma_f32_32x32x16_bf16 v[0:15], v[144:147], v[186:189], v[0:15]
	ds_read_b64_tr_b16 v[186:187], v222 offset:0x2200
	ds_read_b64_tr_b16 v[188:189], v222 offset:0x2a00
	v_mfma_f32_32x32x16_bf16 v[0:15], v[148:151], v[190:193], v[0:15]
	ds_read_b64_tr_b16 v[190:191], v222 offset:0x3200
	ds_read_b64_tr_b16 v[192:193], v222 offset:0x3a00
	s_waitcnt lgkmcnt(0)
	v_mfma_f32_32x32x16_bf16 v[48:63], v[136:139], v[164:167], v[48:63]
	ds_read_b64_tr_b16 v[164:165], v222 offset:0x400
	ds_read_b64_tr_b16 v[166:167], v222 offset:0xc00
	v_mfma_f32_32x32x16_bf16 v[48:63], v[140:143], v[168:171], v[48:63]
	ds_read_b64_tr_b16 v[168:169], v222 offset:0x1400
	ds_read_b64_tr_b16 v[170:171], v222 offset:0x1c00
	v_mfma_f32_32x32x16_bf16 v[48:63], v[144:147], v[186:189], v[48:63]
	ds_read_b64_tr_b16 v[186:187], v222 offset:0x2400
	ds_read_b64_tr_b16 v[188:189], v222 offset:0x2c00
	v_mfma_f32_32x32x16_bf16 v[48:63], v[148:151], v[190:193], v[48:63]
	ds_read_b64_tr_b16 v[190:191], v222 offset:0x3400
	ds_read_b64_tr_b16 v[192:193], v222 offset:0x3c00
	s_waitcnt lgkmcnt(0)
	v_mfma_f32_32x32x16_bf16 v[32:47], v[136:139], v[164:167], v[32:47]
	ds_read_b64_tr_b16 v[164:165], v222 offset:0x600
	ds_read_b64_tr_b16 v[166:167], v222 offset:0xe00
	v_mfma_f32_32x32x16_bf16 v[32:47], v[140:143], v[168:171], v[32:47]
	ds_read_b64_tr_b16 v[168:169], v222 offset:0x1600
	ds_read_b64_tr_b16 v[170:171], v222 offset:0x1e00
	v_mfma_f32_32x32x16_bf16 v[32:47], v[144:147], v[186:189], v[32:47]
	ds_read_b64_tr_b16 v[186:187], v222 offset:0x2600
	ds_read_b64_tr_b16 v[188:189], v222 offset:0x2e00
	v_mfma_f32_32x32x16_bf16 v[32:47], v[148:151], v[190:193], v[32:47]
	ds_read_b64_tr_b16 v[190:191], v222 offset:0x3600
	ds_read_b64_tr_b16 v[192:193], v222 offset:0x3e00
	s_waitcnt lgkmcnt(0)
	v_mfma_f32_32x32x16_bf16 v[16:31], v[136:139], v[164:167], v[16:31]
	v_max_f32_e32 v136, v80, v81
	v_max3_f32 v136, v136, v82, v83
	v_max3_f32 v136, v136, v84, v85
	v_max3_f32 v136, v136, v86, v87
	v_max3_f32 v136, v136, v88, v89
	v_max3_f32 v136, v136, v90, v91
	v_max3_f32 v136, v136, v92, v93
	v_max3_f32 v136, v136, v94, v95
	v_mfma_f32_32x32x16_bf16 v[16:31], v[140:143], v[168:171], v[16:31]
	v_max3_f32 v136, v136, v64, v65
	v_max3_f32 v136, v136, v66, v67
	v_max3_f32 v136, v136, v68, v69
	v_max3_f32 v136, v136, v70, v71
	v_max3_f32 v136, v136, v72, v73
	v_max3_f32 v136, v136, v74, v75
	v_max3_f32 v136, v136, v76, v77
	v_max3_f32 v136, v136, v78, v79
	v_mfma_f32_32x32x16_bf16 v[16:31], v[144:147], v[186:189], v[16:31]
	v_mov_b32_e32 v137, v136
	s_nop 1
	v_permlane32_swap_b32_e32 v136, v137
	v_max_f32_e32 v136, v136, v137
	v_cmp_ge_f32_e32 vcc, s18, v136
	v_mfma_f32_32x32x16_bf16 v[16:31], v[148:151], v[190:193], v[16:31]
	s_cmp_eq_u64 vcc, exec
	s_cselect_b64 s[0:1], -1, 0
	s_cbranch_scc1 .Lattn_fast4
	v_max_f32_e32 v136, 0, v136
	v_exp_f32_e64 v137, -v136
	s_nop 0
.Lattn_fast4:
	v_cndmask_b32_e64 v141, v137, 1.0, s[0:1]
	v_cmp_gt_f32_e32 vcc, 1.0, v141
	s_cbranch_vccz .LBB0_100
	s_and_saveexec_b64 s[12:13], s[6:7]
	ds_write_b32 v173, v141 offset:128
	s_or_b64 exec, exec, s[12:13]
	s_waitcnt lgkmcnt(0)
	v_add_u32_e32 v137, v157, v156
	ds_read_b128 v[124:127], v137 offset:224
	ds_read_b128 v[128:131], v137 offset:192
	ds_read_b128 v[132:135], v137 offset:160
	ds_read_b128 v[142:145], v137 offset:128
	s_waitcnt lgkmcnt(3)
	v_pk_mul_f32 v[12:13], v[12:13], v[124:125]
	s_waitcnt lgkmcnt(2)
	v_pk_mul_f32 v[8:9], v[8:9], v[128:129]
	s_waitcnt lgkmcnt(1)
	v_pk_mul_f32 v[4:5], v[4:5], v[132:133]
	v_pk_mul_f32 v[14:15], v[14:15], v[126:127]
	v_pk_mul_f32 v[10:11], v[10:11], v[130:131]
	v_pk_mul_f32 v[6:7], v[6:7], v[134:135]
	s_waitcnt lgkmcnt(0)
; #define SBAR() __builtin_amdgcn_sched_barrier(0)
; #define SWRITE(b, i) do { *(bf16x8*)(V_lds + (b) * AT_SHM_V + vst0) = sr_[i].vs0; *(bf16x8*)(V_lds + (b) * AT_SHM_V + vst1) = sr_[i].vs1; \
;     *(bf16x8*)(K_lds + (b) * AT_SHM_K + kst) = sr_[i].ks0; } while (0)
; #define SWAIT() asm volatile("s_waitcnt vmcnt(3)" ::: "memory")
; #define RESC(a) do { if (__any((a) < 1.f)) { if (hi == 0) al_l[r32] = (a); asm volatile("s_waitcnt lgkmcnt(0)" ::: "memory"); \
;     for (int d = 0; d < 4; ++d) for (int r = 0; r < 16; ++r) o[d][r] *= al_l[crow(r, hi)]; } } while (0)
; DEV void partialSM(f32x16& p0, f32x16& p1, float& m_reg, float& mn, float& alpha) {
;   constexpr float C = AT_SCALE * 1.4426950408889634f;
;   float pmax = p0[0];
; #pragma unroll
;   for (int r = 1; r < 16; ++r) pmax = fmaxf(pmax, p0[r]);
; #pragma unroll
;   for (int r = 0; r < 16; ++r) pmax = fmaxf(pmax, p1[r]);
;   { auto rr = __builtin_amdgcn_permlane32_swap(__float_as_uint(pmax), __float_as_uint(pmax), false, false);
;     pmax = fmaxf(__uint_as_float(rr[0]), __uint_as_float(rr[1])); }
;   if (__builtin_expect(__all(pmax - m_reg <= AT_THR / AT_SCALE), 1)) { mn = m_reg; alpha = 1.f; }
;   else { mn = fmaxf(m_reg, pmax); alpha = __builtin_amdgcn_exp2f((m_reg - mn) * C); m_reg = mn; }
;   float mnC = -mn * C;
; #pragma unroll
;   for (int r = 0; r < 16; ++r) p0[r] = fmaf(p0[r], C, mnC);
; #pragma unroll
;   for (int r = 0; r < 16; ++r) p1[r] = fmaf(p1[r], C, mnC);
; #pragma unroll
;   for (int r = 0; r < 16; ++r) p0[r] = __builtin_amdgcn_exp2f(p0[r]);
; }
; DEV void attn_pass(const u16* __restrict__ Qb, const u16* __restrict__ Kh, const u16* __restrict__ Vh, int seq, f32x16* o, float* rli) {
;     ...
;     pv_d0(o, vb0 + b0 * AT_SHM_V, pa0, pa1, pa2, pa3); partialSM(pA0, pA1, m_reg, mnA, alA);
;     SWAIT(); SWRITE(b2, SO);
;     RESC(alA); __syncthreads();
;   }
;   { const int bl = (NT - 1) % 3, bp = (NT - 2) % 3;
;     SBAR(); qkt(pB0, pB1, K_lds + bl * AT_SHM_K, qr, r32, hi);
	v_pk_mul_f32 v[2:3], v[2:3], v[144:145]
	v_pk_mul_f32 v[0:1], v[0:1], v[142:143]
	v_pk_mul_f32 v[60:61], v[60:61], v[124:125]
	v_pk_mul_f32 v[56:57], v[56:57], v[128:129]
	v_pk_mul_f32 v[52:53], v[52:53], v[132:133]
	v_pk_mul_f32 v[62:63], v[62:63], v[126:127]
	v_pk_mul_f32 v[58:59], v[58:59], v[130:131]
	v_pk_mul_f32 v[54:55], v[54:55], v[134:135]
	v_pk_mul_f32 v[50:51], v[50:51], v[144:145]
	v_pk_mul_f32 v[48:49], v[48:49], v[142:143]
	v_pk_mul_f32 v[44:45], v[44:45], v[124:125]
	v_pk_mul_f32 v[40:41], v[40:41], v[128:129]
	v_pk_mul_f32 v[36:37], v[36:37], v[132:133]
	v_pk_mul_f32 v[46:47], v[46:47], v[126:127]
	v_pk_mul_f32 v[42:43], v[42:43], v[130:131]
	v_pk_mul_f32 v[38:39], v[38:39], v[134:135]
	v_pk_mul_f32 v[34:35], v[34:35], v[144:145]
	v_pk_mul_f32 v[32:33], v[32:33], v[142:143]
	v_pk_mul_f32 v[28:29], v[28:29], v[124:125]
	v_pk_mul_f32 v[24:25], v[24:25], v[128:129]
	v_pk_mul_f32 v[20:21], v[20:21], v[132:133]
	v_pk_mul_f32 v[30:31], v[30:31], v[126:127]
	v_pk_mul_f32 v[26:27], v[26:27], v[130:131]
	v_pk_mul_f32 v[22:23], v[22:23], v[134:135]
	v_pk_mul_f32 v[18:19], v[18:19], v[144:145]
	v_pk_mul_f32 v[16:17], v[16:17], v[142:143]
	v_sub_f32_e32 v80, v80, v136
	v_sub_f32_e32 v81, v81, v136
	v_sub_f32_e32 v82, v82, v136
	v_sub_f32_e32 v83, v83, v136
	v_sub_f32_e32 v84, v84, v136
	v_sub_f32_e32 v85, v85, v136
	v_sub_f32_e32 v86, v86, v136
	v_sub_f32_e32 v87, v87, v136
	v_sub_f32_e32 v88, v88, v136
	v_sub_f32_e32 v89, v89, v136
	v_sub_f32_e32 v90, v90, v136
	v_sub_f32_e32 v91, v91, v136
	v_sub_f32_e32 v92, v92, v136
	v_sub_f32_e32 v93, v93, v136
	v_sub_f32_e32 v94, v94, v136
	v_sub_f32_e32 v95, v95, v136
	v_sub_f32_e32 v64, v64, v136
	v_sub_f32_e32 v65, v65, v136
	v_sub_f32_e32 v66, v66, v136
	v_sub_f32_e32 v67, v67, v136
	v_sub_f32_e32 v68, v68, v136
	v_sub_f32_e32 v69, v69, v136
	v_sub_f32_e32 v70, v70, v136
	v_sub_f32_e32 v71, v71, v136
	v_sub_f32_e32 v72, v72, v136
	v_sub_f32_e32 v73, v73, v136
	v_sub_f32_e32 v74, v74, v136
	v_sub_f32_e32 v75, v75, v136
	v_sub_f32_e32 v76, v76, v136
	v_sub_f32_e32 v77, v77, v136
	v_sub_f32_e32 v78, v78, v136
	v_sub_f32_e32 v79, v79, v136
	v_sub_f32_e32 v236, v236, v136
	v_sub_f32_e32 v237, v237, v136
	v_sub_f32_e32 v238, v238, v136
	v_sub_f32_e32 v239, v239, v136
	v_sub_f32_e32 v240, v240, v136
	v_sub_f32_e32 v241, v241, v136
	v_sub_f32_e32 v242, v242, v136
	v_sub_f32_e32 v243, v243, v136
	v_sub_f32_e32 v244, v244, v136
	v_sub_f32_e32 v245, v245, v136
	v_sub_f32_e32 v246, v246, v136
	v_sub_f32_e32 v247, v247, v136
	v_sub_f32_e32 v248, v248, v136
	v_sub_f32_e32 v249, v249, v136
	v_sub_f32_e32 v250, v250, v136
	v_sub_f32_e32 v251, v251, v136
.LBB0_100:
	v_exp_f32_e32 v150, v80
	v_exp_f32_e32 v170, v81
	v_exp_f32_e32 v151, v82
	v_exp_f32_e32 v171, v83
	v_exp_f32_e32 v168, v84
	v_exp_f32_e32 v217, v85
	v_exp_f32_e32 v169, v86
	v_exp_f32_e32 v218, v87
	v_exp_f32_e32 v142, v88
	v_exp_f32_e32 v146, v89
	v_exp_f32_e32 v143, v90
	v_exp_f32_e32 v147, v91
	v_exp_f32_e32 v144, v92
	v_exp_f32_e32 v148, v93
	v_exp_f32_e32 v145, v94
	v_exp_f32_e32 v149, v95
	v_mov_b64_e32 v[138:139], v[64:65]
	v_add_f32_e32 v64, v214, v215
	s_mov_b64 s[0:1], 0x4000
	v_fmac_f32_e32 v64, v185, v174
	v_add_f32_e32 v174, v219, v220
	v_lshl_add_u64 v[158:159], v[158:159], 0, s[0:1]
	s_mov_b64 s[0:1], 0x8000
	v_mov_b64_e32 v[136:137], v[66:67]
	v_mov_b64_e32 v[134:135], v[68:69]
	v_mov_b64_e32 v[132:133], v[70:71]
	v_mov_b64_e32 v[130:131], v[72:73]
	v_mov_b64_e32 v[128:129], v[74:75]
	v_mov_b64_e32 v[126:127], v[76:77]
	v_mov_b64_e32 v[124:125], v[78:79]
	v_fmac_f32_e32 v174, v64, v216
	s_addk_i32 s14, 0x4000
	s_add_i32 s46, s46, 2
	s_add_i32 s48, s48, 2
	s_add_i32 s9, s9, 2
	s_add_i32 s8, s8, 0x8000
	v_lshl_add_u64 v[160:161], v[160:161], 0, s[0:1]
	s_add_i32 s64, s64, 2
	s_add_i32 s47, s47, 2
	s_and_b64 vcc, exec, s[10:11]
	s_waitcnt lgkmcnt(0)
	s_barrier
	s_cbranch_vccnz .LBB0_102
	v_mov_b32_e32 v185, v141
	s_branch .LBB0_90
.LBB0_102:
	v_mov_b32_e32 v140, 0
	v_or_b32_e32 v64, v179, v180
	v_or3_b32 v64, v64, v181, v182
	v_add_u32_e32 v112, 0, v64
	v_add_u32_e32 v68, s45, v175
	ds_read_b128 v[64:67], v68 offset:49152
	ds_read_b128 v[68:71], v68 offset:53248
	v_add_u32_e32 v113, s45, v178
	v_exp_f32_e32 v118, v129
	v_exp_f32_e32 v119, v126
	s_waitcnt lgkmcnt(1)
	v_mfma_f32_32x32x16_bf16 v[80:95], v[64:67], v[108:111], v[236:251]
	v_exp_f32_e32 v120, v127
	v_exp_f32_e32 v121, v124
	v_exp_f32_e32 v122, v125
	s_waitcnt lgkmcnt(0)
	v_mfma_f32_32x32x16_bf16 v[64:79], v[68:71], v[108:111], v[236:251]
	ds_read_b128 v[108:111], v113 offset:49152
	ds_read_b128 v[114:117], v113 offset:53248
	v_exp_f32_e32 v113, v132
	s_waitcnt lgkmcnt(1)
	v_mfma_f32_32x32x16_bf16 v[80:95], v[108:111], v[104:107], v[80:95]
	v_add_u32_e32 v108, s45, v177
	s_waitcnt lgkmcnt(0)
	v_mfma_f32_32x32x16_bf16 v[64:79], v[114:117], v[104:107], v[64:79]
	ds_read_b128 v[104:107], v108 offset:49152
	ds_read_b128 v[108:111], v108 offset:53248
	v_exp_f32_e32 v114, v133
	v_exp_f32_e32 v115, v130
	v_exp_f32_e32 v116, v131
	v_exp_f32_e32 v117, v128
	s_waitcnt lgkmcnt(1)
	v_mfma_f32_32x32x16_bf16 v[80:95], v[104:107], v[100:103], v[80:95]
	v_add_u32_e32 v104, s45, v176
	s_waitcnt lgkmcnt(0)
	v_mfma_f32_32x32x16_bf16 v[64:79], v[108:111], v[100:103], v[64:79]
	ds_read_b128 v[100:103], v104 offset:49152
	ds_read_b128 v[104:107], v104 offset:53248
	v_exp_f32_e32 v108, v136
	v_exp_f32_e32 v109, v137
	v_exp_f32_e32 v110, v134
	v_exp_f32_e32 v111, v135
	s_waitcnt lgkmcnt(1)
	v_mfma_f32_32x32x16_bf16 v[80:95], v[100:103], v[96:99], v[80:95]
	v_cvt_pk_bf16_f32 v100, v168, v217
	v_cvt_pk_bf16_f32 v101, v169, v218
	v_cvt_pk_bf16_f32 v102, v142, v146
	v_cvt_pk_bf16_f32 v103, v143, v147
	s_waitcnt lgkmcnt(0)
; #define SBAR() __builtin_amdgcn_sched_barrier(0)
; #define RESC(a) do { if (__any((a) < 1.f)) { if (hi == 0) al_l[r32] = (a); asm volatile("s_waitcnt lgkmcnt(0)" ::: "memory"); \
;     for (int d = 0; d < 4; ++d) for (int r = 0; r < 16; ++r) o[d][r] *= al_l[crow(r, hi)]; } } while (0)
; DEV void partialSM(f32x16& p0, f32x16& p1, float& m_reg, float& mn, float& alpha) {
;   constexpr float C = AT_SCALE * 1.4426950408889634f;
;   float pmax = p0[0];
; #pragma unroll
;   for (int r = 1; r < 16; ++r) pmax = fmaxf(pmax, p0[r]);
; #pragma unroll
;   for (int r = 0; r < 16; ++r) pmax = fmaxf(pmax, p1[r]);
;   { auto rr = __builtin_amdgcn_permlane32_swap(__float_as_uint(pmax), __float_as_uint(pmax), false, false);
;     pmax = fmaxf(__uint_as_float(rr[0]), __uint_as_float(rr[1])); }
;   if (__builtin_expect(__all(pmax - m_reg <= AT_THR / AT_SCALE), 1)) { mn = m_reg; alpha = 1.f; }
;   else { mn = fmaxf(m_reg, pmax); alpha = __builtin_amdgcn_exp2f((m_reg - mn) * C); m_reg = mn; }
;   float mnC = -mn * C;
; #pragma unroll
;   for (int r = 0; r < 16; ++r) p0[r] = fmaf(p0[r], C, mnC);
; #pragma unroll
;   for (int r = 0; r < 16; ++r) p1[r] = fmaf(p1[r], C, mnC);
; #pragma unroll
;   for (int r = 0; r < 16; ++r) p0[r] = __builtin_amdgcn_exp2f(p0[r]);
; }
; DEV void finishSM(f32x16& p0, f32x16& p1, float alpha, float& l_reg, bf16x8& pa0, bf16x8& pa1, bf16x8& pa2, bf16x8& pa3) {
; #pragma unroll
;   for (int r = 0; r < 16; ++r) p1[r] = __builtin_amdgcn_exp2f(p1[r]);
;   float ps = 0;
; #pragma unroll
;   for (int r = 0; r < 16; ++r) ps += p0[r];
; #pragma unroll
;   for (int r = 0; r < 16; ++r) ps += p1[r];
;   { auto rr = __builtin_amdgcn_permlane32_swap(__float_as_uint(ps), __float_as_uint(ps), false, false);
;     ps = __uint_as_float(rr[0]) + __uint_as_float(rr[1]); }
;   l_reg = l_reg * alpha + ps;
;     ...
;   PK4(p0, 0, pa0); PK4(p0, 8, pa1); PK4(p1, 0, pa2); PK4(p1, 8, pa3);
;     ...
; }
; DEV void attn_pass(const u16* __restrict__ Qb, const u16* __restrict__ Kh, const u16* __restrict__ Vh, int seq, f32x16* o, float* rli) {
;     ...
;   { const int bl = (NT - 1) % 3, bp = (NT - 2) % 3;
;     SBAR(); qkt(pB0, pB1, K_lds + bl * AT_SHM_K, qr, r32, hi);
;     finishSM(pA0, pA1, alA, l_reg, pa0, pa1, pa2, pa3); SBAR();
;     pv_d0(o, vb0 + bp * AT_SHM_V, pa0, pa1, pa2, pa3); partialSM(pB0, pB1, m_reg, mnB, alB);
;     RESC(alB);
	v_mfma_f32_32x32x16_bf16 v[64:79], v[104:107], v[96:99], v[64:79]
	v_add_f32_e32 v96, v170, v150
	v_add_f32_e32 v96, v151, v96
	v_add_f32_e32 v96, v171, v96
	v_add_f32_e32 v96, v168, v96
	v_add_f32_e32 v96, v217, v96
	v_add_f32_e32 v96, v169, v96
	v_add_f32_e32 v96, v218, v96
	v_add_f32_e32 v96, v142, v96
	v_add_f32_e32 v96, v146, v96
	v_add_f32_e32 v96, v143, v96
	v_add_f32_e32 v96, v147, v96
	v_exp_f32_e32 v106, v138
	v_add_f32_e32 v96, v144, v96
	v_exp_f32_e32 v107, v139
	v_add_f32_e32 v96, v148, v96
	v_add_f32_e32 v96, v145, v96
	v_add_f32_e32 v96, v149, v96
	v_add_f32_e32 v96, v106, v96
	v_add_f32_e32 v96, v107, v96
	v_add_f32_e32 v96, v108, v96
	v_add_f32_e32 v96, v109, v96
	v_add_f32_e32 v96, v110, v96
	v_add_f32_e32 v96, v111, v96
	v_add_f32_e32 v96, v113, v96
	v_add_f32_e32 v96, v114, v96
	v_add_f32_e32 v96, v115, v96
	v_add_f32_e32 v96, v116, v96
	v_add_f32_e32 v96, v117, v96
	v_add_f32_e32 v96, v118, v96
	v_add_f32_e32 v96, v119, v96
	v_add_f32_e32 v96, v120, v96
	v_add_f32_e32 v96, v121, v96
	v_add_f32_e32 v96, v122, v96
	v_mov_b32_e32 v97, v96
	v_cvt_pk_bf16_f32 v98, v150, v170
	v_cvt_pk_bf16_f32 v99, v151, v171
	s_nop 1
	v_permlane32_swap_b32_e32 v96, v97
	v_permlane32_swap_b32_e32 v98, v100
	v_permlane32_swap_b32_e32 v99, v101
	v_cvt_pk_bf16_f32 v104, v144, v148
	v_cvt_pk_bf16_f32 v105, v145, v149
	v_cvt_pk_bf16_f32 v106, v106, v107
	v_cvt_pk_bf16_f32 v107, v108, v109
	v_cvt_pk_bf16_f32 v108, v110, v111
	v_cvt_pk_bf16_f32 v109, v113, v114
	v_cvt_pk_bf16_f32 v114, v115, v116
	v_cvt_pk_bf16_f32 v115, v117, v118
	v_cvt_pk_bf16_f32 v116, v119, v120
	v_cvt_pk_bf16_f32 v117, v121, v122
	s_nop 0
	v_permlane32_swap_b32_e32 v102, v104
	v_permlane32_swap_b32_e32 v103, v105
	v_permlane32_swap_b32_e32 v106, v108
	v_permlane32_swap_b32_e32 v107, v109
	v_permlane32_swap_b32_e32 v114, v116
	v_permlane32_swap_b32_e32 v115, v117
	v_add_u32_e32 v110, s50, v112
	ds_read_b64_tr_b16 v[118:119], v110 offset:0
	ds_read_b64_tr_b16 v[120:121], v110 offset:0x800
	ds_read_b64_tr_b16 v[122:123], v110 offset:0x1000
	ds_read_b64_tr_b16 v[124:125], v110 offset:0x1800
	ds_read_b64_tr_b16 v[126:127], v110 offset:0x2000
	ds_read_b64_tr_b16 v[128:129], v110 offset:0x2800
	ds_read_b64_tr_b16 v[130:131], v110 offset:0x3000
	ds_read_b64_tr_b16 v[132:133], v110 offset:0x3800
	s_waitcnt lgkmcnt(0)
	s_nop 0
	v_mfma_f32_32x32x16_bf16 v[0:15], v[98:101], v[118:121], v[0:15]
	ds_read_b64_tr_b16 v[118:119], v110 offset:0x200
	ds_read_b64_tr_b16 v[120:121], v110 offset:0xa00
	v_mfma_f32_32x32x16_bf16 v[0:15], v[102:105], v[122:125], v[0:15]
	ds_read_b64_tr_b16 v[122:123], v110 offset:0x1200
	ds_read_b64_tr_b16 v[124:125], v110 offset:0x1a00
	v_mfma_f32_32x32x16_bf16 v[0:15], v[106:109], v[126:129], v[0:15]
	ds_read_b64_tr_b16 v[126:127], v110 offset:0x2200
	ds_read_b64_tr_b16 v[128:129], v110 offset:0x2a00
	v_mfma_f32_32x32x16_bf16 v[0:15], v[114:117], v[130:133], v[0:15]
	ds_read_b64_tr_b16 v[130:131], v110 offset:0x3200
	ds_read_b64_tr_b16 v[132:133], v110 offset:0x3a00
	s_waitcnt lgkmcnt(0)
	v_mfma_f32_32x32x16_bf16 v[48:63], v[98:101], v[118:121], v[48:63]
	ds_read_b64_tr_b16 v[118:119], v110 offset:0x400
	ds_read_b64_tr_b16 v[120:121], v110 offset:0xc00
	v_mfma_f32_32x32x16_bf16 v[48:63], v[102:105], v[122:125], v[48:63]
	ds_read_b64_tr_b16 v[122:123], v110 offset:0x1400
	ds_read_b64_tr_b16 v[124:125], v110 offset:0x1c00
	v_mfma_f32_32x32x16_bf16 v[48:63], v[106:109], v[126:129], v[48:63]
	ds_read_b64_tr_b16 v[126:127], v110 offset:0x2400
	ds_read_b64_tr_b16 v[128:129], v110 offset:0x2c00
	v_mfma_f32_32x32x16_bf16 v[48:63], v[114:117], v[130:133], v[48:63]
	ds_read_b64_tr_b16 v[130:131], v110 offset:0x3400
	ds_read_b64_tr_b16 v[132:133], v110 offset:0x3c00
	s_waitcnt lgkmcnt(0)
	v_mfma_f32_32x32x16_bf16 v[32:47], v[98:101], v[118:121], v[32:47]
	ds_read_b64_tr_b16 v[118:119], v110 offset:0x600
	ds_read_b64_tr_b16 v[120:121], v110 offset:0xe00
	v_mfma_f32_32x32x16_bf16 v[32:47], v[102:105], v[122:125], v[32:47]
	ds_read_b64_tr_b16 v[122:123], v110 offset:0x1600
	ds_read_b64_tr_b16 v[124:125], v110 offset:0x1e00
	v_mfma_f32_32x32x16_bf16 v[32:47], v[106:109], v[126:129], v[32:47]
	ds_read_b64_tr_b16 v[126:127], v110 offset:0x2600
	ds_read_b64_tr_b16 v[128:129], v110 offset:0x2e00
	v_mfma_f32_32x32x16_bf16 v[32:47], v[114:117], v[130:133], v[32:47]
	ds_read_b64_tr_b16 v[130:131], v110 offset:0x3600
	ds_read_b64_tr_b16 v[132:133], v110 offset:0x3e00
	s_waitcnt lgkmcnt(0)
	v_mfma_f32_32x32x16_bf16 v[16:31], v[98:101], v[118:121], v[16:31]
	v_max_f32_e32 v98, v81, v81
	v_max_f32_e32 v99, v80, v80
	v_max_f32_e32 v98, v99, v98
	v_max3_f32 v98, v98, v82, v83
	v_max3_f32 v98, v98, v84, v85
	v_max3_f32 v98, v98, v86, v87
	v_max3_f32 v98, v98, v88, v89
	v_max3_f32 v98, v98, v90, v91
	v_max3_f32 v98, v98, v92, v93
	v_mfma_f32_32x32x16_bf16 v[16:31], v[102:105], v[122:125], v[16:31]
	v_max3_f32 v98, v98, v94, v95
	v_max3_f32 v98, v98, v64, v65
	v_max3_f32 v98, v98, v66, v67
	v_max3_f32 v98, v98, v68, v69
	v_max3_f32 v98, v98, v70, v71
	v_max3_f32 v98, v98, v72, v73
	v_max3_f32 v98, v98, v74, v75
	v_max3_f32 v98, v98, v76, v77
	v_mfma_f32_32x32x16_bf16 v[16:31], v[106:109], v[126:129], v[16:31]
	v_max3_f32 v98, v98, v78, v79
	v_mov_b32_e32 v99, v98
	s_nop 1
	v_permlane32_swap_b32_e32 v98, v99
	v_max_f32_e32 v99, v99, v99
	v_max_f32_e32 v98, v98, v98
	v_max_f32_e32 v98, v98, v99
	v_sub_f32_e32 v99, v98, v140
	v_cmp_ge_f32_e32 vcc, s18, v99
	v_max_f32_e32 v99, v140, v140
	v_max_f32_e32 v99, v99, v98
	v_mfma_f32_32x32x16_bf16 v[16:31], v[114:117], v[130:133], v[16:31]
	v_sub_f32_e32 v98, v140, v99
	v_mul_f32_e32 v98, 0x3f800000, v98
	v_exp_f32_e32 v98, v98
	s_cmp_eq_u64 vcc, exec
	s_cselect_b64 s[0:1], -1, 0
	v_cndmask_b32_e64 v98, v98, 1.0, s[0:1]
	v_cmp_gt_f32_e32 vcc, 1.0, v98
	s_cbranch_vccz .LBB0_106
; #define SBAR() __builtin_amdgcn_sched_barrier(0)
; #define RESC(a) do { if (__any((a) < 1.f)) { if (hi == 0) al_l[r32] = (a); asm volatile("s_waitcnt lgkmcnt(0)" ::: "memory"); \
;     for (int d = 0; d < 4; ++d) for (int r = 0; r < 16; ++r) o[d][r] *= al_l[crow(r, hi)]; } } while (0)
; DEV void attn_pass(const u16* __restrict__ Qb, const u16* __restrict__ Kh, const u16* __restrict__ Vh, int seq, f32x16* o, float* rli) {
;     ...
;   { const int bl = (NT - 1) % 3, bp = (NT - 2) % 3;
;     SBAR(); qkt(pB0, pB1, K_lds + bl * AT_SHM_K, qr, r32, hi);
;     finishSM(pA0, pA1, alA, l_reg, pa0, pa1, pa2, pa3); SBAR();
;     pv_d0(o, vb0 + bp * AT_SHM_V, pa0, pa1, pa2, pa3); partialSM(pB0, pB1, m_reg, mnB, alB);
;     RESC(alB);
;     finishSM(pB0, pB1, alB, l_reg, pa0, pa1, pa2, pa3); SBAR();
	s_mov_b64 s[8:9], exec
	s_and_b64 s[10:11], s[8:9], s[6:7]
	s_movk_i32 s45, 0x2000
	v_mov_b32_e32 v175, v235
	v_mov_b32_e32 v176, 0xb9500d01
	v_mov_b32_e32 v178, 0x37d00d01
	v_mov_b32_e32 v177, 0x7f800000
	s_mov_b64 exec, s[10:11]
	ds_write_b32 v173, v98 offset:128
	s_or_b64 exec, exec, s[8:9]
	s_waitcnt lgkmcnt(0)
	v_add_u32_e32 v113, v157, v156
	ds_read_b128 v[100:103], v113 offset:224
	ds_read_b128 v[104:107], v113 offset:192
	ds_read_b128 v[108:111], v113 offset:160
	ds_read_b128 v[114:117], v113 offset:128
	s_waitcnt lgkmcnt(3)
	v_pk_mul_f32 v[12:13], v[12:13], v[100:101]
	s_waitcnt lgkmcnt(2)
	v_pk_mul_f32 v[8:9], v[8:9], v[104:105]
	s_waitcnt lgkmcnt(1)
	v_pk_mul_f32 v[4:5], v[4:5], v[108:109]
	v_pk_mul_f32 v[14:15], v[14:15], v[102:103]
	v_pk_mul_f32 v[10:11], v[10:11], v[106:107]
	v_pk_mul_f32 v[6:7], v[6:7], v[110:111]
	s_waitcnt lgkmcnt(0)
	v_pk_mul_f32 v[2:3], v[2:3], v[116:117]
	v_pk_mul_f32 v[0:1], v[0:1], v[114:115]
	v_pk_mul_f32 v[60:61], v[60:61], v[100:101]
	v_pk_mul_f32 v[56:57], v[56:57], v[104:105]
	v_pk_mul_f32 v[52:53], v[52:53], v[108:109]
	v_pk_mul_f32 v[62:63], v[62:63], v[102:103]
	v_pk_mul_f32 v[58:59], v[58:59], v[106:107]
	v_pk_mul_f32 v[54:55], v[54:55], v[110:111]
	v_pk_mul_f32 v[50:51], v[50:51], v[116:117]
	v_pk_mul_f32 v[48:49], v[48:49], v[114:115]
	v_pk_mul_f32 v[44:45], v[44:45], v[100:101]
	v_pk_mul_f32 v[40:41], v[40:41], v[104:105]
	v_pk_mul_f32 v[36:37], v[36:37], v[108:109]
	v_pk_mul_f32 v[46:47], v[46:47], v[102:103]
	v_pk_mul_f32 v[42:43], v[42:43], v[106:107]
	v_pk_mul_f32 v[38:39], v[38:39], v[110:111]
	v_pk_mul_f32 v[34:35], v[34:35], v[116:117]
	v_pk_mul_f32 v[32:33], v[32:33], v[114:115]
	v_pk_mul_f32 v[28:29], v[28:29], v[100:101]
	v_pk_mul_f32 v[24:25], v[24:25], v[104:105]
	v_pk_mul_f32 v[20:21], v[20:21], v[108:109]
	v_pk_mul_f32 v[30:31], v[30:31], v[102:103]
	v_pk_mul_f32 v[26:27], v[26:27], v[106:107]
	v_pk_mul_f32 v[22:23], v[22:23], v[110:111]
	v_pk_mul_f32 v[18:19], v[18:19], v[116:117]
	v_pk_mul_f32 v[16:17], v[16:17], v[114:115]
	s_branch .LBB0_107
.LBB0_106:
	s_movk_i32 s45, 0x2000
	v_mov_b32_e32 v175, v235
	v_mov_b32_e32 v176, 0xb9500d01
	v_mov_b32_e32 v178, 0x37d00d01
	v_mov_b32_e32 v177, 0x7f800000
; DEV void finishSM(f32x16& p0, f32x16& p1, float alpha, float& l_reg, bf16x8& pa0, bf16x8& pa1, bf16x8& pa2, bf16x8& pa3) {
; #pragma unroll
;   for (int r = 0; r < 16; ++r) p1[r] = __builtin_amdgcn_exp2f(p1[r]);
;   float ps = 0;
; #pragma unroll
;   for (int r = 0; r < 16; ++r) ps += p0[r];
; #pragma unroll
;   for (int r = 0; r < 16; ++r) ps += p1[r];
;   { auto rr = __builtin_amdgcn_permlane32_swap(__float_as_uint(ps), __float_as_uint(ps), false, false);
;     ps = __uint_as_float(rr[0]) + __uint_as_float(rr[1]); }
;   l_reg = l_reg * alpha + ps;
;     ...
;   PK4(p0, 0, pa0); PK4(p0, 8, pa1); PK4(p1, 0, pa2); PK4(p1, 8, pa3);
;     ...
; }
; DEV void qkt(f32x16& p0, f32x16& p1, const char* Ks, const bf16x8* qr, int r32, int hi) {
;   p0 = f32x16{}; p1 = f32x16{};
; #pragma unroll
;   for (int d0 = 0; d0 < 4; ++d0) { int cb = (d0 * 16 + hi * 8) * 2;
;     bf16x8 b0 = *reinterpret_cast<const bf16x8*>(Ks + KSWZ64(r32, cb));
;     bf16x8 b1 = *reinterpret_cast<const bf16x8*>(Ks + KSWZ64(32 + r32, cb));
;     p0 = __builtin_amdgcn_mfma_f32_32x32x16_bf16(b0, qr[d0], p0, 0, 0, 0);
;     p1 = __builtin_amdgcn_mfma_f32_32x32x16_bf16(b1, qr[d0], p1, 0, 0, 0); }
; }
; DEV int v_st(int k, int c) { const int kk = (k & ~0xC) | ((k & 4) << 1) | ((k & 8) >> 1); return ((kk >> 3) * 4 + (c >> 5)) * 512 + ((kk & 7) * 32 + (c & 31)) * 2; }
; DEV int v_rd_base(int lane) { return ((lane & 3) << 3) | (((lane >> 2) & 3) << 6) | (((lane >> 4) & 1) << 5) | (((lane >> 5) & 1) << 8); }
; template <int OFF> DEV s16x4 tr_read(int vb) {
;   s16x4 r; asm volatile("ds_read_b64_tr_b16 %0, %1 offset:%2" : "=&v"(r) : "v"(vb), "i"(OFF) : "memory"); return r;
; }
; template <int D0> DEV void pv_one(f32x16& od, int vb, bf16x8 pa0, bf16x8 pa1, bf16x8 pa2, bf16x8 pa3) {
;   const s16x4 l0 = tr_read<v_rd_off(D0, 0, 0)>(vb), h0 = tr_read<v_rd_off(D0, 0, 1)>(vb), l1 = tr_read<v_rd_off(D0, 1, 0)>(vb), h1 = tr_read<v_rd_off(D0, 1, 1)>(vb);
;   const s16x4 l2 = tr_read<v_rd_off(D0, 2, 0)>(vb), h2 = tr_read<v_rd_off(D0, 2, 1)>(vb), l3 = tr_read<v_rd_off(D0, 3, 0)>(vb), h3 = tr_read<v_rd_off(D0, 3, 1)>(vb);
;   asm volatile("s_waitcnt lgkmcnt(0)" ::: "memory"); SBAR();
;     ...
;   od = __builtin_amdgcn_mfma_f32_32x32x16_bf16(pa0, PK(l0, h0), od, 0, 0, 0);
;   od = __builtin_amdgcn_mfma_f32_32x32x16_bf16(pa1, PK(l1, h1), od, 0, 0, 0);
;   od = __builtin_amdgcn_mfma_f32_32x32x16_bf16(pa2, PK(l2, h2), od, 0, 0, 0);
.LBB0_107:
	v_cndmask_b32_e64 v99, v99, v140, s[0:1]
	v_mul_f32_e32 v99, 0xbf800000, v99
	v_fmamk_f32 v80, v80, 0x3f800000, v99
	v_fmamk_f32 v81, v81, 0x3f800000, v99
	v_fmamk_f32 v82, v82, 0x3f800000, v99
	v_fmamk_f32 v83, v83, 0x3f800000, v99
	v_fmamk_f32 v84, v84, 0x3f800000, v99
	v_fmamk_f32 v85, v85, 0x3f800000, v99
	v_fmamk_f32 v86, v86, 0x3f800000, v99
	v_fmamk_f32 v87, v87, 0x3f800000, v99
	v_fmamk_f32 v88, v88, 0x3f800000, v99
	v_fmamk_f32 v89, v89, 0x3f800000, v99
	v_fmamk_f32 v90, v90, 0x3f800000, v99
	v_fmamk_f32 v91, v91, 0x3f800000, v99
	v_fmamk_f32 v92, v92, 0x3f800000, v99
	v_fmamk_f32 v93, v93, 0x3f800000, v99
	v_fmamk_f32 v94, v94, 0x3f800000, v99
	v_fmamk_f32 v95, v95, 0x3f800000, v99
	v_fmamk_f32 v64, v64, 0x3f800000, v99
	v_fmamk_f32 v65, v65, 0x3f800000, v99
	v_fmamk_f32 v66, v66, 0x3f800000, v99
	v_fmamk_f32 v67, v67, 0x3f800000, v99
	v_fmamk_f32 v68, v68, 0x3f800000, v99
	v_fmamk_f32 v69, v69, 0x3f800000, v99
	v_fmamk_f32 v70, v70, 0x3f800000, v99
	v_fmamk_f32 v71, v71, 0x3f800000, v99
	v_fmamk_f32 v72, v72, 0x3f800000, v99
	v_fmamk_f32 v73, v73, 0x3f800000, v99
	v_fmamk_f32 v74, v74, 0x3f800000, v99
	v_fmamk_f32 v75, v75, 0x3f800000, v99
	v_fmamk_f32 v76, v76, 0x3f800000, v99
	v_fmamk_f32 v77, v77, 0x3f800000, v99
	v_fmamk_f32 v78, v78, 0x3f800000, v99
	v_fmac_f32_e32 v99, 0x3f800000, v79
	v_exp_f32_e32 v79, v80
	v_exp_f32_e32 v80, v81
	v_exp_f32_e32 v81, v82
	v_exp_f32_e32 v82, v83
	v_exp_f32_e32 v83, v84
	v_exp_f32_e32 v84, v85
	v_exp_f32_e32 v85, v86
	v_exp_f32_e32 v86, v87
	v_exp_f32_e32 v87, v88
	v_exp_f32_e32 v88, v89
	v_exp_f32_e32 v89, v90
	v_exp_f32_e32 v90, v91
	v_exp_f32_e32 v91, v92
	v_exp_f32_e32 v92, v93
	v_exp_f32_e32 v93, v94
	v_exp_f32_e32 v94, v95
	v_exp_f32_e32 v95, v64
	v_add_f32_e32 v64, 0, v79
	v_add_f32_e32 v64, v80, v64
	v_add_f32_e32 v64, v81, v64
	v_add_f32_e32 v64, v82, v64
	v_add_f32_e32 v64, v83, v64
	v_add_f32_e32 v64, v84, v64
	v_add_f32_e32 v64, v85, v64
	v_add_f32_e32 v64, v86, v64
	v_add_f32_e32 v64, v87, v64
	v_add_f32_e32 v64, v88, v64
	v_add_f32_e32 v64, v89, v64
	v_add_f32_e32 v64, v90, v64
	v_add_f32_e32 v64, v91, v64
	v_exp_f32_e32 v100, v65
	v_add_f32_e32 v64, v92, v64
	v_exp_f32_e32 v101, v66
	v_add_f32_e32 v64, v93, v64
	v_exp_f32_e32 v102, v67
	v_add_f32_e32 v64, v94, v64
	v_exp_f32_e32 v103, v68
	v_add_f32_e32 v64, v95, v64
	v_exp_f32_e32 v104, v69
	v_add_f32_e32 v64, v100, v64
	v_exp_f32_e32 v105, v70
	v_add_f32_e32 v64, v101, v64
	v_exp_f32_e32 v106, v71
	v_add_f32_e32 v64, v102, v64
	v_exp_f32_e32 v107, v72
	v_add_f32_e32 v64, v103, v64
	v_exp_f32_e32 v108, v73
	v_add_f32_e32 v64, v104, v64
	v_exp_f32_e32 v109, v74
	v_add_f32_e32 v64, v105, v64
	v_exp_f32_e32 v110, v75
	v_add_f32_e32 v64, v106, v64
	v_exp_f32_e32 v111, v76
	v_add_f32_e32 v64, v107, v64
	v_exp_f32_e32 v113, v77
	v_add_f32_e32 v64, v108, v64
	v_exp_f32_e32 v114, v78
	v_add_f32_e32 v64, v109, v64
	v_exp_f32_e32 v99, v99
	v_add_f32_e32 v64, v110, v64
	v_add_f32_e32 v64, v111, v64
	v_add_f32_e32 v64, v113, v64
	v_add_f32_e32 v64, v114, v64
	v_add_f32_e32 v64, v99, v64
	v_mov_b32_e32 v65, v64
	s_nop 1
	v_permlane32_swap_b32_e32 v64, v65
	v_cvt_pk_bf16_f32 v66, v79, v80
	v_cvt_pk_bf16_f32 v67, v81, v82
	v_cvt_pk_bf16_f32 v68, v83, v84
	v_cvt_pk_bf16_f32 v69, v85, v86
	v_cvt_pk_bf16_f32 v70, v87, v88
	v_cvt_pk_bf16_f32 v71, v89, v90
	v_cvt_pk_bf16_f32 v72, v91, v92
	v_cvt_pk_bf16_f32 v73, v93, v94
	v_cvt_pk_bf16_f32 v74, v95, v100
	v_cvt_pk_bf16_f32 v75, v101, v102
	v_cvt_pk_bf16_f32 v76, v103, v104
	v_cvt_pk_bf16_f32 v77, v105, v106
	v_cvt_pk_bf16_f32 v78, v107, v108
	v_cvt_pk_bf16_f32 v79, v109, v110
	v_cvt_pk_bf16_f32 v80, v111, v113
	v_cvt_pk_bf16_f32 v81, v114, v99
	s_nop 0
	v_permlane32_swap_b32_e32 v66, v68
	v_permlane32_swap_b32_e32 v67, v69
	v_permlane32_swap_b32_e32 v70, v72
	v_permlane32_swap_b32_e32 v71, v73
	v_permlane32_swap_b32_e32 v74, v76
	v_permlane32_swap_b32_e32 v75, v77
	v_permlane32_swap_b32_e32 v78, v80
	v_permlane32_swap_b32_e32 v79, v81
	v_add_u32_e32 v94, s51, v112
	ds_read_b64_tr_b16 v[82:83], v94 offset:0
	ds_read_b64_tr_b16 v[84:85], v94 offset:0x800
	ds_read_b64_tr_b16 v[86:87], v94 offset:0x1000
	ds_read_b64_tr_b16 v[88:89], v94 offset:0x1800
	ds_read_b64_tr_b16 v[90:91], v94 offset:0x2000
	ds_read_b64_tr_b16 v[92:93], v94 offset:0x2800
	ds_read_b64_tr_b16 v[100:101], v94 offset:0x3000
	ds_read_b64_tr_b16 v[102:103], v94 offset:0x3800
	s_waitcnt lgkmcnt(0)
	s_nop 0
	v_mfma_f32_32x32x16_bf16 v[0:15], v[66:69], v[82:85], v[0:15]
	ds_read_b64_tr_b16 v[82:83], v94 offset:0x200
	ds_read_b64_tr_b16 v[84:85], v94 offset:0xa00
	v_mfma_f32_32x32x16_bf16 v[0:15], v[70:73], v[86:89], v[0:15]
	ds_read_b64_tr_b16 v[86:87], v94 offset:0x1200
	ds_read_b64_tr_b16 v[88:89], v94 offset:0x1a00
	v_mfma_f32_32x32x16_bf16 v[0:15], v[74:77], v[90:93], v[0:15]
	ds_read_b64_tr_b16 v[90:91], v94 offset:0x2200
	ds_read_b64_tr_b16 v[92:93], v94 offset:0x2a00
	v_mfma_f32_32x32x16_bf16 v[0:15], v[78:81], v[100:103], v[0:15]
	ds_read_b64_tr_b16 v[100:101], v94 offset:0x3200
	ds_read_b64_tr_b16 v[102:103], v94 offset:0x3a00
	s_waitcnt lgkmcnt(0)
	v_mfma_f32_32x32x16_bf16 v[48:63], v[66:69], v[82:85], v[48:63]
	ds_read_b64_tr_b16 v[82:83], v94 offset:0x400
	ds_read_b64_tr_b16 v[84:85], v94 offset:0xc00
	v_mfma_f32_32x32x16_bf16 v[48:63], v[70:73], v[86:89], v[48:63]
	ds_read_b64_tr_b16 v[86:87], v94 offset:0x1400
	ds_read_b64_tr_b16 v[88:89], v94 offset:0x1c00
	v_mfma_f32_32x32x16_bf16 v[48:63], v[74:77], v[90:93], v[48:63]
	ds_read_b64_tr_b16 v[90:91], v94 offset:0x2400
	ds_read_b64_tr_b16 v[92:93], v94 offset:0x2c00
	v_mfma_f32_32x32x16_bf16 v[48:63], v[78:81], v[100:103], v[48:63]
	ds_read_b64_tr_b16 v[100:101], v94 offset:0x3400
	ds_read_b64_tr_b16 v[102:103], v94 offset:0x3c00
	s_waitcnt lgkmcnt(0)
	v_mfma_f32_32x32x16_bf16 v[32:47], v[66:69], v[82:85], v[32:47]
	ds_read_b64_tr_b16 v[82:83], v94 offset:0x600
	ds_read_b64_tr_b16 v[84:85], v94 offset:0xe00
	v_mfma_f32_32x32x16_bf16 v[32:47], v[70:73], v[86:89], v[32:47]
	ds_read_b64_tr_b16 v[86:87], v94 offset:0x1600
	ds_read_b64_tr_b16 v[88:89], v94 offset:0x1e00
	v_mfma_f32_32x32x16_bf16 v[32:47], v[74:77], v[90:93], v[32:47]
	ds_read_b64_tr_b16 v[90:91], v94 offset:0x2600
	ds_read_b64_tr_b16 v[92:93], v94 offset:0x2e00
	v_mfma_f32_32x32x16_bf16 v[32:47], v[78:81], v[100:103], v[32:47]
	ds_read_b64_tr_b16 v[100:101], v94 offset:0x3600
	ds_read_b64_tr_b16 v[102:103], v94 offset:0x3e00
	s_waitcnt lgkmcnt(0)
	v_mfma_f32_32x32x16_bf16 v[16:31], v[66:69], v[82:85], v[16:31]
	v_mfma_f32_32x32x16_bf16 v[16:31], v[70:73], v[86:89], v[16:31]
	v_mfma_f32_32x32x16_bf16 v[16:31], v[74:77], v[90:93], v[16:31]
	v_mfma_f32_32x32x16_bf16 v[16:31], v[78:81], v[100:103], v[16:31]
	s_and_saveexec_b64 s[0:1], s[6:7]
	s_cbranch_execz .LBB0_57
	v_add_f32_e32 v66, v96, v97
	v_fmac_f32_e32 v66, v174, v141
	v_add_f32_e32 v64, v64, v65
	v_fmac_f32_e32 v64, v66, v98
	ds_write_b32 v173, v64
	s_branch .LBB0_57

; DEV void phase_gemm(const Params& p, int l, int mode) {
;     ...
;           const bool ropeR = !isctx && (sec == 0 || sec == 4);
;           const bool ropeA = !isctx && (sec == 2 || sec == 6);
;           const float qs = (sec == 4) ? 0.0625f : 1.f;
;           f32x4 tb[1][4];
;           const float2* rtR = (const float2*)(ws + OFF_ROPR); const float2* rtA = (const float2*)(ws + OFF_ROPA);
;     ...
; #pragma unroll
;           for (int q = 0; q < 8; ++q) {
;               const int ai = q >> 2, m = q & 3;
;               ROPE_LOAD(q);
;               const int iu = ai * 128 + e_wr * 64 + m * 16 + e_fr;
;               if (ropeR) {
; #pragma unroll
;                 for (int n = 0; n < 2; ++n)
; #pragma unroll
;                   for (int h2 = 0; h2 < 2; ++h2) {
;                     const f32x4 cs = tb[0][n * 2 + h2];
;                     float x1 = acc[ai][0][m][n][2 * h2], x2 = acc[ai][1][m][n][2 * h2];
;                     acc[ai][0][m][n][2 * h2] = x1 * cs[0] - x2 * cs[1]; acc[ai][1][m][n][2 * h2] = x1 * cs[1] + x2 * cs[0];
;                     x1 = acc[ai][0][m][n][2 * h2 + 1]; x2 = acc[ai][1][m][n][2 * h2 + 1];
;                     acc[ai][0][m][n][2 * h2 + 1] = x1 * cs[2] - x2 * cs[3]; acc[ai][1][m][n][2 * h2 + 1] = x1 * cs[3] + x2 * cs[2];
;                   }
;               }
; #pragma unroll
;               for (int bj = 0; bj < 2; ++bj) {
;                 const int c0 = bj * 128 + e_wc * 32 + 8 * e_fq;
;                 if (ropeA) {
; #pragma unroll
;                   for (int h2 = 0; h2 < 2; ++h2) {
;                     const f32x4 cs = tb[0][h2];
;                     float x1 = acc[ai][bj][m][0][2 * h2], x2 = acc[ai][bj][m][1][2 * h2];
;                     acc[ai][bj][m][0][2 * h2] = x1 * cs[0] - x2 * cs[1]; acc[ai][bj][m][1][2 * h2] = x1 * cs[1] + x2 * cs[0];
;                     x1 = acc[ai][bj][m][0][2 * h2 + 1]; x2 = acc[ai][bj][m][1][2 * h2 + 1];
;                     acc[ai][bj][m][0][2 * h2 + 1] = x1 * cs[2] - x2 * cs[3]; acc[ai][bj][m][1][2 * h2 + 1] = x1 * cs[3] + x2 * cs[2];
;                   }
;                 }
;                 if (sec >= 8 && sec <= 11) {
;                   const f32x4 qa = acc[ai][bj][m][0], qb = acc[ai][bj][m][1];
;                   f32x4 r4;
;                   if (sec >= 10) { r4[0] = qa[0] * silu_f(qb[0]); r4[1] = qa[1] * silu_f(qb[1]); r4[2] = qa[2] * silu_f(qb[2]); r4[3] = qa[3] * silu_f(qb[3]); }
.LBB0_353:
	s_cmp_eq_u32 s44, 7
	s_cselect_b32 s2, 0x20e00000, s28
	s_cmp_lg_u32 s44, 5
	s_cselect_b32 s2, s2, 0x1ec00000
	s_add_u32 s2, s96, s2
	s_addc_u32 s3, s97, 0
	s_lshl_b32 s4, s42, 1
	s_add_u32 s4, s2, s4
	s_addc_u32 s5, s3, 0
	s_ashr_i32 s23, s22, 31
	s_lshl_b64 s[2:3], s[22:23], 1
	s_add_u32 s2, s96, s2
	s_addc_u32 s3, s97, s3
	s_lshl_b32 s8, s41, 2
	s_lshr_b32 s9, s42, 8
	s_or_b32 s8, s8, s9
	s_add_u32 s18, s96, 0x16400000
	v_or_b32_e32 v158, v182, v228
	s_addc_u32 s19, s97, 0
	s_mul_hi_i32 s9, s8, 0x1100
	s_mulk_i32 s8, 0x1100
	s_add_u32 s74, s8, s90
	v_add_u32_e32 v16, s40, v158
	s_addc_u32 s75, s9, 0
	s_and_b32 s8, s22, 0x700
	v_ashrrev_i32_e32 v17, 31, v16
	v_mov_b64_e32 v[18:19], s[2:3]
	s_movk_i32 s22, 0x1800
	v_lshlrev_b64 v[168:169], 11, v[16:17]
	v_mad_i64_i32 v[16:17], s[22:23], v16, s22, v[18:19]
	v_ashrrev_i32_e32 v159, 31, v158
	s_mov_b64 s[22:23], 0x2b7fa000
	v_lshl_add_u64 v[174:175], v[16:17], 0, s[22:23]
	v_lshl_add_u64 v[16:17], s[74:75], 0, v[158:159]
	v_lshlrev_b64 v[16:17], 9, v[16:17]
	s_add_u32 s8, s96, s8
	v_lshl_add_u64 v[160:161], s[18:19], 0, v[16:17]
	v_mov_b32_e32 v16, 0x3d800000
	s_addc_u32 s9, s97, 0
	v_cndmask_b32_e64 v185, 1.0, v16, s[0:1]
	v_mov_b32_e32 v16, 0x3e38aa3b
	s_cmp_eq_u32 s44, 6
	s_cselect_b64 s[22:23], -1, 0
	s_nop 0
	v_cndmask_b32_e64 v185, v185, v16, s[22:23]
	s_and_b32 s0, s44, 0x7ffffffc
	s_cmp_lg_u32 s0, 8
	s_cselect_b64 s[22:23], -1, 0
	s_lshl_b32 s0, s41, 3
	s_lshr_b32 s1, s42, 7
	s_or_b32 s46, s0, s1
	s_add_u32 s0, s96, 0x1a800000
	s_addc_u32 s1, s97, 0
	v_writelane_b32 v255, s0, 46
	s_lshl_b32 s45, s41, 4
	s_cmp_eq_u32 s44, 2
	v_writelane_b32 v255, s1, 47
	s_mov_b32 s0, 0x18600000
	s_cselect_b32 s0, s0, 0x1ca00000
	s_add_u32 s0, s96, s0
	s_addc_u32 s1, s97, 0
	v_writelane_b32 v255, s0, 31
	s_cmp_lt_u32 s44, 12
	v_lshl_add_u64 v[170:171], v[158:159], 0, s[90:91]
	v_writelane_b32 v255, s1, 32
	s_cselect_b64 s[0:1], -1, 0
	v_writelane_b32 v255, s0, 48
	s_cmp_lt_u32 s44, 10
	v_lshl_add_u64 v[176:177], s[4:5], 0, v[168:169]
	v_writelane_b32 v255, s1, 49
	s_cselect_b64 s[28:29], -1, 0
	v_or_b32_e32 v162, v183, v184
	s_mov_b64 s[0:1], -1
	s_and_b64 vcc, exec, s[22:23]
	s_cbranch_vccz .LBB0_364
	v_mul_f32_e32 v16, v185, v144
	v_mul_f32_e32 v17, v185, v145
	v_cvt_pk_bf16_f32 v144, v16, v17
	v_mul_f32_e32 v16, v185, v146
	v_mul_f32_e32 v17, v185, v147
	v_cvt_pk_bf16_f32 v145, v16, v17
	v_mul_f32_e32 v16, v185, v172
	v_mul_f32_e32 v17, v185, v173
	s_and_b64 vcc, exec, s[24:25]
	v_cvt_pk_bf16_f32 v146, v16, v17
	v_mul_f32_e32 v16, v185, v152
	v_mul_f32_e32 v17, v185, v153
	v_cvt_pk_bf16_f32 v147, v16, v17
	s_cbranch_vccz .LBB0_378
	s_cmp_lt_i32 s44, 3
	s_mov_b64 s[26:27], -1
	s_cbranch_scc1 .LBB0_375
	s_mov_b64 vcc, -1
	s_mov_b64 s[52:53], 0
	s_cmp_gt_i32 s44, 5
	s_mov_b64 s[26:27], 0
	s_mov_b64 s[0:1], 0
	s_cbranch_scc0 .LBB0_371
	s_cmp_lg_u32 s44, 6
	s_mov_b64 s[26:27], -1
	s_cselect_b64 s[0:1], -1, 0
	s_cbranch_execz .LBB0_372
